# v2 + DPP/permlane wave sums in rw phases, conv, GLA scan; relaxed vmcnt drains at GLA scan step tops
# speedup vs baseline: 1.0060x; 1.0060x over previous
; DI unsigned pk(float lo, float hi) { f32x2 v = {lo, hi}; bf2_t b = __builtin_convertvector(v, bf2_t); return __builtin_bit_cast(unsigned, b); }
; DI float bflo(unsigned w) { return __uint_as_float(w << 16); }
; DI float bfhi(unsigned w) { return __uint_as_float(w & 0xffff0000u); }
; DI void rw_phase(const float* x, bf16_t* hb, const bf16_t* y, const float* gpost, float* rh, float* fout, bool y_unscaled) {
;     ...
;       float s2 = 0.f;
; #pragma unroll
;       for (int c = 0; c < 2; ++c) {
;         u32x4 w;
;         w.x = pk(hv[8 * c + 0], hv[8 * c + 1]); w.y = pk(hv[8 * c + 2], hv[8 * c + 3]); w.z = pk(hv[8 * c + 4], hv[8 * c + 5]); w.w = pk(hv[8 * c + 6], hv[8 * c + 7]);
;         gst<u32x4>(hb + (size_t)row * 1024 + 512 * c + 8 * lane, w);
;         s2 += bflo(w.x) * bflo(w.x) + bfhi(w.x) * bfhi(w.x) + bflo(w.y) * bflo(w.y) + bfhi(w.y) * bfhi(w.y) +
;               bflo(w.z) * bflo(w.z) + bfhi(w.z) * bfhi(w.z) + bflo(w.w) * bflo(w.w) + bfhi(w.w) * bfhi(w.w);
;       }
;       s2 = wave_sum(s2);
;       if (lane == 0) gst<float>(rh + row, rsqrtf(s2 * (1.0f / 1024.0f) + EPS));
.LBB0_10:
	s_waitcnt vmcnt(0)
	v_cvt_pk_bf16_f32 v10, v10, v11
	v_cvt_pk_bf16_f32 v11, v12, v13
	v_cvt_pk_bf16_f32 v12, v14, v15
	v_and_b32_e32 v15, 0xffff0000, v10
	v_lshlrev_b32_e32 v14, 16, v10
	v_mul_f32_e32 v26, v15, v15
	v_fmac_f32_e32 v26, v14, v14
	v_lshlrev_b32_e32 v14, 16, v11
	v_fmac_f32_e32 v26, v14, v14
	v_and_b32_e32 v14, 0xffff0000, v11
	v_fmac_f32_e32 v26, v14, v14
	v_lshlrev_b32_e32 v14, 16, v12
	v_cvt_pk_bf16_f32 v13, v16, v17
	v_fmac_f32_e32 v26, v14, v14
	v_and_b32_e32 v14, 0xffff0000, v12
	v_fmac_f32_e32 v26, v14, v14
	v_lshlrev_b32_e32 v14, 16, v13
	v_fmac_f32_e32 v26, v14, v14
	v_and_b32_e32 v14, 0xffff0000, v13
	v_fmac_f32_e32 v26, v14, v14
	s_waitcnt lgkmcnt(0)
	v_cvt_pk_bf16_f32 v14, v2, v3
	v_and_b32_e32 v3, 0xffff0000, v14
	v_cvt_pk_bf16_f32 v15, v4, v5
	v_lshlrev_b32_e32 v2, 16, v14
	v_mul_f32_e32 v3, v3, v3
	v_fmac_f32_e32 v3, v2, v2
	v_lshlrev_b32_e32 v2, 16, v15
	v_cvt_pk_bf16_f32 v16, v6, v7
	v_fmac_f32_e32 v3, v2, v2
	v_and_b32_e32 v2, 0xffff0000, v15
	v_fmac_f32_e32 v3, v2, v2
	v_lshlrev_b32_e32 v2, 16, v16
	v_cvt_pk_bf16_f32 v17, v8, v9
	v_fmac_f32_e32 v3, v2, v2
	v_and_b32_e32 v2, 0xffff0000, v16
	v_fmac_f32_e32 v3, v2, v2
	v_lshlrev_b32_e32 v2, 16, v17
	v_fmac_f32_e32 v3, v2, v2
	v_and_b32_e32 v2, 0xffff0000, v17
	v_fmac_f32_e32 v3, v2, v2
	v_add_f32_e32 v2, v26, v3
	s_nop 1
	v_mov_b32_dpp v3, v2 quad_perm:[1,0,3,2] row_mask:0xf bank_mask:0xf
	v_lshl_add_u64 v[4:5], v[22:23], 0, v[24:25]
	global_store_dwordx4 v[4:5], v[10:13], off
	global_store_dwordx4 v[4:5], v[14:17], off offset:1024
	s_waitcnt lgkmcnt(0)
	v_add_f32_e32 v2, v2, v3
	s_nop 1
	v_mov_b32_dpp v3, v2 quad_perm:[2,3,0,1] row_mask:0xf bank_mask:0xf
	s_waitcnt lgkmcnt(0)
	v_add_f32_e32 v2, v2, v3
	s_nop 1
	v_mov_b32_dpp v3, v2 row_half_mirror row_mask:0xf bank_mask:0xf
	s_waitcnt lgkmcnt(0)
	v_add_f32_e32 v2, v2, v3
	s_nop 1
	v_mov_b32_dpp v3, v2 row_mirror row_mask:0xf bank_mask:0xf
	s_waitcnt lgkmcnt(0)
	v_add_f32_e32 v2, v2, v3
	v_mov_b32_e32 v3, v2
	v_mov_b32_e32 v120, v2
	s_nop 1
	v_permlane16_swap_b32_e32 v3, v120
	s_waitcnt lgkmcnt(0)
	v_add_f32_e32 v2, v3, v120
	v_mov_b32_e32 v3, v2
	v_mov_b32_e32 v120, v2
	s_nop 1
	v_permlane32_swap_b32_e32 v3, v120
	s_and_saveexec_b64 s[18:19], s[4:5]
	s_cbranch_execz .LBB0_6
	s_waitcnt lgkmcnt(0)
	v_add_f32_e32 v2, v3, v120
	v_fmamk_f32 v2, v2, 0x3a800000, v34
	v_mul_f32_e32 v3, 0x4b800000, v2
	v_cmp_gt_f32_e32 vcc, s21, v2
	s_nop 1
	v_cndmask_b32_e32 v2, v2, v3, vcc
	v_rsq_f32_e32 v4, v2
	v_lshl_add_u64 v[2:3], v[18:19], 2, s[12:13]
	v_mul_f32_e32 v5, 0x45800000, v4
	v_cndmask_b32_e32 v4, v4, v5, vcc
	global_store_dword v[2:3], v4, off
	s_branch .LBB0_6

; DI float bflo(unsigned w) { return __uint_as_float(w << 16); }
; DI float bfhi(unsigned w) { return __uint_as_float(w & 0xffff0000u); }
; DI void rw_phase(const float* x, bf16_t* hb, const bf16_t* y, const float* gpost, float* rh, float* fout, bool y_unscaled) {
;     ...
;     if (y) {
;       float yv[16]; float ss = 0.f;
; #pragma unroll
;       for (int c = 0; c < 2; ++c) {
;         const u32x4 w = gld<u32x4>(y + (size_t)row * 1024 + 512 * c + 8 * lane);
;         yv[8 * c + 0] = bflo(w.x); yv[8 * c + 1] = bfhi(w.x); yv[8 * c + 2] = bflo(w.y); yv[8 * c + 3] = bfhi(w.y);
;         yv[8 * c + 4] = bflo(w.z); yv[8 * c + 5] = bfhi(w.z); yv[8 * c + 6] = bflo(w.w); yv[8 * c + 7] = bfhi(w.w);
;       }
; #pragma unroll
;       for (int i = 0; i < 16; ++i) ss += yv[i] * yv[i];
;       ss = wave_sum(ss);
;       float epsn = EPS;
;       if (y_unscaled) { const float r = gld<float>(rh + row), r2 = r * r; epsn = EPS / (r2 * r2); }
;       const float ry = rsqrtf(ss * (1.0f / 1024.0f) + epsn);
; #pragma unroll
;       for (int c = 0; c < 2; ++c) {
;         const f32x4 g0 = gld<f32x4>(gpost + 512 * c + 8 * lane), g1 = gld<f32x4>(gpost + 512 * c + 8 * lane + 4);
; #pragma unroll
;         for (int i = 0; i < 4; ++i) { hv[8 * c + i] += yv[8 * c + i] * ry * g0[i]; hv[8 * c + 4 + i] += yv[8 * c + 4 + i] * ry * g1[i]; }
;       }
;     }
;     if (fout) {
;       float* op = fout + (size_t)row * 1024;
; #pragma unroll
;       for (int c = 0; c < 2; ++c) {
;         gst<f32x4>(op + 512 * c + 8 * lane, (f32x4){hv[8 * c], hv[8 * c + 1], hv[8 * c + 2], hv[8 * c + 3]});
;         gst<f32x4>(op + 512 * c + 8 * lane + 4, (f32x4){hv[8 * c + 4], hv[8 * c + 5], hv[8 * c + 6], hv[8 * c + 7]});
;       }
.LBB0_109:
	v_ashrrev_i32_e32 v25, 31, v24
	s_waitcnt lgkmcnt(0)
	v_lshlrev_b64 v[0:1], 11, v[24:25]
	v_lshl_add_u64 v[34:35], v[24:25], 2, s[74:75]
	v_lshl_add_u64 v[36:37], v[26:27], 0, v[0:1]
	global_load_dword v16, v[34:35], off
	global_load_dwordx4 v[8:11], v[36:37], off offset:1024
	v_lshl_add_u64 v[0:1], v[28:29], 0, v[0:1]
	global_load_dwordx4 v[12:15], v[0:1], off offset:1024
	global_load_dwordx4 v[54:57], v[0:1], off
	global_load_dwordx4 v[68:71], v[36:37], off
	s_nop 0
	global_load_dwordx4 v[0:3], v[30:31], off offset:16
	global_load_dwordx4 v[4:7], v[30:31], off
	s_waitcnt vmcnt(0)
	v_lshlrev_b32_e32 v22, 16, v12
	v_lshlrev_b32_e32 v52, 16, v54
	v_and_b32_e32 v53, 0xffff0000, v54
	v_lshlrev_b32_e32 v50, 16, v55
	v_and_b32_e32 v51, 0xffff0000, v55
	v_pk_mul_f32 v[54:55], v[52:53], v[52:53]
	v_lshlrev_b32_e32 v42, 16, v9
	v_and_b32_e32 v43, 0xffff0000, v9
	v_add_f32_e32 v9, v54, v55
	v_pk_mul_f32 v[54:55], v[50:51], v[50:51]
	v_lshlrev_b32_e32 v48, 16, v56
	v_and_b32_e32 v49, 0xffff0000, v56
	v_add_f32_e32 v9, v54, v9
	v_add_f32_e32 v9, v55, v9
	v_pk_mul_f32 v[54:55], v[48:49], v[48:49]
	v_lshlrev_b32_e32 v46, 16, v57
	v_and_b32_e32 v47, 0xffff0000, v57
	v_add_f32_e32 v9, v54, v9
	v_add_f32_e32 v9, v55, v9
	v_pk_mul_f32 v[54:55], v[46:47], v[46:47]
	v_and_b32_e32 v23, 0xffff0000, v12
	v_add_f32_e32 v9, v54, v9
	v_add_f32_e32 v9, v55, v9
	v_pk_mul_f32 v[54:55], v[22:23], v[22:23]
	v_lshlrev_b32_e32 v20, 16, v13
	v_and_b32_e32 v21, 0xffff0000, v13
	v_add_f32_e32 v9, v54, v9
	v_mul_f32_e32 v61, v16, v16
	v_lshlrev_b32_e32 v16, 16, v15
	v_and_b32_e32 v17, 0xffff0000, v15
	v_lshlrev_b32_e32 v18, 16, v14
	v_and_b32_e32 v19, 0xffff0000, v14
	v_pk_mul_f32 v[14:15], v[20:21], v[20:21]
	v_add_f32_e32 v9, v55, v9
	v_add_f32_e32 v9, v14, v9
	v_pk_mul_f32 v[12:13], v[18:19], v[18:19]
	v_add_f32_e32 v9, v15, v9
	v_add_f32_e32 v9, v12, v9
	v_lshlrev_b32_e32 v38, 16, v11
	v_and_b32_e32 v39, 0xffff0000, v11
	v_lshlrev_b32_e32 v40, 16, v10
	v_and_b32_e32 v41, 0xffff0000, v10
	v_pk_mul_f32 v[10:11], v[16:17], v[16:17]
	v_add_f32_e32 v9, v13, v9
	v_add_f32_e32 v9, v10, v9
	v_add_f32_e32 v9, v11, v9
	s_nop 1
	v_mov_b32_dpp v10, v9 quad_perm:[1,0,3,2] row_mask:0xf bank_mask:0xf
	v_lshlrev_b32_e32 v44, 16, v8
	v_and_b32_e32 v45, 0xffff0000, v8
	v_lshlrev_b32_e32 v58, 16, v69
	v_and_b32_e32 v59, 0xffff0000, v69
	s_waitcnt lgkmcnt(0)
	v_add_f32_e32 v8, v9, v10
	s_nop 1
	v_mov_b32_dpp v9, v8 quad_perm:[2,3,0,1] row_mask:0xf bank_mask:0xf
	v_mul_f32_e32 v10, v61, v61
	v_div_scale_f32 v11, s[44:45], v10, v10, s64
	v_rcp_f32_e32 v12, v11
	s_waitcnt lgkmcnt(0)
	v_add_f32_e32 v8, v8, v9
	s_nop 1
	v_mov_b32_dpp v9, v8 row_half_mirror row_mask:0xf bank_mask:0xf
	v_div_scale_f32 v13, vcc, s64, v10, s64
	v_fma_f32 v14, -v11, v12, 1.0
	v_fmac_f32_e32 v12, v14, v12
	s_waitcnt lgkmcnt(0)
	v_add_f32_e32 v8, v8, v9
	s_nop 1
	v_mov_b32_dpp v9, v8 row_mirror row_mask:0xf bank_mask:0xf
	v_mul_f32_e32 v14, v13, v12
	v_fma_f32 v15, -v11, v14, v13
	v_fmac_f32_e32 v14, v15, v12
	v_fma_f32 v11, -v11, v14, v13
	s_waitcnt lgkmcnt(0)
	v_add_f32_e32 v8, v8, v9
	v_mov_b32_e32 v9, v8
	v_mov_b32_e32 v120, v8
	s_nop 1
	v_permlane16_swap_b32_e32 v9, v120
	v_div_fmas_f32 v11, v11, v12, v14
	v_lshlrev_b32_e32 v60, 16, v68
	v_and_b32_e32 v61, 0xffff0000, v68
	v_div_fixup_f32 v68, v11, v10, s64
	s_waitcnt lgkmcnt(0)
	v_add_f32_e32 v8, v9, v120
	v_mov_b32_e32 v9, v8
	v_mov_b32_e32 v120, v8
	s_nop 1
	v_permlane32_swap_b32_e32 v9, v120
	v_lshlrev_b32_e32 v54, 16, v71
	v_and_b32_e32 v55, 0xffff0000, v71
	v_lshlrev_b32_e32 v56, 16, v70
	v_and_b32_e32 v57, 0xffff0000, v70
	s_waitcnt lgkmcnt(0)
	v_add_f32_e32 v69, v9, v120
	global_load_dwordx4 v[12:15], v[30:31], off offset:2048
	global_load_dwordx4 v[8:11], v[30:31], off offset:2064
	v_fmac_f32_e32 v68, 0x3a800000, v69
	v_mul_f32_e32 v69, 0x4b800000, v68
	v_cmp_gt_f32_e32 vcc, s33, v68
	s_and_b64 s[44:45], exec, s[38:39]
	s_nop 0
	v_cndmask_b32_e32 v68, v68, v69, vcc
	v_rsq_f32_e32 v68, v68
	s_nop 0
	v_mul_f32_e32 v69, 0x45800000, v68
	v_cndmask_b32_e32 v68, v68, v69, vcc
	v_pk_mul_f32 v[52:53], v[68:69], v[52:53] op_sel_hi:[0,1]
	v_pk_mul_f32 v[48:49], v[68:69], v[48:49] op_sel_hi:[0,1]
	v_pk_mul_f32 v[50:51], v[68:69], v[50:51] op_sel_hi:[0,1]
	v_pk_mul_f32 v[46:47], v[68:69], v[46:47] op_sel_hi:[0,1]
	v_pk_mul_f32 v[70:71], v[68:69], v[22:23] op_sel_hi:[0,1]
	v_pk_mul_f32 v[72:73], v[68:69], v[18:19] op_sel_hi:[0,1]
	v_pk_mul_f32 v[74:75], v[68:69], v[20:21] op_sel_hi:[0,1]
	v_pk_mul_f32 v[68:69], v[68:69], v[16:17] op_sel_hi:[0,1]
	v_pk_fma_f32 v[20:21], v[4:5], v[52:53], v[60:61]
	v_pk_fma_f32 v[16:17], v[0:1], v[48:49], v[56:57]
	v_pk_fma_f32 v[22:23], v[6:7], v[50:51], v[58:59]
	v_pk_fma_f32 v[18:19], v[2:3], v[46:47], v[54:55]
	s_mov_b64 vcc, s[44:45]
	s_waitcnt vmcnt(1)
	v_pk_fma_f32 v[4:5], v[12:13], v[70:71], v[44:45]
	s_waitcnt vmcnt(0)
	v_pk_fma_f32 v[0:1], v[8:9], v[72:73], v[40:41]
	v_pk_fma_f32 v[6:7], v[14:15], v[74:75], v[42:43]
	v_pk_fma_f32 v[2:3], v[10:11], v[68:69], v[38:39]
	s_cbranch_vccz .LBB0_111
	v_lshlrev_b64 v[8:9], 12, v[24:25]
	v_lshl_add_u64 v[8:9], v[32:33], 0, v[8:9]
	global_store_dwordx4 v[8:9], v[20:23], off
	global_store_dwordx4 v[8:9], v[16:19], off offset:16
	global_store_dwordx4 v[8:9], v[4:7], off offset:2048
	global_store_dwordx4 v[8:9], v[0:3], off offset:2064
	s_cbranch_execnz .LBB0_108
	s_branch .LBB0_112
; DI unsigned pk(float lo, float hi) { f32x2 v = {lo, hi}; bf2_t b = __builtin_convertvector(v, bf2_t); return __builtin_bit_cast(unsigned, b); }
; DI float bflo(unsigned w) { return __uint_as_float(w << 16); }
; DI float bfhi(unsigned w) { return __uint_as_float(w & 0xffff0000u); }
; DI void rw_phase(const float* x, bf16_t* hb, const bf16_t* y, const float* gpost, float* rh, float* fout, bool y_unscaled) {
;     ...
;       float s2 = 0.f;
; #pragma unroll
;       for (int c = 0; c < 2; ++c) {
;         u32x4 w;
;         w.x = pk(hv[8 * c + 0], hv[8 * c + 1]); w.y = pk(hv[8 * c + 2], hv[8 * c + 3]); w.z = pk(hv[8 * c + 4], hv[8 * c + 5]); w.w = pk(hv[8 * c + 6], hv[8 * c + 7]);
;         gst<u32x4>(hb + (size_t)row * 1024 + 512 * c + 8 * lane, w);
;         s2 += bflo(w.x) * bflo(w.x) + bfhi(w.x) * bfhi(w.x) + bflo(w.y) * bflo(w.y) + bfhi(w.y) * bfhi(w.y) +
;               bflo(w.z) * bflo(w.z) + bfhi(w.z) * bfhi(w.z) + bflo(w.w) * bflo(w.w) + bfhi(w.w) * bfhi(w.w);
;       }
;       s2 = wave_sum(s2);
;       if (lane == 0) gst<float>(rh + row, rsqrtf(s2 * (1.0f / 1024.0f) + EPS));
.LBB0_111:
.LBB0_112:
	v_cvt_pk_bf16_f32 v8, v20, v21
	v_cvt_pk_bf16_f32 v4, v4, v5
	v_and_b32_e32 v13, 0xffff0000, v8
	v_cvt_pk_bf16_f32 v5, v6, v7
	v_cvt_pk_bf16_f32 v6, v0, v1
	v_and_b32_e32 v1, 0xffff0000, v4
	v_cvt_pk_bf16_f32 v9, v22, v23
	v_lshlrev_b32_e32 v12, 16, v8
	v_mul_f32_e32 v13, v13, v13
	v_lshlrev_b32_e32 v0, 16, v4
	v_mul_f32_e32 v1, v1, v1
	v_fmac_f32_e32 v13, v12, v12
	v_lshlrev_b32_e32 v12, 16, v9
	v_fmac_f32_e32 v1, v0, v0
	v_lshlrev_b32_e32 v0, 16, v5
	v_cvt_pk_bf16_f32 v10, v16, v17
	v_fmac_f32_e32 v13, v12, v12
	v_and_b32_e32 v12, 0xffff0000, v9
	v_fmac_f32_e32 v1, v0, v0
	v_and_b32_e32 v0, 0xffff0000, v5
	v_fmac_f32_e32 v13, v12, v12
	v_lshlrev_b32_e32 v12, 16, v10
	v_fmac_f32_e32 v1, v0, v0
	v_lshlrev_b32_e32 v0, 16, v6
	v_cvt_pk_bf16_f32 v11, v18, v19
	v_fmac_f32_e32 v13, v12, v12
	v_and_b32_e32 v12, 0xffff0000, v10
	v_cvt_pk_bf16_f32 v7, v2, v3
	v_fmac_f32_e32 v1, v0, v0
	v_and_b32_e32 v0, 0xffff0000, v6
	v_fmac_f32_e32 v13, v12, v12
	v_lshlrev_b32_e32 v12, 16, v11
	v_fmac_f32_e32 v1, v0, v0
	v_lshlrev_b32_e32 v0, 16, v7
	v_fmac_f32_e32 v13, v12, v12
	v_and_b32_e32 v12, 0xffff0000, v11
	v_fmac_f32_e32 v1, v0, v0
	v_and_b32_e32 v0, 0xffff0000, v7
	v_fmac_f32_e32 v13, v12, v12
	v_fmac_f32_e32 v1, v0, v0
	v_add_f32_e32 v0, v13, v1
	s_nop 1
	v_mov_b32_dpp v1, v0 quad_perm:[1,0,3,2] row_mask:0xf bank_mask:0xf
	global_store_dwordx4 v[36:37], v[8:11], off
	global_store_dwordx4 v[36:37], v[4:7], off offset:1024
	s_waitcnt lgkmcnt(0)
	v_add_f32_e32 v0, v0, v1
	s_nop 1
	v_mov_b32_dpp v1, v0 quad_perm:[2,3,0,1] row_mask:0xf bank_mask:0xf
	s_waitcnt lgkmcnt(0)
	v_add_f32_e32 v0, v0, v1
	s_nop 1
	v_mov_b32_dpp v1, v0 row_half_mirror row_mask:0xf bank_mask:0xf
	s_waitcnt lgkmcnt(0)
	v_add_f32_e32 v0, v0, v1
	s_nop 1
	v_mov_b32_dpp v1, v0 row_mirror row_mask:0xf bank_mask:0xf
	s_waitcnt lgkmcnt(0)
	v_add_f32_e32 v0, v0, v1
	v_mov_b32_e32 v1, v0
	v_mov_b32_e32 v120, v0
	s_nop 1
	v_permlane16_swap_b32_e32 v1, v120
	s_waitcnt lgkmcnt(0)
	v_add_f32_e32 v0, v1, v120
	v_mov_b32_e32 v1, v0
	v_mov_b32_e32 v120, v0
	s_nop 1
	v_permlane32_swap_b32_e32 v1, v120
	s_and_saveexec_b64 s[44:45], s[42:43]
	s_cbranch_execz .LBB0_107
	s_waitcnt lgkmcnt(0)
	v_add_f32_e32 v0, v1, v120
	v_fmamk_f32 v0, v0, 0x3a800000, v204
	v_mul_f32_e32 v1, 0x4b800000, v0
	v_cmp_gt_f32_e32 vcc, s33, v0
	s_nop 1
	v_cndmask_b32_e32 v0, v0, v1, vcc
	v_rsq_f32_e32 v0, v0
	s_nop 0
	v_mul_f32_e32 v1, 0x45800000, v0
	v_cndmask_b32_e32 v0, v0, v1, vcc
	global_store_dword v[34:35], v0, off
	s_branch .LBB0_107

; DI float bflo(unsigned w) { return __uint_as_float(w << 16); }
; DI void rw_phase(const float* x, bf16_t* hb, const bf16_t* y, const float* gpost, float* rh, float* fout, bool y_unscaled) {
;     ...
;       for (int c = 0; c < 2; ++c) {
;         const u32x4 w = gld<u32x4>(hb + (size_t)row * 1024 + 512 * c + 8 * lane);
;         hv[8 * c + 0] = bflo(w.x); hv[8 * c + 1] = bfhi(w.x); hv[8 * c + 2] = bflo(w.y); hv[8 * c + 3] = bfhi(w.y);
;         hv[8 * c + 4] = bflo(w.z); hv[8 * c + 5] = bfhi(w.z); hv[8 * c + 6] = bflo(w.w); hv[8 * c + 7] = bfhi(w.w);
;       }
;     }
;     if (y) {
;       float yv[16]; float ss = 0.f;
; #pragma unroll
;       for (int c = 0; c < 2; ++c) {
;         const u32x4 w = gld<u32x4>(y + (size_t)row * 1024 + 512 * c + 8 * lane);
;         yv[8 * c + 0] = bflo(w.x); yv[8 * c + 1] = bfhi(w.x); yv[8 * c + 2] = bflo(w.y); yv[8 * c + 3] = bfhi(w.y);
;         yv[8 * c + 4] = bflo(w.z); yv[8 * c + 5] = bfhi(w.z); yv[8 * c + 6] = bflo(w.w); yv[8 * c + 7] = bfhi(w.w);
;       }
; #pragma unroll
;       for (int i = 0; i < 16; ++i) ss += yv[i] * yv[i];
;       ss = wave_sum(ss);
;       float epsn = EPS;
;       if (y_unscaled) { const float r = gld<float>(rh + row), r2 = r * r; epsn = EPS / (r2 * r2); }
;       const float ry = rsqrtf(ss * (1.0f / 1024.0f) + epsn);
; #pragma unroll
;       for (int c = 0; c < 2; ++c) {
;         const f32x4 g0 = gld<f32x4>(gpost + 512 * c + 8 * lane), g1 = gld<f32x4>(gpost + 512 * c + 8 * lane + 4);
; #pragma unroll
;         for (int i = 0; i < 4; ++i) { hv[8 * c + i] += yv[8 * c + i] * ry * g0[i]; hv[8 * c + 4 + i] += yv[8 * c + 4 + i] * ry * g1[i]; }
;       }
;     }
;     if (fout) {
;       float* op = fout + (size_t)row * 1024;
; #pragma unroll
;       for (int c = 0; c < 2; ++c) {
;         gst<f32x4>(op + 512 * c + 8 * lane, (f32x4){hv[8 * c], hv[8 * c + 1], hv[8 * c + 2], hv[8 * c + 3]});
;         gst<f32x4>(op + 512 * c + 8 * lane + 4, (f32x4){hv[8 * c + 4], hv[8 * c + 5], hv[8 * c + 6], hv[8 * c + 7]});
;       }
;     } else {
;       float s2 = 0.f;
; #pragma unroll
;       for (int c = 0; c < 2; ++c) {
;         u32x4 w;
;         w.x = pk(hv[8 * c + 0], hv[8 * c + 1]); w.y = pk(hv[8 * c + 2], hv[8 * c + 3]); w.z = pk(hv[8 * c + 4], hv[8 * c + 5]); w.w = pk(hv[8 * c + 6], hv[8 * c + 7]);
;         gst<u32x4>(hb + (size_t)row * 1024 + 512 * c + 8 * lane, w);
.LBB0_488:
	v_ashrrev_i32_e32 v1, 31, v0
	v_lshlrev_b64 v[8:9], 11, v[0:1]
	v_lshl_add_u64 v[20:21], v[4:5], 0, v[8:9]
	s_waitcnt lgkmcnt(0)
	global_load_dwordx4 v[16:19], v[20:21], off offset:1024
	s_nop 0
	global_load_dwordx4 v[20:23], v[20:21], off
	v_lshl_add_u64 v[8:9], v[2:3], 0, v[8:9]
	global_load_dwordx4 v[24:27], v[8:9], off offset:1024
	global_load_dwordx4 v[28:31], v[8:9], off
	global_load_dwordx4 v[32:35], v[6:7], off offset:16
	global_load_dwordx4 v[36:39], v[6:7], off
	global_load_dwordx4 v[40:43], v[6:7], off offset:2064
	global_load_dwordx4 v[44:47], v[6:7], off offset:2048
	s_waitcnt vmcnt(0)
	v_lshlrev_b32_e32 v48, 16, v19
	v_lshlrev_b32_e32 v56, 16, v20
	v_and_b32_e32 v57, 0xffff0000, v20
	v_and_b32_e32 v49, 0xffff0000, v19
	v_lshlrev_b32_e32 v50, 16, v18
	v_and_b32_e32 v51, 0xffff0000, v18
	v_lshlrev_b32_e32 v18, 16, v17
	v_and_b32_e32 v19, 0xffff0000, v17
	v_lshlrev_b32_e32 v52, 16, v16
	v_and_b32_e32 v53, 0xffff0000, v16
	v_lshlrev_b32_e32 v16, 16, v23
	v_and_b32_e32 v17, 0xffff0000, v23
	v_lshlrev_b32_e32 v54, 16, v22
	v_and_b32_e32 v55, 0xffff0000, v22
	v_lshlrev_b32_e32 v22, 16, v21
	v_and_b32_e32 v23, 0xffff0000, v21
	v_pk_mul_f32 v[70:71], v[56:57], v[56:57]
	v_pk_mul_f32 v[68:69], v[22:23], v[22:23]
	v_add_f32_e32 v70, v70, v71
	v_add_f32_e32 v68, v68, v70
	v_pk_mul_f32 v[66:67], v[54:55], v[54:55]
	v_add_f32_e32 v68, v69, v68
	v_add_f32_e32 v66, v66, v68
	v_pk_mul_f32 v[64:65], v[16:17], v[16:17]
	v_add_f32_e32 v66, v67, v66
	v_add_f32_e32 v64, v64, v66
	v_pk_mul_f32 v[62:63], v[52:53], v[52:53]
	v_add_f32_e32 v64, v65, v64
	v_add_f32_e32 v62, v62, v64
	v_pk_mul_f32 v[60:61], v[18:19], v[18:19]
	v_add_f32_e32 v62, v63, v62
	v_add_f32_e32 v60, v60, v62
	v_pk_mul_f32 v[58:59], v[50:51], v[50:51]
	v_add_f32_e32 v60, v61, v60
	v_add_f32_e32 v58, v58, v60
	v_pk_mul_f32 v[20:21], v[48:49], v[48:49]
	v_add_f32_e32 v58, v59, v58
	v_add_f32_e32 v20, v20, v58
	v_add_f32_e32 v20, v21, v20
	s_nop 1
	v_mov_b32_dpp v21, v20 quad_perm:[1,0,3,2] row_mask:0xf bank_mask:0xf
	v_and_b32_e32 v59, 0xffff0000, v26
	s_waitcnt lgkmcnt(0)
	v_add_f32_e32 v20, v20, v21
	s_nop 1
	v_mov_b32_dpp v21, v20 quad_perm:[2,3,0,1] row_mask:0xf bank_mask:0xf
	s_waitcnt lgkmcnt(0)
	v_add_f32_e32 v21, v20, v21
	s_nop 1
	v_mov_b32_dpp v58, v21 row_half_mirror row_mask:0xf bank_mask:0xf
	v_lshlrev_b32_e32 v20, 16, v27
	s_waitcnt lgkmcnt(0)
	v_add_f32_e32 v60, v21, v58
	s_nop 1
	v_mov_b32_dpp v61, v60 row_mirror row_mask:0xf bank_mask:0xf
	v_and_b32_e32 v21, 0xffff0000, v27
	v_lshlrev_b32_e32 v58, 16, v26
	v_lshlrev_b32_e32 v26, 16, v25
	v_and_b32_e32 v27, 0xffff0000, v25
	s_waitcnt lgkmcnt(0)
	v_add_f32_e32 v62, v60, v61
	v_mov_b32_e32 v63, v62
	v_mov_b32_e32 v120, v62
	s_nop 1
	v_permlane16_swap_b32_e32 v63, v120
	v_lshlrev_b32_e32 v60, 16, v24
	v_and_b32_e32 v61, 0xffff0000, v24
	v_lshlrev_b32_e32 v24, 16, v31
	v_and_b32_e32 v25, 0xffff0000, v31
	s_waitcnt lgkmcnt(0)
	v_add_f32_e32 v64, v63, v120
	v_mov_b32_e32 v65, v64
	v_mov_b32_e32 v120, v64
	s_nop 1
	v_permlane32_swap_b32_e32 v65, v120
	v_lshlrev_b32_e32 v62, 16, v30
	v_and_b32_e32 v63, 0xffff0000, v30
	v_lshlrev_b32_e32 v30, 16, v29
	s_waitcnt lgkmcnt(0)
	v_add_f32_e32 v31, v65, v120
	v_fmamk_f32 v31, v31, 0x3a800000, v204
	v_mul_f32_e32 v64, 0x4b800000, v31
	v_cmp_gt_f32_e64 s[42:43], s33, v31
	v_and_b32_e32 v65, 0xffff0000, v28
	s_nop 0
	v_cndmask_b32_e64 v31, v31, v64, s[42:43]
	v_rsq_f32_e32 v66, v31
	v_lshlrev_b32_e32 v64, 16, v28
	v_and_b32_e32 v31, 0xffff0000, v29
	v_mul_f32_e32 v28, 0x45800000, v66
	v_cndmask_b32_e64 v28, v66, v28, s[42:43]
	v_pk_mul_f32 v[56:57], v[28:29], v[56:57] op_sel_hi:[0,1]
	v_pk_mul_f32 v[22:23], v[28:29], v[22:23] op_sel_hi:[0,1]
	v_pk_mul_f32 v[16:17], v[28:29], v[16:17] op_sel_hi:[0,1]
	v_pk_mul_f32 v[52:53], v[28:29], v[52:53] op_sel_hi:[0,1]
	v_pk_mul_f32 v[54:55], v[28:29], v[54:55] op_sel_hi:[0,1]
	v_pk_mul_f32 v[18:19], v[28:29], v[18:19] op_sel_hi:[0,1]
	v_pk_fma_f32 v[36:37], v[36:37], v[56:57], v[64:65]
	v_pk_fma_f32 v[22:23], v[38:39], v[22:23], v[30:31]
	v_pk_fma_f32 v[16:17], v[34:35], v[16:17], v[24:25]
	v_pk_fma_f32 v[24:25], v[44:45], v[52:53], v[60:61]
	v_pk_mul_f32 v[50:51], v[28:29], v[50:51] op_sel_hi:[0,1]
	v_pk_mul_f32 v[28:29], v[28:29], v[48:49] op_sel_hi:[0,1]
	v_pk_fma_f32 v[32:33], v[32:33], v[54:55], v[62:63]
	v_pk_fma_f32 v[26:27], v[46:47], v[18:19], v[26:27]
	v_cvt_pk_bf16_f32 v18, v36, v37
	v_cvt_pk_bf16_f32 v19, v22, v23
	v_cvt_pk_bf16_f32 v22, v24, v25
	v_pk_fma_f32 v[28:29], v[42:43], v[28:29], v[20:21]
	v_cvt_pk_bf16_f32 v20, v32, v33
	v_cvt_pk_bf16_f32 v21, v16, v17
	v_and_b32_e32 v17, 0xffff0000, v18
	v_and_b32_e32 v33, 0xffff0000, v22
	v_cvt_pk_bf16_f32 v23, v26, v27
	v_lshlrev_b32_e32 v16, 16, v18
	v_lshlrev_b32_e32 v32, 16, v22
	v_mul_f32_e32 v17, v17, v17
	v_mul_f32_e32 v33, v33, v33
	v_pk_fma_f32 v[30:31], v[40:41], v[50:51], v[58:59]
	v_lshlrev_b32_e32 v26, 16, v19
	v_lshlrev_b32_e32 v34, 16, v23
	v_fmac_f32_e32 v17, v16, v16
	v_fmac_f32_e32 v33, v32, v32
	v_cvt_pk_bf16_f32 v24, v30, v31
	v_and_b32_e32 v27, 0xffff0000, v19
	v_and_b32_e32 v35, 0xffff0000, v23
	v_fmac_f32_e32 v17, v26, v26
	v_fmac_f32_e32 v33, v34, v34
	v_cvt_pk_bf16_f32 v25, v28, v29
	v_lshlrev_b32_e32 v28, 16, v20
	v_lshlrev_b32_e32 v36, 16, v24
	v_fmac_f32_e32 v17, v27, v27
	v_fmac_f32_e32 v33, v35, v35
	v_and_b32_e32 v29, 0xffff0000, v20
	v_and_b32_e32 v37, 0xffff0000, v24
	v_fmac_f32_e32 v17, v28, v28
	v_fmac_f32_e32 v33, v36, v36
	v_lshlrev_b32_e32 v30, 16, v21
	v_lshlrev_b32_e32 v38, 16, v25
	v_fmac_f32_e32 v17, v29, v29
	v_fmac_f32_e32 v33, v37, v37
	v_and_b32_e32 v31, 0xffff0000, v21
	v_and_b32_e32 v39, 0xffff0000, v25
	v_fmac_f32_e32 v17, v30, v30
	v_fmac_f32_e32 v33, v38, v38
	v_fmac_f32_e32 v17, v31, v31
	v_fmac_f32_e32 v33, v39, v39
	v_add_f32_e32 v16, v17, v33
	s_nop 1
	v_mov_b32_dpp v17, v16 quad_perm:[1,0,3,2] row_mask:0xf bank_mask:0xf
	global_store_dwordx4 v[8:9], v[18:21], off
	global_store_dwordx4 v[8:9], v[22:25], off offset:1024
	s_waitcnt lgkmcnt(0)
	v_add_f32_e32 v16, v16, v17
	s_nop 1
	v_mov_b32_dpp v17, v16 quad_perm:[2,3,0,1] row_mask:0xf bank_mask:0xf
	s_waitcnt lgkmcnt(0)
	v_add_f32_e32 v16, v16, v17
	s_nop 1
	v_mov_b32_dpp v17, v16 row_half_mirror row_mask:0xf bank_mask:0xf
	s_waitcnt lgkmcnt(0)
	v_add_f32_e32 v16, v16, v17
	s_nop 1
	v_mov_b32_dpp v17, v16 row_mirror row_mask:0xf bank_mask:0xf
	s_waitcnt lgkmcnt(0)
	v_add_f32_e32 v16, v16, v17
	v_mov_b32_e32 v17, v16
	v_mov_b32_e32 v120, v16
	s_nop 1
	v_permlane16_swap_b32_e32 v17, v120
	s_waitcnt lgkmcnt(0)
	v_add_f32_e32 v16, v17, v120
	v_mov_b32_e32 v17, v16
	v_mov_b32_e32 v120, v16
	s_nop 1
	v_permlane32_swap_b32_e32 v17, v120
	s_and_saveexec_b64 s[38:39], vcc
	s_cbranch_execz .LBB0_487
; DI void rw_phase(const float* x, bf16_t* hb, const bf16_t* y, const float* gpost, float* rh, float* fout, bool y_unscaled) {
;     ...
;       if (lane == 0) gst<float>(rh + row, rsqrtf(s2 * (1.0f / 1024.0f) + EPS));
	s_waitcnt lgkmcnt(0)
	v_add_f32_e32 v8, v17, v120
	v_fmamk_f32 v8, v8, 0x3a800000, v204
	v_mul_f32_e32 v9, 0x4b800000, v8
	v_cmp_gt_f32_e64 s[42:43], s33, v8
	s_nop 1
	v_cndmask_b32_e64 v8, v8, v9, s[42:43]
	v_rsq_f32_e32 v16, v8
	v_lshl_add_u64 v[8:9], v[0:1], 2, s[74:75]
	v_mul_f32_e32 v1, 0x45800000, v16
	v_cndmask_b32_e64 v1, v16, v1, s[42:43]
	global_store_dword v[8:9], v1, off
	s_branch .LBB0_487

; DI float bflo(unsigned w) { return __uint_as_float(w << 16); }
; DI float bfhi(unsigned w) { return __uint_as_float(w & 0xffff0000u); }
;   static DI void run(f32x2 (&acc)[32], const f32x2 (&wt)[31], const unsigned* tile, int tid) { conv_row<R0>(acc, wt, tile, tid); ConvRows<R0 + 1, N - 1>::run(acc, wt, tile, tid); }
; template <int R> DI void conv_row(f32x2 (&acc)[32], const f32x2 (&wt)[31], const unsigned* tile, int tid) {
;   const unsigned x = tile[R * 512 + tid];
;   const f32x2 xv = {bflo(x), bfhi(x)};
; #pragma unroll
;   for (int i = 0; i < 32; ++i) { if (R - i >= 0 && R - i < 31) acc[i] = acc[i] + xv * wt[(R - i >= 0 && R - i < 31) ? R - i : 0]; }
;   if ((R & 7) == 7) asm volatile("" ::: "memory");
; DI void conv_phase(const bf16_t* hc, bf16_t* hn, char* lds) {
;     ...
;     __syncthreads();
;     const float* wd2 = wdw; asm volatile("" : "+s"(wd2));
;     f32x2 acc[32], wt[31];
; #pragma unroll
;     for (int i = 0; i < 32; ++i) acc[i] = bdw;
; #pragma unroll
;     for (int j = 0; j < 31; ++j) wt[j] = gld<f32x2>(wd2 + j * 1024 + 2 * tid);
;     ConvRows<0, 62>::run(acc, wt, tile, tid);
.LBB0_708:
	s_or_b64 exec, exec, s[26:27]
	s_mov_b64 s[26:27], s[84:85]
	s_waitcnt lgkmcnt(0)
	s_barrier
	s_waitcnt vmcnt(0)
	v_lshl_add_u64 v[0:1], v[32:33], 2, s[26:27]
	v_add_co_u32_e32 v2, vcc, 0x1000, v0
	global_load_dwordx2 v[68:69], v[0:1], off
	s_nop 0
	v_addc_co_u32_e32 v3, vcc, 0, v1, vcc
	global_load_dwordx2 v[72:73], v[2:3], off
	v_add_co_u32_e32 v2, vcc, 0x2000, v0
	s_movk_i32 s26, 0x3000
	s_nop 0
	v_addc_co_u32_e32 v3, vcc, 0, v1, vcc
	global_load_dwordx2 v[64:65], v[2:3], off
	v_add_co_u32_e32 v2, vcc, s26, v0
	s_movk_i32 s26, 0x6000
	s_nop 0
	v_addc_co_u32_e32 v3, vcc, 0, v1, vcc
	global_load_dwordx2 v[66:67], v[2:3], off
	v_add_co_u32_e32 v2, vcc, 0x4000, v0
	s_nop 1
	v_addc_co_u32_e32 v3, vcc, 0, v1, vcc
	global_load_dwordx2 v[56:57], v[2:3], off
	v_add_co_u32_e32 v2, vcc, 0x5000, v0
	s_nop 1
	v_addc_co_u32_e32 v3, vcc, 0, v1, vcc
	global_load_dwordx2 v[54:55], v[2:3], off
	v_add_co_u32_e32 v2, vcc, s26, v0
	s_mov_b32 s26, 0x11000
	s_nop 0
	v_addc_co_u32_e32 v3, vcc, 0, v1, vcc
	global_load_dwordx2 v[50:51], v[2:3], off
	v_add_co_u32_e32 v2, vcc, 0x7000, v0
	s_nop 1
	v_addc_co_u32_e32 v3, vcc, 0, v1, vcc
	global_load_dwordx2 v[62:63], v[2:3], off
	v_add_co_u32_e32 v2, vcc, s63, v0
	s_nop 1
	v_addc_co_u32_e32 v3, vcc, 0, v1, vcc
	global_load_dwordx2 v[58:59], v[2:3], off
	v_add_co_u32_e32 v2, vcc, 0x9000, v0
	s_nop 1
	v_addc_co_u32_e32 v3, vcc, 0, v1, vcc
	global_load_dwordx2 v[60:61], v[2:3], off
	v_add_co_u32_e32 v2, vcc, 0xa000, v0
	s_nop 1
	v_addc_co_u32_e32 v3, vcc, 0, v1, vcc
	global_load_dwordx2 v[48:49], v[2:3], off
	v_add_co_u32_e32 v2, vcc, 0xb000, v0
	s_nop 1
	v_addc_co_u32_e32 v3, vcc, 0, v1, vcc
	global_load_dwordx2 v[52:53], v[2:3], off
	v_add_co_u32_e32 v2, vcc, 0xc000, v0
	s_nop 1
	v_addc_co_u32_e32 v3, vcc, 0, v1, vcc
	global_load_dwordx2 v[44:45], v[2:3], off
	v_add_co_u32_e32 v2, vcc, 0xd000, v0
	s_nop 1
	v_addc_co_u32_e32 v3, vcc, 0, v1, vcc
	global_load_dwordx2 v[28:29], v[2:3], off
	v_add_co_u32_e32 v2, vcc, 0xe000, v0
	s_nop 1
	v_addc_co_u32_e32 v3, vcc, 0, v1, vcc
	global_load_dwordx2 v[24:25], v[2:3], off
	v_add_co_u32_e32 v2, vcc, 0xf000, v0
	s_nop 1
	v_addc_co_u32_e32 v3, vcc, 0, v1, vcc
	global_load_dwordx2 v[46:47], v[2:3], off
	v_add_co_u32_e32 v2, vcc, s26, v0
	s_mov_b32 s26, 0x13000
	s_nop 0
	v_addc_co_u32_e32 v3, vcc, 0, v1, vcc
	global_load_dwordx2 v[26:27], v[2:3], off offset:-4096
	global_load_dwordx2 v[30:31], v[2:3], off
	v_add_co_u32_e32 v2, vcc, s26, v0
	s_mov_b32 s26, 0x15000
	s_nop 0
	v_addc_co_u32_e32 v3, vcc, 0, v1, vcc
	global_load_dwordx2 v[20:21], v[2:3], off offset:-4096
	global_load_dwordx2 v[22:23], v[2:3], off
	v_add_co_u32_e32 v2, vcc, s26, v0
	s_mov_b32 s26, 0x17000
	s_nop 0
	v_addc_co_u32_e32 v3, vcc, 0, v1, vcc
	global_load_dwordx2 v[16:17], v[2:3], off offset:-4096
	global_load_dwordx2 v[14:15], v[2:3], off
	v_add_co_u32_e32 v2, vcc, s26, v0
	s_mov_b32 s26, 0x19000
	s_nop 0
	v_addc_co_u32_e32 v3, vcc, 0, v1, vcc
	global_load_dwordx2 v[12:13], v[2:3], off offset:-4096
	global_load_dwordx2 v[18:19], v[2:3], off
	v_add_co_u32_e32 v2, vcc, s26, v0
	s_mov_b32 s26, 0x1b000
	s_nop 0
	v_addc_co_u32_e32 v3, vcc, 0, v1, vcc
	global_load_dwordx2 v[10:11], v[2:3], off offset:-4096
	global_load_dwordx2 v[8:9], v[2:3], off
	v_add_co_u32_e32 v2, vcc, s26, v0
	s_mov_b32 s26, 0x1d000
	s_nop 0
	v_addc_co_u32_e32 v3, vcc, 0, v1, vcc
	v_add_co_u32_e32 v70, vcc, s26, v0
	global_load_dwordx2 v[6:7], v[2:3], off offset:-4096
	global_load_dwordx2 v[4:5], v[2:3], off
	v_addc_co_u32_e32 v71, vcc, 0, v1, vcc
	s_mov_b32 s26, 0x1e000
	v_add_co_u32_e32 v0, vcc, s26, v0
	global_load_dwordx2 v[2:3], v[70:71], off offset:-4096
	s_nop 0
	global_load_dwordx2 v[70:71], v[70:71], off
	v_addc_co_u32_e32 v1, vcc, 0, v1, vcc
	global_load_dwordx2 v[0:1], v[0:1], off
	ds_read2st64_b32 v[74:75], v124 offset1:8
	ds_read2st64_b32 v[78:79], v124 offset0:16 offset1:24
	ds_read2st64_b32 v[82:83], v124 offset0:32 offset1:40
	ds_read2st64_b32 v[86:87], v124 offset0:48 offset1:56
	s_waitcnt lgkmcnt(3)
	v_lshlrev_b32_e32 v76, 16, v74
	v_and_b32_e32 v77, 0xffff0000, v74
	s_waitcnt vmcnt(30)
	v_pk_fma_f32 v[76:77], v[68:69], v[76:77], v[34:35]
	v_lshlrev_b32_e32 v74, 16, v75
	v_and_b32_e32 v75, 0xffff0000, v75
	s_waitcnt vmcnt(29)
	v_pk_fma_f32 v[76:77], v[72:73], v[74:75], v[76:77]
	v_pk_fma_f32 v[74:75], v[68:69], v[74:75], v[34:35]
	s_waitcnt lgkmcnt(2)
	v_lshlrev_b32_e32 v80, 16, v78
	v_and_b32_e32 v81, 0xffff0000, v78
	s_waitcnt vmcnt(28)
	v_pk_fma_f32 v[76:77], v[64:65], v[80:81], v[76:77]
	v_pk_fma_f32 v[74:75], v[72:73], v[80:81], v[74:75]
	v_pk_fma_f32 v[80:81], v[68:69], v[80:81], v[34:35]
	v_lshlrev_b32_e32 v78, 16, v79
	v_and_b32_e32 v79, 0xffff0000, v79
	ds_read2st64_b32 v[90:91], v124 offset0:64 offset1:72
	s_waitcnt vmcnt(27)
	v_pk_fma_f32 v[76:77], v[66:67], v[78:79], v[76:77]
	v_pk_fma_f32 v[74:75], v[64:65], v[78:79], v[74:75]
	v_pk_fma_f32 v[80:81], v[72:73], v[78:79], v[80:81]
	v_pk_fma_f32 v[78:79], v[68:69], v[78:79], v[34:35]
	s_waitcnt lgkmcnt(2)
	v_lshlrev_b32_e32 v84, 16, v82
	v_and_b32_e32 v85, 0xffff0000, v82
	s_waitcnt vmcnt(26)
	v_pk_fma_f32 v[76:77], v[56:57], v[84:85], v[76:77]
	v_pk_fma_f32 v[74:75], v[66:67], v[84:85], v[74:75]
	v_pk_fma_f32 v[80:81], v[64:65], v[84:85], v[80:81]
	v_pk_fma_f32 v[78:79], v[72:73], v[84:85], v[78:79]
	v_pk_fma_f32 v[84:85], v[68:69], v[84:85], v[34:35]
	v_lshlrev_b32_e32 v82, 16, v83
	v_and_b32_e32 v83, 0xffff0000, v83
	ds_read2st64_b32 v[94:95], v124 offset0:80 offset1:88
	s_waitcnt vmcnt(25)
; DI float bflo(unsigned w) { return __uint_as_float(w << 16); }
; DI float bfhi(unsigned w) { return __uint_as_float(w & 0xffff0000u); }
; template <int R> DI void conv_row(f32x2 (&acc)[32], const f32x2 (&wt)[31], const unsigned* tile, int tid) {
;   const unsigned x = tile[R * 512 + tid];
;   const f32x2 xv = {bflo(x), bfhi(x)};
; #pragma unroll
;   for (int i = 0; i < 32; ++i) { if (R - i >= 0 && R - i < 31) acc[i] = acc[i] + xv * wt[(R - i >= 0 && R - i < 31) ? R - i : 0]; }
;   if ((R & 7) == 7) asm volatile("" ::: "memory");
	v_pk_fma_f32 v[76:77], v[54:55], v[82:83], v[76:77]
	v_pk_fma_f32 v[74:75], v[56:57], v[82:83], v[74:75]
	v_pk_fma_f32 v[80:81], v[66:67], v[82:83], v[80:81]
	v_pk_fma_f32 v[78:79], v[64:65], v[82:83], v[78:79]
	v_pk_fma_f32 v[84:85], v[72:73], v[82:83], v[84:85]
	v_pk_fma_f32 v[82:83], v[68:69], v[82:83], v[34:35]
	s_waitcnt lgkmcnt(2)
	v_lshlrev_b32_e32 v88, 16, v86
	v_and_b32_e32 v89, 0xffff0000, v86
	s_waitcnt vmcnt(24)
	v_pk_fma_f32 v[76:77], v[50:51], v[88:89], v[76:77]
	v_pk_fma_f32 v[74:75], v[54:55], v[88:89], v[74:75]
	v_pk_fma_f32 v[80:81], v[56:57], v[88:89], v[80:81]
	v_pk_fma_f32 v[78:79], v[66:67], v[88:89], v[78:79]
	v_pk_fma_f32 v[84:85], v[64:65], v[88:89], v[84:85]
	v_pk_fma_f32 v[82:83], v[72:73], v[88:89], v[82:83]
	v_pk_fma_f32 v[88:89], v[68:69], v[88:89], v[34:35]
	v_lshlrev_b32_e32 v86, 16, v87
	v_and_b32_e32 v87, 0xffff0000, v87
	ds_read2st64_b32 v[98:99], v124 offset0:96 offset1:104
	s_waitcnt vmcnt(23)
	v_pk_fma_f32 v[76:77], v[62:63], v[86:87], v[76:77]
	v_pk_fma_f32 v[74:75], v[50:51], v[86:87], v[74:75]
	v_pk_fma_f32 v[80:81], v[54:55], v[86:87], v[80:81]
	v_pk_fma_f32 v[78:79], v[56:57], v[86:87], v[78:79]
	v_pk_fma_f32 v[84:85], v[66:67], v[86:87], v[84:85]
	v_pk_fma_f32 v[82:83], v[64:65], v[86:87], v[82:83]
	v_pk_fma_f32 v[88:89], v[72:73], v[86:87], v[88:89]
	v_pk_fma_f32 v[86:87], v[68:69], v[86:87], v[34:35]
	s_waitcnt lgkmcnt(2)
	v_lshlrev_b32_e32 v92, 16, v90
	v_and_b32_e32 v93, 0xffff0000, v90
	s_waitcnt vmcnt(22)
	v_pk_fma_f32 v[76:77], v[58:59], v[92:93], v[76:77]
	v_pk_fma_f32 v[74:75], v[62:63], v[92:93], v[74:75]
	v_pk_fma_f32 v[80:81], v[50:51], v[92:93], v[80:81]
	v_pk_fma_f32 v[78:79], v[54:55], v[92:93], v[78:79]
	v_pk_fma_f32 v[84:85], v[56:57], v[92:93], v[84:85]
	v_pk_fma_f32 v[82:83], v[66:67], v[92:93], v[82:83]
	v_pk_fma_f32 v[88:89], v[64:65], v[92:93], v[88:89]
	v_pk_fma_f32 v[86:87], v[72:73], v[92:93], v[86:87]
	v_pk_fma_f32 v[92:93], v[68:69], v[92:93], v[34:35]
	v_lshlrev_b32_e32 v90, 16, v91
	v_and_b32_e32 v91, 0xffff0000, v91
	ds_read2st64_b32 v[102:103], v124 offset0:112 offset1:120
	s_waitcnt vmcnt(21)
	v_pk_fma_f32 v[76:77], v[60:61], v[90:91], v[76:77]
	v_pk_fma_f32 v[74:75], v[58:59], v[90:91], v[74:75]
	v_pk_fma_f32 v[80:81], v[62:63], v[90:91], v[80:81]
	v_pk_fma_f32 v[78:79], v[50:51], v[90:91], v[78:79]
	v_pk_fma_f32 v[84:85], v[54:55], v[90:91], v[84:85]
	v_pk_fma_f32 v[82:83], v[56:57], v[90:91], v[82:83]
	v_pk_fma_f32 v[88:89], v[66:67], v[90:91], v[88:89]
	v_pk_fma_f32 v[86:87], v[64:65], v[90:91], v[86:87]
	v_pk_fma_f32 v[92:93], v[72:73], v[90:91], v[92:93]
	v_pk_fma_f32 v[90:91], v[68:69], v[90:91], v[34:35]
	s_waitcnt lgkmcnt(2)
	v_lshlrev_b32_e32 v96, 16, v94
	v_and_b32_e32 v97, 0xffff0000, v94
	s_waitcnt vmcnt(20)
	v_pk_fma_f32 v[76:77], v[48:49], v[96:97], v[76:77]
	v_pk_fma_f32 v[74:75], v[60:61], v[96:97], v[74:75]
	v_pk_fma_f32 v[80:81], v[58:59], v[96:97], v[80:81]
	v_pk_fma_f32 v[78:79], v[62:63], v[96:97], v[78:79]
	v_pk_fma_f32 v[84:85], v[50:51], v[96:97], v[84:85]
	v_pk_fma_f32 v[82:83], v[54:55], v[96:97], v[82:83]
	v_pk_fma_f32 v[88:89], v[56:57], v[96:97], v[88:89]
	v_pk_fma_f32 v[86:87], v[66:67], v[96:97], v[86:87]
	v_pk_fma_f32 v[92:93], v[64:65], v[96:97], v[92:93]
	v_pk_fma_f32 v[90:91], v[72:73], v[96:97], v[90:91]
	v_pk_fma_f32 v[96:97], v[68:69], v[96:97], v[34:35]
	v_lshlrev_b32_e32 v94, 16, v95
	v_and_b32_e32 v95, 0xffff0000, v95
	ds_read2st64_b32 v[106:107], v124 offset0:128 offset1:136
	s_waitcnt vmcnt(19)
	v_pk_fma_f32 v[76:77], v[52:53], v[94:95], v[76:77]
	v_pk_fma_f32 v[74:75], v[48:49], v[94:95], v[74:75]
	v_pk_fma_f32 v[80:81], v[60:61], v[94:95], v[80:81]
	v_pk_fma_f32 v[78:79], v[58:59], v[94:95], v[78:79]
	v_pk_fma_f32 v[84:85], v[62:63], v[94:95], v[84:85]
	v_pk_fma_f32 v[82:83], v[50:51], v[94:95], v[82:83]
	v_pk_fma_f32 v[88:89], v[54:55], v[94:95], v[88:89]
	v_pk_fma_f32 v[86:87], v[56:57], v[94:95], v[86:87]
	v_pk_fma_f32 v[92:93], v[66:67], v[94:95], v[92:93]
	v_pk_fma_f32 v[90:91], v[64:65], v[94:95], v[90:91]
	v_pk_fma_f32 v[96:97], v[72:73], v[94:95], v[96:97]
	v_pk_fma_f32 v[94:95], v[68:69], v[94:95], v[34:35]
	s_waitcnt lgkmcnt(2)
	v_lshlrev_b32_e32 v100, 16, v98
	v_and_b32_e32 v101, 0xffff0000, v98
	s_waitcnt vmcnt(18)
	v_pk_fma_f32 v[76:77], v[44:45], v[100:101], v[76:77]
	v_pk_fma_f32 v[74:75], v[52:53], v[100:101], v[74:75]
	v_pk_fma_f32 v[80:81], v[48:49], v[100:101], v[80:81]
	v_pk_fma_f32 v[78:79], v[60:61], v[100:101], v[78:79]
	v_pk_fma_f32 v[84:85], v[58:59], v[100:101], v[84:85]
	v_pk_fma_f32 v[82:83], v[62:63], v[100:101], v[82:83]
	v_pk_fma_f32 v[88:89], v[50:51], v[100:101], v[88:89]
	v_pk_fma_f32 v[86:87], v[54:55], v[100:101], v[86:87]
	v_pk_fma_f32 v[92:93], v[56:57], v[100:101], v[92:93]
	v_pk_fma_f32 v[90:91], v[66:67], v[100:101], v[90:91]
	v_pk_fma_f32 v[96:97], v[64:65], v[100:101], v[96:97]
	v_pk_fma_f32 v[94:95], v[72:73], v[100:101], v[94:95]
	v_pk_fma_f32 v[100:101], v[68:69], v[100:101], v[34:35]
	v_lshlrev_b32_e32 v98, 16, v99
	v_and_b32_e32 v99, 0xffff0000, v99
	ds_read2st64_b32 v[110:111], v124 offset0:144 offset1:152
	s_waitcnt vmcnt(17)
	v_pk_fma_f32 v[76:77], v[28:29], v[98:99], v[76:77]
	v_pk_fma_f32 v[74:75], v[44:45], v[98:99], v[74:75]
	v_pk_fma_f32 v[80:81], v[52:53], v[98:99], v[80:81]
	v_pk_fma_f32 v[78:79], v[48:49], v[98:99], v[78:79]
	v_pk_fma_f32 v[84:85], v[60:61], v[98:99], v[84:85]
	v_pk_fma_f32 v[82:83], v[58:59], v[98:99], v[82:83]
	v_pk_fma_f32 v[88:89], v[62:63], v[98:99], v[88:89]
	v_pk_fma_f32 v[86:87], v[50:51], v[98:99], v[86:87]
	v_pk_fma_f32 v[92:93], v[54:55], v[98:99], v[92:93]
	v_pk_fma_f32 v[90:91], v[56:57], v[98:99], v[90:91]
	v_pk_fma_f32 v[96:97], v[66:67], v[98:99], v[96:97]
	v_pk_fma_f32 v[94:95], v[64:65], v[98:99], v[94:95]
	v_pk_fma_f32 v[100:101], v[72:73], v[98:99], v[100:101]
	v_pk_fma_f32 v[98:99], v[68:69], v[98:99], v[34:35]
	s_waitcnt lgkmcnt(2)
; DI float bflo(unsigned w) { return __uint_as_float(w << 16); }
; DI float bfhi(unsigned w) { return __uint_as_float(w & 0xffff0000u); }
; template <int R> DI void conv_row(f32x2 (&acc)[32], const f32x2 (&wt)[31], const unsigned* tile, int tid) {
;   const unsigned x = tile[R * 512 + tid];
;   const f32x2 xv = {bflo(x), bfhi(x)};
; #pragma unroll
;   for (int i = 0; i < 32; ++i) { if (R - i >= 0 && R - i < 31) acc[i] = acc[i] + xv * wt[(R - i >= 0 && R - i < 31) ? R - i : 0]; }
;   if ((R & 7) == 7) asm volatile("" ::: "memory");
	v_lshlrev_b32_e32 v104, 16, v102
	v_and_b32_e32 v105, 0xffff0000, v102
	s_waitcnt vmcnt(16)
	v_pk_fma_f32 v[76:77], v[24:25], v[104:105], v[76:77]
	v_pk_fma_f32 v[74:75], v[28:29], v[104:105], v[74:75]
	v_pk_fma_f32 v[80:81], v[44:45], v[104:105], v[80:81]
	v_pk_fma_f32 v[78:79], v[52:53], v[104:105], v[78:79]
	v_pk_fma_f32 v[84:85], v[48:49], v[104:105], v[84:85]
	v_pk_fma_f32 v[82:83], v[60:61], v[104:105], v[82:83]
	v_pk_fma_f32 v[88:89], v[58:59], v[104:105], v[88:89]
	v_pk_fma_f32 v[86:87], v[62:63], v[104:105], v[86:87]
	v_pk_fma_f32 v[92:93], v[50:51], v[104:105], v[92:93]
	v_pk_fma_f32 v[90:91], v[54:55], v[104:105], v[90:91]
	v_pk_fma_f32 v[96:97], v[56:57], v[104:105], v[96:97]
	v_pk_fma_f32 v[94:95], v[66:67], v[104:105], v[94:95]
	v_pk_fma_f32 v[100:101], v[64:65], v[104:105], v[100:101]
	v_pk_fma_f32 v[98:99], v[72:73], v[104:105], v[98:99]
	v_pk_fma_f32 v[104:105], v[68:69], v[104:105], v[34:35]
	v_lshlrev_b32_e32 v102, 16, v103
	v_and_b32_e32 v103, 0xffff0000, v103
	ds_read2st64_b32 v[114:115], v124 offset0:160 offset1:168
	s_waitcnt vmcnt(15)
	v_pk_fma_f32 v[76:77], v[46:47], v[102:103], v[76:77]
	v_pk_fma_f32 v[74:75], v[24:25], v[102:103], v[74:75]
	v_pk_fma_f32 v[80:81], v[28:29], v[102:103], v[80:81]
	v_pk_fma_f32 v[78:79], v[44:45], v[102:103], v[78:79]
	v_pk_fma_f32 v[84:85], v[52:53], v[102:103], v[84:85]
	v_pk_fma_f32 v[82:83], v[48:49], v[102:103], v[82:83]
	v_pk_fma_f32 v[88:89], v[60:61], v[102:103], v[88:89]
	v_pk_fma_f32 v[86:87], v[58:59], v[102:103], v[86:87]
	v_pk_fma_f32 v[92:93], v[62:63], v[102:103], v[92:93]
	v_pk_fma_f32 v[90:91], v[50:51], v[102:103], v[90:91]
	v_pk_fma_f32 v[96:97], v[54:55], v[102:103], v[96:97]
	v_pk_fma_f32 v[94:95], v[56:57], v[102:103], v[94:95]
	v_pk_fma_f32 v[100:101], v[66:67], v[102:103], v[100:101]
	v_pk_fma_f32 v[98:99], v[64:65], v[102:103], v[98:99]
	v_pk_fma_f32 v[104:105], v[72:73], v[102:103], v[104:105]
	v_pk_fma_f32 v[102:103], v[68:69], v[102:103], v[34:35]
	s_waitcnt lgkmcnt(2)
	v_lshlrev_b32_e32 v108, 16, v106
	v_and_b32_e32 v109, 0xffff0000, v106
	s_waitcnt vmcnt(14)
	v_pk_fma_f32 v[76:77], v[26:27], v[108:109], v[76:77]
	v_pk_fma_f32 v[74:75], v[46:47], v[108:109], v[74:75]
	v_pk_fma_f32 v[80:81], v[24:25], v[108:109], v[80:81]
	v_pk_fma_f32 v[78:79], v[28:29], v[108:109], v[78:79]
	v_pk_fma_f32 v[84:85], v[44:45], v[108:109], v[84:85]
	v_pk_fma_f32 v[82:83], v[52:53], v[108:109], v[82:83]
	v_pk_fma_f32 v[88:89], v[48:49], v[108:109], v[88:89]
	v_pk_fma_f32 v[86:87], v[60:61], v[108:109], v[86:87]
	v_pk_fma_f32 v[92:93], v[58:59], v[108:109], v[92:93]
	v_pk_fma_f32 v[90:91], v[62:63], v[108:109], v[90:91]
	v_pk_fma_f32 v[96:97], v[50:51], v[108:109], v[96:97]
	v_pk_fma_f32 v[94:95], v[54:55], v[108:109], v[94:95]
	v_pk_fma_f32 v[100:101], v[56:57], v[108:109], v[100:101]
	v_pk_fma_f32 v[98:99], v[66:67], v[108:109], v[98:99]
	v_pk_fma_f32 v[104:105], v[64:65], v[108:109], v[104:105]
	v_pk_fma_f32 v[102:103], v[72:73], v[108:109], v[102:103]
	v_pk_fma_f32 v[108:109], v[68:69], v[108:109], v[34:35]
	v_lshlrev_b32_e32 v106, 16, v107
	v_and_b32_e32 v107, 0xffff0000, v107
	ds_read2st64_b32 v[118:119], v124 offset0:176 offset1:184
	s_waitcnt vmcnt(13)
	v_pk_fma_f32 v[76:77], v[30:31], v[106:107], v[76:77]
	v_pk_fma_f32 v[74:75], v[26:27], v[106:107], v[74:75]
	v_pk_fma_f32 v[80:81], v[46:47], v[106:107], v[80:81]
	v_pk_fma_f32 v[78:79], v[24:25], v[106:107], v[78:79]
	v_pk_fma_f32 v[84:85], v[28:29], v[106:107], v[84:85]
	v_pk_fma_f32 v[82:83], v[44:45], v[106:107], v[82:83]
	v_pk_fma_f32 v[88:89], v[52:53], v[106:107], v[88:89]
	v_pk_fma_f32 v[86:87], v[48:49], v[106:107], v[86:87]
	v_pk_fma_f32 v[92:93], v[60:61], v[106:107], v[92:93]
	v_pk_fma_f32 v[90:91], v[58:59], v[106:107], v[90:91]
	v_pk_fma_f32 v[96:97], v[62:63], v[106:107], v[96:97]
	v_pk_fma_f32 v[94:95], v[50:51], v[106:107], v[94:95]
	v_pk_fma_f32 v[100:101], v[54:55], v[106:107], v[100:101]
	v_pk_fma_f32 v[98:99], v[56:57], v[106:107], v[98:99]
	v_pk_fma_f32 v[104:105], v[66:67], v[106:107], v[104:105]
	v_pk_fma_f32 v[102:103], v[64:65], v[106:107], v[102:103]
	v_pk_fma_f32 v[108:109], v[72:73], v[106:107], v[108:109]
	v_pk_fma_f32 v[106:107], v[68:69], v[106:107], v[34:35]
	s_waitcnt lgkmcnt(2)
	v_lshlrev_b32_e32 v112, 16, v110
	v_and_b32_e32 v113, 0xffff0000, v110
	s_waitcnt vmcnt(12)
	v_pk_fma_f32 v[76:77], v[20:21], v[112:113], v[76:77]
	v_pk_fma_f32 v[74:75], v[30:31], v[112:113], v[74:75]
	v_pk_fma_f32 v[80:81], v[26:27], v[112:113], v[80:81]
	v_pk_fma_f32 v[78:79], v[46:47], v[112:113], v[78:79]
	v_pk_fma_f32 v[84:85], v[24:25], v[112:113], v[84:85]
	v_pk_fma_f32 v[82:83], v[28:29], v[112:113], v[82:83]
	v_pk_fma_f32 v[88:89], v[44:45], v[112:113], v[88:89]
	v_pk_fma_f32 v[86:87], v[52:53], v[112:113], v[86:87]
	v_pk_fma_f32 v[92:93], v[48:49], v[112:113], v[92:93]
	v_pk_fma_f32 v[90:91], v[60:61], v[112:113], v[90:91]
	v_pk_fma_f32 v[96:97], v[58:59], v[112:113], v[96:97]
	v_pk_fma_f32 v[94:95], v[62:63], v[112:113], v[94:95]
	v_pk_fma_f32 v[100:101], v[50:51], v[112:113], v[100:101]
	v_pk_fma_f32 v[98:99], v[54:55], v[112:113], v[98:99]
	v_pk_fma_f32 v[104:105], v[56:57], v[112:113], v[104:105]
	v_pk_fma_f32 v[102:103], v[66:67], v[112:113], v[102:103]
	v_pk_fma_f32 v[108:109], v[64:65], v[112:113], v[108:109]
	v_pk_fma_f32 v[106:107], v[72:73], v[112:113], v[106:107]
	v_pk_fma_f32 v[112:113], v[68:69], v[112:113], v[34:35]
	v_lshlrev_b32_e32 v110, 16, v111
	v_and_b32_e32 v111, 0xffff0000, v111
	ds_read2st64_b32 v[122:123], v124 offset0:192 offset1:200
	s_waitcnt vmcnt(11)
; DI float bflo(unsigned w) { return __uint_as_float(w << 16); }
; DI float bfhi(unsigned w) { return __uint_as_float(w & 0xffff0000u); }
; template <int R> DI void conv_row(f32x2 (&acc)[32], const f32x2 (&wt)[31], const unsigned* tile, int tid) {
;   const unsigned x = tile[R * 512 + tid];
;   const f32x2 xv = {bflo(x), bfhi(x)};
; #pragma unroll
;   for (int i = 0; i < 32; ++i) { if (R - i >= 0 && R - i < 31) acc[i] = acc[i] + xv * wt[(R - i >= 0 && R - i < 31) ? R - i : 0]; }
;   if ((R & 7) == 7) asm volatile("" ::: "memory");
	v_pk_fma_f32 v[76:77], v[22:23], v[110:111], v[76:77]
	v_pk_fma_f32 v[74:75], v[20:21], v[110:111], v[74:75]
	v_pk_fma_f32 v[80:81], v[30:31], v[110:111], v[80:81]
	v_pk_fma_f32 v[78:79], v[26:27], v[110:111], v[78:79]
	v_pk_fma_f32 v[84:85], v[46:47], v[110:111], v[84:85]
	v_pk_fma_f32 v[82:83], v[24:25], v[110:111], v[82:83]
	v_pk_fma_f32 v[88:89], v[28:29], v[110:111], v[88:89]
	v_pk_fma_f32 v[86:87], v[44:45], v[110:111], v[86:87]
	v_pk_fma_f32 v[92:93], v[52:53], v[110:111], v[92:93]
	v_pk_fma_f32 v[90:91], v[48:49], v[110:111], v[90:91]
	v_pk_fma_f32 v[96:97], v[60:61], v[110:111], v[96:97]
	v_pk_fma_f32 v[94:95], v[58:59], v[110:111], v[94:95]
	v_pk_fma_f32 v[100:101], v[62:63], v[110:111], v[100:101]
	v_pk_fma_f32 v[98:99], v[50:51], v[110:111], v[98:99]
	v_pk_fma_f32 v[104:105], v[54:55], v[110:111], v[104:105]
	v_pk_fma_f32 v[102:103], v[56:57], v[110:111], v[102:103]
	v_pk_fma_f32 v[108:109], v[66:67], v[110:111], v[108:109]
	v_pk_fma_f32 v[106:107], v[64:65], v[110:111], v[106:107]
	v_pk_fma_f32 v[112:113], v[72:73], v[110:111], v[112:113]
	v_pk_fma_f32 v[110:111], v[68:69], v[110:111], v[34:35]
	s_waitcnt lgkmcnt(2)
	v_lshlrev_b32_e32 v116, 16, v114
	v_and_b32_e32 v117, 0xffff0000, v114
	s_waitcnt vmcnt(10)
	v_pk_fma_f32 v[76:77], v[16:17], v[116:117], v[76:77]
	v_pk_fma_f32 v[74:75], v[22:23], v[116:117], v[74:75]
	v_pk_fma_f32 v[80:81], v[20:21], v[116:117], v[80:81]
	v_pk_fma_f32 v[78:79], v[30:31], v[116:117], v[78:79]
	v_pk_fma_f32 v[84:85], v[26:27], v[116:117], v[84:85]
	v_pk_fma_f32 v[82:83], v[46:47], v[116:117], v[82:83]
	v_pk_fma_f32 v[88:89], v[24:25], v[116:117], v[88:89]
	v_pk_fma_f32 v[86:87], v[28:29], v[116:117], v[86:87]
	v_pk_fma_f32 v[92:93], v[44:45], v[116:117], v[92:93]
	v_pk_fma_f32 v[90:91], v[52:53], v[116:117], v[90:91]
	v_pk_fma_f32 v[96:97], v[48:49], v[116:117], v[96:97]
	v_pk_fma_f32 v[94:95], v[60:61], v[116:117], v[94:95]
	v_pk_fma_f32 v[100:101], v[58:59], v[116:117], v[100:101]
	v_pk_fma_f32 v[98:99], v[62:63], v[116:117], v[98:99]
	v_pk_fma_f32 v[104:105], v[50:51], v[116:117], v[104:105]
	v_pk_fma_f32 v[102:103], v[54:55], v[116:117], v[102:103]
	v_pk_fma_f32 v[108:109], v[56:57], v[116:117], v[108:109]
	v_pk_fma_f32 v[106:107], v[66:67], v[116:117], v[106:107]
	v_pk_fma_f32 v[112:113], v[64:65], v[116:117], v[112:113]
	v_pk_fma_f32 v[110:111], v[72:73], v[116:117], v[110:111]
	v_pk_fma_f32 v[116:117], v[68:69], v[116:117], v[34:35]
	v_lshlrev_b32_e32 v114, 16, v115
	v_and_b32_e32 v115, 0xffff0000, v115
	ds_read2st64_b32 v[242:243], v124 offset0:208 offset1:216
	s_waitcnt vmcnt(9)
	v_pk_fma_f32 v[76:77], v[14:15], v[114:115], v[76:77]
	v_pk_fma_f32 v[74:75], v[16:17], v[114:115], v[74:75]
	v_pk_fma_f32 v[80:81], v[22:23], v[114:115], v[80:81]
	v_pk_fma_f32 v[78:79], v[20:21], v[114:115], v[78:79]
	v_pk_fma_f32 v[84:85], v[30:31], v[114:115], v[84:85]
	v_pk_fma_f32 v[82:83], v[26:27], v[114:115], v[82:83]
	v_pk_fma_f32 v[88:89], v[46:47], v[114:115], v[88:89]
	v_pk_fma_f32 v[86:87], v[24:25], v[114:115], v[86:87]
	v_pk_fma_f32 v[92:93], v[28:29], v[114:115], v[92:93]
	v_pk_fma_f32 v[90:91], v[44:45], v[114:115], v[90:91]
	v_pk_fma_f32 v[96:97], v[52:53], v[114:115], v[96:97]
	v_pk_fma_f32 v[94:95], v[48:49], v[114:115], v[94:95]
	v_pk_fma_f32 v[100:101], v[60:61], v[114:115], v[100:101]
	v_pk_fma_f32 v[98:99], v[58:59], v[114:115], v[98:99]
	v_pk_fma_f32 v[104:105], v[62:63], v[114:115], v[104:105]
	v_pk_fma_f32 v[102:103], v[50:51], v[114:115], v[102:103]
	v_pk_fma_f32 v[108:109], v[54:55], v[114:115], v[108:109]
	v_pk_fma_f32 v[106:107], v[56:57], v[114:115], v[106:107]
	v_pk_fma_f32 v[112:113], v[66:67], v[114:115], v[112:113]
	v_pk_fma_f32 v[110:111], v[64:65], v[114:115], v[110:111]
	v_pk_fma_f32 v[116:117], v[72:73], v[114:115], v[116:117]
	v_pk_fma_f32 v[114:115], v[68:69], v[114:115], v[34:35]
	s_waitcnt lgkmcnt(2)
	v_lshlrev_b32_e32 v120, 16, v118
	v_and_b32_e32 v121, 0xffff0000, v118
	s_waitcnt vmcnt(8)
	v_pk_fma_f32 v[76:77], v[12:13], v[120:121], v[76:77]
	v_pk_fma_f32 v[74:75], v[14:15], v[120:121], v[74:75]
	v_pk_fma_f32 v[80:81], v[16:17], v[120:121], v[80:81]
	v_pk_fma_f32 v[78:79], v[22:23], v[120:121], v[78:79]
	v_pk_fma_f32 v[84:85], v[20:21], v[120:121], v[84:85]
	v_pk_fma_f32 v[82:83], v[30:31], v[120:121], v[82:83]
	v_pk_fma_f32 v[88:89], v[26:27], v[120:121], v[88:89]
	v_pk_fma_f32 v[86:87], v[46:47], v[120:121], v[86:87]
	v_pk_fma_f32 v[92:93], v[24:25], v[120:121], v[92:93]
	v_pk_fma_f32 v[90:91], v[28:29], v[120:121], v[90:91]
	v_pk_fma_f32 v[96:97], v[44:45], v[120:121], v[96:97]
	v_pk_fma_f32 v[94:95], v[52:53], v[120:121], v[94:95]
	v_pk_fma_f32 v[100:101], v[48:49], v[120:121], v[100:101]
	v_pk_fma_f32 v[98:99], v[60:61], v[120:121], v[98:99]
	v_pk_fma_f32 v[104:105], v[58:59], v[120:121], v[104:105]
	v_pk_fma_f32 v[102:103], v[62:63], v[120:121], v[102:103]
	v_pk_fma_f32 v[108:109], v[50:51], v[120:121], v[108:109]
	v_pk_fma_f32 v[106:107], v[54:55], v[120:121], v[106:107]
	v_pk_fma_f32 v[112:113], v[56:57], v[120:121], v[112:113]
	v_pk_fma_f32 v[110:111], v[66:67], v[120:121], v[110:111]
	v_pk_fma_f32 v[116:117], v[64:65], v[120:121], v[116:117]
	v_pk_fma_f32 v[114:115], v[72:73], v[120:121], v[114:115]
	v_pk_fma_f32 v[120:121], v[68:69], v[120:121], v[34:35]
	v_lshlrev_b32_e32 v118, 16, v119
	v_and_b32_e32 v119, 0xffff0000, v119
	ds_read2st64_b32 v[246:247], v124 offset0:224 offset1:232
	s_waitcnt vmcnt(7)
; DI float bflo(unsigned w) { return __uint_as_float(w << 16); }
; DI float bfhi(unsigned w) { return __uint_as_float(w & 0xffff0000u); }
; template <int R> DI void conv_row(f32x2 (&acc)[32], const f32x2 (&wt)[31], const unsigned* tile, int tid) {
;   const unsigned x = tile[R * 512 + tid];
;   const f32x2 xv = {bflo(x), bfhi(x)};
; #pragma unroll
;   for (int i = 0; i < 32; ++i) { if (R - i >= 0 && R - i < 31) acc[i] = acc[i] + xv * wt[(R - i >= 0 && R - i < 31) ? R - i : 0]; }
;   if ((R & 7) == 7) asm volatile("" ::: "memory");
	v_pk_fma_f32 v[76:77], v[18:19], v[118:119], v[76:77]
	v_pk_fma_f32 v[74:75], v[12:13], v[118:119], v[74:75]
	v_pk_fma_f32 v[80:81], v[14:15], v[118:119], v[80:81]
	v_pk_fma_f32 v[78:79], v[16:17], v[118:119], v[78:79]
	v_pk_fma_f32 v[84:85], v[22:23], v[118:119], v[84:85]
	v_pk_fma_f32 v[82:83], v[20:21], v[118:119], v[82:83]
	v_pk_fma_f32 v[88:89], v[30:31], v[118:119], v[88:89]
	v_pk_fma_f32 v[86:87], v[26:27], v[118:119], v[86:87]
	v_pk_fma_f32 v[92:93], v[46:47], v[118:119], v[92:93]
	v_pk_fma_f32 v[90:91], v[24:25], v[118:119], v[90:91]
	v_pk_fma_f32 v[96:97], v[28:29], v[118:119], v[96:97]
	v_pk_fma_f32 v[94:95], v[44:45], v[118:119], v[94:95]
	v_pk_fma_f32 v[100:101], v[52:53], v[118:119], v[100:101]
	v_pk_fma_f32 v[98:99], v[48:49], v[118:119], v[98:99]
	v_pk_fma_f32 v[104:105], v[60:61], v[118:119], v[104:105]
	v_pk_fma_f32 v[102:103], v[58:59], v[118:119], v[102:103]
	v_pk_fma_f32 v[108:109], v[62:63], v[118:119], v[108:109]
	v_pk_fma_f32 v[106:107], v[50:51], v[118:119], v[106:107]
	v_pk_fma_f32 v[112:113], v[54:55], v[118:119], v[112:113]
	v_pk_fma_f32 v[110:111], v[56:57], v[118:119], v[110:111]
	v_pk_fma_f32 v[116:117], v[66:67], v[118:119], v[116:117]
	v_pk_fma_f32 v[114:115], v[64:65], v[118:119], v[114:115]
	v_pk_fma_f32 v[120:121], v[72:73], v[118:119], v[120:121]
	v_pk_fma_f32 v[118:119], v[68:69], v[118:119], v[34:35]
	s_waitcnt lgkmcnt(2)
	v_lshlrev_b32_e32 v240, 16, v122
	v_and_b32_e32 v241, 0xffff0000, v122
	s_waitcnt vmcnt(6)
	v_pk_fma_f32 v[76:77], v[10:11], v[240:241], v[76:77]
	v_pk_fma_f32 v[74:75], v[18:19], v[240:241], v[74:75]
	v_pk_fma_f32 v[80:81], v[12:13], v[240:241], v[80:81]
	v_pk_fma_f32 v[78:79], v[14:15], v[240:241], v[78:79]
	v_pk_fma_f32 v[84:85], v[16:17], v[240:241], v[84:85]
	v_pk_fma_f32 v[82:83], v[22:23], v[240:241], v[82:83]
	v_pk_fma_f32 v[88:89], v[20:21], v[240:241], v[88:89]
	v_pk_fma_f32 v[86:87], v[30:31], v[240:241], v[86:87]
	v_pk_fma_f32 v[92:93], v[26:27], v[240:241], v[92:93]
	v_pk_fma_f32 v[90:91], v[46:47], v[240:241], v[90:91]
	v_pk_fma_f32 v[96:97], v[24:25], v[240:241], v[96:97]
	v_pk_fma_f32 v[94:95], v[28:29], v[240:241], v[94:95]
	v_pk_fma_f32 v[100:101], v[44:45], v[240:241], v[100:101]
	v_pk_fma_f32 v[98:99], v[52:53], v[240:241], v[98:99]
	v_pk_fma_f32 v[104:105], v[48:49], v[240:241], v[104:105]
	v_pk_fma_f32 v[102:103], v[60:61], v[240:241], v[102:103]
	v_pk_fma_f32 v[108:109], v[58:59], v[240:241], v[108:109]
	v_pk_fma_f32 v[106:107], v[62:63], v[240:241], v[106:107]
	v_pk_fma_f32 v[112:113], v[50:51], v[240:241], v[112:113]
	v_pk_fma_f32 v[110:111], v[54:55], v[240:241], v[110:111]
	v_pk_fma_f32 v[116:117], v[56:57], v[240:241], v[116:117]
	v_pk_fma_f32 v[114:115], v[66:67], v[240:241], v[114:115]
	v_pk_fma_f32 v[120:121], v[64:65], v[240:241], v[120:121]
	v_pk_fma_f32 v[118:119], v[72:73], v[240:241], v[118:119]
	v_pk_fma_f32 v[240:241], v[68:69], v[240:241], v[34:35]
	v_lshlrev_b32_e32 v122, 16, v123
	v_and_b32_e32 v123, 0xffff0000, v123
	ds_read2st64_b32 v[250:251], v124 offset0:240 offset1:248
	s_waitcnt vmcnt(5)
	v_pk_fma_f32 v[76:77], v[8:9], v[122:123], v[76:77]
	v_pk_fma_f32 v[74:75], v[10:11], v[122:123], v[74:75]
	v_pk_fma_f32 v[80:81], v[18:19], v[122:123], v[80:81]
	v_pk_fma_f32 v[78:79], v[12:13], v[122:123], v[78:79]
	v_pk_fma_f32 v[84:85], v[14:15], v[122:123], v[84:85]
	v_pk_fma_f32 v[82:83], v[16:17], v[122:123], v[82:83]
	v_pk_fma_f32 v[88:89], v[22:23], v[122:123], v[88:89]
	v_pk_fma_f32 v[86:87], v[20:21], v[122:123], v[86:87]
	v_pk_fma_f32 v[92:93], v[30:31], v[122:123], v[92:93]
	v_pk_fma_f32 v[90:91], v[26:27], v[122:123], v[90:91]
	v_pk_fma_f32 v[96:97], v[46:47], v[122:123], v[96:97]
	v_pk_fma_f32 v[94:95], v[24:25], v[122:123], v[94:95]
	v_pk_fma_f32 v[100:101], v[28:29], v[122:123], v[100:101]
	v_pk_fma_f32 v[98:99], v[44:45], v[122:123], v[98:99]
	v_pk_fma_f32 v[104:105], v[52:53], v[122:123], v[104:105]
	v_pk_fma_f32 v[102:103], v[48:49], v[122:123], v[102:103]
	v_pk_fma_f32 v[108:109], v[60:61], v[122:123], v[108:109]
	v_pk_fma_f32 v[106:107], v[58:59], v[122:123], v[106:107]
	v_pk_fma_f32 v[112:113], v[62:63], v[122:123], v[112:113]
	v_pk_fma_f32 v[110:111], v[50:51], v[122:123], v[110:111]
	v_pk_fma_f32 v[116:117], v[54:55], v[122:123], v[116:117]
	v_pk_fma_f32 v[114:115], v[56:57], v[122:123], v[114:115]
	v_pk_fma_f32 v[120:121], v[66:67], v[122:123], v[120:121]
	v_pk_fma_f32 v[118:119], v[64:65], v[122:123], v[118:119]
	v_pk_fma_f32 v[240:241], v[72:73], v[122:123], v[240:241]
	v_pk_fma_f32 v[122:123], v[68:69], v[122:123], v[34:35]
	s_waitcnt lgkmcnt(2)
	v_lshlrev_b32_e32 v244, 16, v242
	v_and_b32_e32 v245, 0xffff0000, v242
	s_waitcnt vmcnt(4)
	v_pk_fma_f32 v[76:77], v[6:7], v[244:245], v[76:77]
	v_pk_fma_f32 v[74:75], v[8:9], v[244:245], v[74:75]
	v_pk_fma_f32 v[80:81], v[10:11], v[244:245], v[80:81]
	v_pk_fma_f32 v[78:79], v[18:19], v[244:245], v[78:79]
	v_pk_fma_f32 v[84:85], v[12:13], v[244:245], v[84:85]
	v_pk_fma_f32 v[82:83], v[14:15], v[244:245], v[82:83]
	v_pk_fma_f32 v[88:89], v[16:17], v[244:245], v[88:89]
	v_pk_fma_f32 v[86:87], v[22:23], v[244:245], v[86:87]
	v_pk_fma_f32 v[92:93], v[20:21], v[244:245], v[92:93]
	v_pk_fma_f32 v[90:91], v[30:31], v[244:245], v[90:91]
	v_pk_fma_f32 v[96:97], v[26:27], v[244:245], v[96:97]
	v_pk_fma_f32 v[94:95], v[46:47], v[244:245], v[94:95]
	v_pk_fma_f32 v[100:101], v[24:25], v[244:245], v[100:101]
	v_pk_fma_f32 v[98:99], v[28:29], v[244:245], v[98:99]
	v_pk_fma_f32 v[104:105], v[44:45], v[244:245], v[104:105]
	v_pk_fma_f32 v[102:103], v[52:53], v[244:245], v[102:103]
	v_pk_fma_f32 v[108:109], v[48:49], v[244:245], v[108:109]
	v_pk_fma_f32 v[106:107], v[60:61], v[244:245], v[106:107]
	v_pk_fma_f32 v[112:113], v[58:59], v[244:245], v[112:113]
	v_pk_fma_f32 v[110:111], v[62:63], v[244:245], v[110:111]
	v_pk_fma_f32 v[116:117], v[50:51], v[244:245], v[116:117]
	v_pk_fma_f32 v[114:115], v[54:55], v[244:245], v[114:115]
	v_pk_fma_f32 v[120:121], v[56:57], v[244:245], v[120:121]
	v_pk_fma_f32 v[118:119], v[66:67], v[244:245], v[118:119]
	v_pk_fma_f32 v[240:241], v[64:65], v[244:245], v[240:241]
	v_pk_fma_f32 v[122:123], v[72:73], v[244:245], v[122:123]
	v_pk_fma_f32 v[244:245], v[68:69], v[244:245], v[34:35]
	v_lshlrev_b32_e32 v242, 16, v243
	v_and_b32_e32 v243, 0xffff0000, v243
	s_waitcnt vmcnt(3)
; DI float bflo(unsigned w) { return __uint_as_float(w << 16); }
; DI float bfhi(unsigned w) { return __uint_as_float(w & 0xffff0000u); }
; template <int R> DI void conv_row(f32x2 (&acc)[32], const f32x2 (&wt)[31], const unsigned* tile, int tid) {
;   const unsigned x = tile[R * 512 + tid];
;   const f32x2 xv = {bflo(x), bfhi(x)};
; #pragma unroll
;   for (int i = 0; i < 32; ++i) { if (R - i >= 0 && R - i < 31) acc[i] = acc[i] + xv * wt[(R - i >= 0 && R - i < 31) ? R - i : 0]; }
;   if ((R & 7) == 7) asm volatile("" ::: "memory");
	v_pk_fma_f32 v[76:77], v[4:5], v[242:243], v[76:77]
	v_pk_fma_f32 v[74:75], v[6:7], v[242:243], v[74:75]
	v_pk_fma_f32 v[80:81], v[8:9], v[242:243], v[80:81]
	v_pk_fma_f32 v[78:79], v[10:11], v[242:243], v[78:79]
	v_pk_fma_f32 v[84:85], v[18:19], v[242:243], v[84:85]
	v_pk_fma_f32 v[82:83], v[12:13], v[242:243], v[82:83]
	v_pk_fma_f32 v[88:89], v[14:15], v[242:243], v[88:89]
	v_pk_fma_f32 v[86:87], v[16:17], v[242:243], v[86:87]
	v_pk_fma_f32 v[92:93], v[22:23], v[242:243], v[92:93]
	v_pk_fma_f32 v[90:91], v[20:21], v[242:243], v[90:91]
	v_pk_fma_f32 v[96:97], v[30:31], v[242:243], v[96:97]
	v_pk_fma_f32 v[94:95], v[26:27], v[242:243], v[94:95]
	v_pk_fma_f32 v[100:101], v[46:47], v[242:243], v[100:101]
	v_pk_fma_f32 v[98:99], v[24:25], v[242:243], v[98:99]
	v_pk_fma_f32 v[104:105], v[28:29], v[242:243], v[104:105]
	v_pk_fma_f32 v[102:103], v[44:45], v[242:243], v[102:103]
	v_pk_fma_f32 v[108:109], v[52:53], v[242:243], v[108:109]
	v_pk_fma_f32 v[106:107], v[48:49], v[242:243], v[106:107]
	v_pk_fma_f32 v[112:113], v[60:61], v[242:243], v[112:113]
	v_pk_fma_f32 v[110:111], v[58:59], v[242:243], v[110:111]
	v_pk_fma_f32 v[116:117], v[62:63], v[242:243], v[116:117]
	v_pk_fma_f32 v[114:115], v[50:51], v[242:243], v[114:115]
	v_pk_fma_f32 v[120:121], v[54:55], v[242:243], v[120:121]
	v_pk_fma_f32 v[118:119], v[56:57], v[242:243], v[118:119]
	v_pk_fma_f32 v[240:241], v[66:67], v[242:243], v[240:241]
	v_pk_fma_f32 v[122:123], v[64:65], v[242:243], v[122:123]
	v_pk_fma_f32 v[244:245], v[72:73], v[242:243], v[244:245]
	v_pk_fma_f32 v[242:243], v[68:69], v[242:243], v[34:35]
	s_waitcnt lgkmcnt(1)
	v_lshlrev_b32_e32 v248, 16, v246
	v_and_b32_e32 v249, 0xffff0000, v246
	s_waitcnt vmcnt(2)
	v_pk_fma_f32 v[76:77], v[2:3], v[248:249], v[76:77]
	v_pk_fma_f32 v[74:75], v[4:5], v[248:249], v[74:75]
	v_pk_fma_f32 v[80:81], v[6:7], v[248:249], v[80:81]
	v_pk_fma_f32 v[78:79], v[8:9], v[248:249], v[78:79]
	v_pk_fma_f32 v[84:85], v[10:11], v[248:249], v[84:85]
	v_pk_fma_f32 v[82:83], v[18:19], v[248:249], v[82:83]
	v_pk_fma_f32 v[88:89], v[12:13], v[248:249], v[88:89]
	v_pk_fma_f32 v[86:87], v[14:15], v[248:249], v[86:87]
	v_pk_fma_f32 v[92:93], v[16:17], v[248:249], v[92:93]
	v_pk_fma_f32 v[90:91], v[22:23], v[248:249], v[90:91]
	v_pk_fma_f32 v[96:97], v[20:21], v[248:249], v[96:97]
	v_pk_fma_f32 v[94:95], v[30:31], v[248:249], v[94:95]
	v_pk_fma_f32 v[100:101], v[26:27], v[248:249], v[100:101]
	v_pk_fma_f32 v[98:99], v[46:47], v[248:249], v[98:99]
	v_pk_fma_f32 v[104:105], v[24:25], v[248:249], v[104:105]
	v_pk_fma_f32 v[102:103], v[28:29], v[248:249], v[102:103]
	v_pk_fma_f32 v[108:109], v[44:45], v[248:249], v[108:109]
	v_pk_fma_f32 v[106:107], v[52:53], v[248:249], v[106:107]
	v_pk_fma_f32 v[112:113], v[48:49], v[248:249], v[112:113]
	v_pk_fma_f32 v[110:111], v[60:61], v[248:249], v[110:111]
	v_pk_fma_f32 v[116:117], v[58:59], v[248:249], v[116:117]
	v_pk_fma_f32 v[114:115], v[62:63], v[248:249], v[114:115]
	v_pk_fma_f32 v[120:121], v[50:51], v[248:249], v[120:121]
	v_pk_fma_f32 v[118:119], v[54:55], v[248:249], v[118:119]
	v_pk_fma_f32 v[240:241], v[56:57], v[248:249], v[240:241]
	v_pk_fma_f32 v[122:123], v[66:67], v[248:249], v[122:123]
	v_pk_fma_f32 v[244:245], v[64:65], v[248:249], v[244:245]
	v_pk_fma_f32 v[242:243], v[72:73], v[248:249], v[242:243]
	v_pk_fma_f32 v[248:249], v[68:69], v[248:249], v[34:35]
	v_lshlrev_b32_e32 v246, 16, v247
	v_and_b32_e32 v247, 0xffff0000, v247
	s_waitcnt vmcnt(1)
	v_pk_fma_f32 v[76:77], v[70:71], v[246:247], v[76:77]
	v_pk_fma_f32 v[74:75], v[2:3], v[246:247], v[74:75]
	v_pk_fma_f32 v[80:81], v[4:5], v[246:247], v[80:81]
	v_pk_fma_f32 v[78:79], v[6:7], v[246:247], v[78:79]
	v_pk_fma_f32 v[84:85], v[8:9], v[246:247], v[84:85]
	v_pk_fma_f32 v[82:83], v[10:11], v[246:247], v[82:83]
	v_pk_fma_f32 v[88:89], v[18:19], v[246:247], v[88:89]
	v_pk_fma_f32 v[86:87], v[12:13], v[246:247], v[86:87]
	v_pk_fma_f32 v[92:93], v[14:15], v[246:247], v[92:93]
	v_pk_fma_f32 v[90:91], v[16:17], v[246:247], v[90:91]
	v_pk_fma_f32 v[96:97], v[22:23], v[246:247], v[96:97]
	v_pk_fma_f32 v[94:95], v[20:21], v[246:247], v[94:95]
	v_pk_fma_f32 v[100:101], v[30:31], v[246:247], v[100:101]
	v_pk_fma_f32 v[98:99], v[26:27], v[246:247], v[98:99]
	v_pk_fma_f32 v[104:105], v[46:47], v[246:247], v[104:105]
	v_pk_fma_f32 v[102:103], v[24:25], v[246:247], v[102:103]
	v_pk_fma_f32 v[108:109], v[28:29], v[246:247], v[108:109]
	v_pk_fma_f32 v[106:107], v[44:45], v[246:247], v[106:107]
	v_pk_fma_f32 v[112:113], v[52:53], v[246:247], v[112:113]
	v_pk_fma_f32 v[110:111], v[48:49], v[246:247], v[110:111]
	v_pk_fma_f32 v[116:117], v[60:61], v[246:247], v[116:117]
	v_pk_fma_f32 v[114:115], v[58:59], v[246:247], v[114:115]
	v_pk_fma_f32 v[120:121], v[62:63], v[246:247], v[120:121]
	v_pk_fma_f32 v[118:119], v[50:51], v[246:247], v[118:119]
	v_pk_fma_f32 v[240:241], v[54:55], v[246:247], v[240:241]
	v_pk_fma_f32 v[122:123], v[56:57], v[246:247], v[122:123]
	v_pk_fma_f32 v[244:245], v[66:67], v[246:247], v[244:245]
	v_pk_fma_f32 v[242:243], v[64:65], v[246:247], v[242:243]
	v_pk_fma_f32 v[248:249], v[72:73], v[246:247], v[248:249]
	v_pk_fma_f32 v[246:247], v[68:69], v[246:247], v[34:35]
	s_waitcnt lgkmcnt(0)
	v_lshlrev_b32_e32 v252, 16, v250
	v_and_b32_e32 v253, 0xffff0000, v250
	s_waitcnt vmcnt(0)
; DI float bflo(unsigned w) { return __uint_as_float(w << 16); }
; DI float bfhi(unsigned w) { return __uint_as_float(w & 0xffff0000u); }
; template <int R> DI void conv_row(f32x2 (&acc)[32], const f32x2 (&wt)[31], const unsigned* tile, int tid) {
;   const unsigned x = tile[R * 512 + tid];
;   const f32x2 xv = {bflo(x), bfhi(x)};
; #pragma unroll
;   for (int i = 0; i < 32; ++i) { if (R - i >= 0 && R - i < 31) acc[i] = acc[i] + xv * wt[(R - i >= 0 && R - i < 31) ? R - i : 0]; }
;   if ((R & 7) == 7) asm volatile("" ::: "memory");
	v_pk_fma_f32 v[76:77], v[0:1], v[252:253], v[76:77]
	v_pk_fma_f32 v[74:75], v[70:71], v[252:253], v[74:75]
	v_pk_fma_f32 v[80:81], v[2:3], v[252:253], v[80:81]
	v_pk_fma_f32 v[78:79], v[4:5], v[252:253], v[78:79]
	v_pk_fma_f32 v[84:85], v[6:7], v[252:253], v[84:85]
	v_pk_fma_f32 v[82:83], v[8:9], v[252:253], v[82:83]
	v_pk_fma_f32 v[88:89], v[10:11], v[252:253], v[88:89]
	v_pk_fma_f32 v[86:87], v[18:19], v[252:253], v[86:87]
	v_pk_fma_f32 v[92:93], v[12:13], v[252:253], v[92:93]
	v_pk_fma_f32 v[90:91], v[14:15], v[252:253], v[90:91]
	v_pk_fma_f32 v[96:97], v[16:17], v[252:253], v[96:97]
	v_pk_fma_f32 v[94:95], v[22:23], v[252:253], v[94:95]
	v_pk_fma_f32 v[100:101], v[20:21], v[252:253], v[100:101]
	v_pk_fma_f32 v[98:99], v[30:31], v[252:253], v[98:99]
	v_pk_fma_f32 v[104:105], v[26:27], v[252:253], v[104:105]
	v_pk_fma_f32 v[102:103], v[46:47], v[252:253], v[102:103]
	v_pk_fma_f32 v[108:109], v[24:25], v[252:253], v[108:109]
	v_pk_fma_f32 v[106:107], v[28:29], v[252:253], v[106:107]
	v_pk_fma_f32 v[112:113], v[44:45], v[252:253], v[112:113]
	v_pk_fma_f32 v[110:111], v[52:53], v[252:253], v[110:111]
	v_pk_fma_f32 v[116:117], v[48:49], v[252:253], v[116:117]
	v_pk_fma_f32 v[114:115], v[60:61], v[252:253], v[114:115]
	v_pk_fma_f32 v[120:121], v[58:59], v[252:253], v[120:121]
	v_pk_fma_f32 v[118:119], v[62:63], v[252:253], v[118:119]
	v_pk_fma_f32 v[240:241], v[50:51], v[252:253], v[240:241]
	v_pk_fma_f32 v[122:123], v[54:55], v[252:253], v[122:123]
	v_pk_fma_f32 v[244:245], v[56:57], v[252:253], v[244:245]
	v_pk_fma_f32 v[242:243], v[66:67], v[252:253], v[242:243]
	v_pk_fma_f32 v[248:249], v[64:65], v[252:253], v[248:249]
	v_pk_fma_f32 v[246:247], v[72:73], v[252:253], v[246:247]
	v_pk_fma_f32 v[252:253], v[68:69], v[252:253], v[34:35]
	v_lshlrev_b32_e32 v250, 16, v251
	v_and_b32_e32 v251, 0xffff0000, v251
	v_pk_fma_f32 v[74:75], v[0:1], v[250:251], v[74:75]
	v_pk_fma_f32 v[80:81], v[70:71], v[250:251], v[80:81]
	v_pk_fma_f32 v[78:79], v[2:3], v[250:251], v[78:79]
	v_pk_fma_f32 v[84:85], v[4:5], v[250:251], v[84:85]
	v_pk_fma_f32 v[82:83], v[6:7], v[250:251], v[82:83]
	v_pk_fma_f32 v[88:89], v[8:9], v[250:251], v[88:89]
	v_pk_fma_f32 v[86:87], v[10:11], v[250:251], v[86:87]
	v_pk_fma_f32 v[92:93], v[18:19], v[250:251], v[92:93]
	v_pk_fma_f32 v[90:91], v[12:13], v[250:251], v[90:91]
	v_pk_fma_f32 v[96:97], v[14:15], v[250:251], v[96:97]
	v_pk_fma_f32 v[94:95], v[16:17], v[250:251], v[94:95]
	v_pk_fma_f32 v[100:101], v[22:23], v[250:251], v[100:101]
	v_pk_fma_f32 v[98:99], v[20:21], v[250:251], v[98:99]
	v_pk_fma_f32 v[104:105], v[30:31], v[250:251], v[104:105]
	v_pk_fma_f32 v[102:103], v[26:27], v[250:251], v[102:103]
	v_pk_fma_f32 v[108:109], v[46:47], v[250:251], v[108:109]
	v_pk_fma_f32 v[106:107], v[24:25], v[250:251], v[106:107]
	v_pk_fma_f32 v[112:113], v[28:29], v[250:251], v[112:113]
	v_pk_fma_f32 v[110:111], v[44:45], v[250:251], v[110:111]
	v_pk_fma_f32 v[116:117], v[52:53], v[250:251], v[116:117]
	v_pk_fma_f32 v[114:115], v[48:49], v[250:251], v[114:115]
	v_pk_fma_f32 v[120:121], v[60:61], v[250:251], v[120:121]
	v_pk_fma_f32 v[118:119], v[58:59], v[250:251], v[118:119]
	v_pk_fma_f32 v[240:241], v[62:63], v[250:251], v[240:241]
	v_pk_fma_f32 v[122:123], v[50:51], v[250:251], v[122:123]
	v_pk_fma_f32 v[244:245], v[54:55], v[250:251], v[244:245]
	v_pk_fma_f32 v[242:243], v[56:57], v[250:251], v[242:243]
	v_pk_fma_f32 v[248:249], v[66:67], v[250:251], v[248:249]
	v_pk_fma_f32 v[246:247], v[64:65], v[250:251], v[246:247]
	v_pk_fma_f32 v[252:253], v[72:73], v[250:251], v[252:253]
	v_pk_fma_f32 v[250:251], v[68:69], v[250:251], v[34:35]
	v_add_u32_e32 v68, 0x10000, v124
	ds_read_b32 v68, v68
	v_cmp_lt_i32_e32 vcc, v209, v208
	s_waitcnt lgkmcnt(0)
	v_lshlrev_b32_e32 v212, 16, v68
	v_and_b32_e32 v213, 0xffff0000, v68
	v_pk_fma_f32 v[68:69], v[0:1], v[212:213], v[80:81]
	v_pk_fma_f32 v[78:79], v[70:71], v[212:213], v[78:79]
	v_pk_fma_f32 v[80:81], v[2:3], v[212:213], v[84:85]
	v_pk_fma_f32 v[82:83], v[4:5], v[212:213], v[82:83]
	v_pk_fma_f32 v[84:85], v[6:7], v[212:213], v[88:89]
	v_pk_fma_f32 v[86:87], v[8:9], v[212:213], v[86:87]
	v_pk_fma_f32 v[88:89], v[10:11], v[212:213], v[92:93]
	v_pk_fma_f32 v[90:91], v[18:19], v[212:213], v[90:91]
	v_pk_fma_f32 v[92:93], v[12:13], v[212:213], v[96:97]
	v_pk_fma_f32 v[94:95], v[14:15], v[212:213], v[94:95]
	v_pk_fma_f32 v[96:97], v[16:17], v[212:213], v[100:101]
	v_pk_fma_f32 v[98:99], v[22:23], v[212:213], v[98:99]
	v_pk_fma_f32 v[100:101], v[20:21], v[212:213], v[104:105]
	v_pk_fma_f32 v[102:103], v[30:31], v[212:213], v[102:103]
	v_pk_fma_f32 v[104:105], v[26:27], v[212:213], v[108:109]
	v_pk_fma_f32 v[106:107], v[46:47], v[212:213], v[106:107]
	v_pk_fma_f32 v[108:109], v[24:25], v[212:213], v[112:113]
	v_pk_fma_f32 v[110:111], v[28:29], v[212:213], v[110:111]
	v_pk_fma_f32 v[112:113], v[44:45], v[212:213], v[116:117]
	v_pk_fma_f32 v[114:115], v[52:53], v[212:213], v[114:115]
	v_pk_fma_f32 v[116:117], v[48:49], v[212:213], v[120:121]
	v_pk_fma_f32 v[118:119], v[60:61], v[212:213], v[118:119]
	v_pk_fma_f32 v[120:121], v[58:59], v[212:213], v[240:241]
	v_pk_fma_f32 v[122:123], v[62:63], v[212:213], v[122:123]
	v_pk_fma_f32 v[240:241], v[50:51], v[212:213], v[244:245]
	v_pk_fma_f32 v[242:243], v[54:55], v[212:213], v[242:243]
	v_pk_fma_f32 v[244:245], v[56:57], v[212:213], v[248:249]
	v_pk_fma_f32 v[246:247], v[66:67], v[212:213], v[246:247]
	v_pk_fma_f32 v[248:249], v[64:65], v[212:213], v[252:253]
	v_pk_fma_f32 v[212:213], v[72:73], v[212:213], v[250:251]
	ds_read_b32 v72, v125
	s_waitcnt lgkmcnt(0)
; DI float bflo(unsigned w) { return __uint_as_float(w << 16); }
; DI float bfhi(unsigned w) { return __uint_as_float(w & 0xffff0000u); }
; template <int R> DI void conv_row(f32x2 (&acc)[32], const f32x2 (&wt)[31], const unsigned* tile, int tid) {
;   const unsigned x = tile[R * 512 + tid];
;   const f32x2 xv = {bflo(x), bfhi(x)};
; #pragma unroll
;   for (int i = 0; i < 32; ++i) { if (R - i >= 0 && R - i < 31) acc[i] = acc[i] + xv * wt[(R - i >= 0 && R - i < 31) ? R - i : 0]; }
;   if ((R & 7) == 7) asm volatile("" ::: "memory");
	v_lshlrev_b32_e32 v250, 16, v72
	v_and_b32_e32 v251, 0xffff0000, v72
	v_pk_fma_f32 v[212:213], v[64:65], v[250:251], v[212:213]
	ds_read_b32 v64, v126
	v_pk_fma_f32 v[72:73], v[0:1], v[250:251], v[78:79]
	v_pk_fma_f32 v[78:79], v[70:71], v[250:251], v[80:81]
	v_pk_fma_f32 v[80:81], v[2:3], v[250:251], v[82:83]
	v_pk_fma_f32 v[82:83], v[4:5], v[250:251], v[84:85]
	v_pk_fma_f32 v[84:85], v[6:7], v[250:251], v[86:87]
	v_pk_fma_f32 v[86:87], v[8:9], v[250:251], v[88:89]
	v_pk_fma_f32 v[88:89], v[10:11], v[250:251], v[90:91]
	v_pk_fma_f32 v[90:91], v[18:19], v[250:251], v[92:93]
	v_pk_fma_f32 v[92:93], v[12:13], v[250:251], v[94:95]
	v_pk_fma_f32 v[94:95], v[14:15], v[250:251], v[96:97]
	v_pk_fma_f32 v[96:97], v[16:17], v[250:251], v[98:99]
	v_pk_fma_f32 v[98:99], v[22:23], v[250:251], v[100:101]
	v_pk_fma_f32 v[100:101], v[20:21], v[250:251], v[102:103]
	v_pk_fma_f32 v[102:103], v[30:31], v[250:251], v[104:105]
	v_pk_fma_f32 v[104:105], v[26:27], v[250:251], v[106:107]
	v_pk_fma_f32 v[106:107], v[46:47], v[250:251], v[108:109]
	v_pk_fma_f32 v[108:109], v[24:25], v[250:251], v[110:111]
	v_pk_fma_f32 v[110:111], v[28:29], v[250:251], v[112:113]
	v_pk_fma_f32 v[112:113], v[44:45], v[250:251], v[114:115]
	v_pk_fma_f32 v[114:115], v[52:53], v[250:251], v[116:117]
	v_pk_fma_f32 v[116:117], v[48:49], v[250:251], v[118:119]
	v_pk_fma_f32 v[118:119], v[60:61], v[250:251], v[120:121]
	v_pk_fma_f32 v[120:121], v[58:59], v[250:251], v[122:123]
	v_pk_fma_f32 v[122:123], v[62:63], v[250:251], v[240:241]
	v_pk_fma_f32 v[240:241], v[50:51], v[250:251], v[242:243]
	v_pk_fma_f32 v[242:243], v[54:55], v[250:251], v[244:245]
	v_pk_fma_f32 v[244:245], v[56:57], v[250:251], v[246:247]
	v_pk_fma_f32 v[246:247], v[66:67], v[250:251], v[248:249]
	s_waitcnt lgkmcnt(0)
	v_lshlrev_b32_e32 v248, 16, v64
	v_and_b32_e32 v249, 0xffff0000, v64
	v_pk_fma_f32 v[212:213], v[66:67], v[248:249], v[212:213]
	ds_read_b32 v66, v127
	v_pk_fma_f32 v[64:65], v[0:1], v[248:249], v[78:79]
	v_pk_fma_f32 v[78:79], v[70:71], v[248:249], v[80:81]
	v_pk_fma_f32 v[80:81], v[2:3], v[248:249], v[82:83]
	v_pk_fma_f32 v[82:83], v[4:5], v[248:249], v[84:85]
	v_pk_fma_f32 v[84:85], v[6:7], v[248:249], v[86:87]
	v_pk_fma_f32 v[86:87], v[8:9], v[248:249], v[88:89]
	v_pk_fma_f32 v[88:89], v[10:11], v[248:249], v[90:91]
	v_pk_fma_f32 v[90:91], v[18:19], v[248:249], v[92:93]
	v_pk_fma_f32 v[92:93], v[12:13], v[248:249], v[94:95]
	v_pk_fma_f32 v[94:95], v[14:15], v[248:249], v[96:97]
	v_pk_fma_f32 v[96:97], v[16:17], v[248:249], v[98:99]
	v_pk_fma_f32 v[98:99], v[22:23], v[248:249], v[100:101]
	v_pk_fma_f32 v[100:101], v[20:21], v[248:249], v[102:103]
	v_pk_fma_f32 v[102:103], v[30:31], v[248:249], v[104:105]
	v_pk_fma_f32 v[104:105], v[26:27], v[248:249], v[106:107]
	v_pk_fma_f32 v[106:107], v[46:47], v[248:249], v[108:109]
	v_pk_fma_f32 v[108:109], v[24:25], v[248:249], v[110:111]
	v_pk_fma_f32 v[110:111], v[28:29], v[248:249], v[112:113]
	v_pk_fma_f32 v[112:113], v[44:45], v[248:249], v[114:115]
	v_pk_fma_f32 v[114:115], v[52:53], v[248:249], v[116:117]
	v_pk_fma_f32 v[116:117], v[48:49], v[248:249], v[118:119]
	v_pk_fma_f32 v[118:119], v[60:61], v[248:249], v[120:121]
	v_pk_fma_f32 v[120:121], v[58:59], v[248:249], v[122:123]
	v_pk_fma_f32 v[122:123], v[62:63], v[248:249], v[240:241]
	v_pk_fma_f32 v[240:241], v[50:51], v[248:249], v[242:243]
	v_pk_fma_f32 v[242:243], v[54:55], v[248:249], v[244:245]
	v_pk_fma_f32 v[244:245], v[56:57], v[248:249], v[246:247]
	s_waitcnt lgkmcnt(0)
	v_lshlrev_b32_e32 v246, 16, v66
	v_and_b32_e32 v247, 0xffff0000, v66
	v_pk_fma_f32 v[212:213], v[56:57], v[246:247], v[212:213]
	ds_read_b32 v56, v128
	v_pk_fma_f32 v[66:67], v[0:1], v[246:247], v[78:79]
	v_pk_fma_f32 v[78:79], v[70:71], v[246:247], v[80:81]
	v_pk_fma_f32 v[80:81], v[2:3], v[246:247], v[82:83]
	v_pk_fma_f32 v[82:83], v[4:5], v[246:247], v[84:85]
	v_pk_fma_f32 v[84:85], v[6:7], v[246:247], v[86:87]
	v_pk_fma_f32 v[86:87], v[8:9], v[246:247], v[88:89]
	v_pk_fma_f32 v[88:89], v[10:11], v[246:247], v[90:91]
	v_pk_fma_f32 v[90:91], v[18:19], v[246:247], v[92:93]
	v_pk_fma_f32 v[92:93], v[12:13], v[246:247], v[94:95]
	v_pk_fma_f32 v[94:95], v[14:15], v[246:247], v[96:97]
	v_pk_fma_f32 v[96:97], v[16:17], v[246:247], v[98:99]
	v_pk_fma_f32 v[98:99], v[22:23], v[246:247], v[100:101]
	v_pk_fma_f32 v[100:101], v[20:21], v[246:247], v[102:103]
	v_pk_fma_f32 v[102:103], v[30:31], v[246:247], v[104:105]
	v_pk_fma_f32 v[104:105], v[26:27], v[246:247], v[106:107]
	v_pk_fma_f32 v[106:107], v[46:47], v[246:247], v[108:109]
	v_pk_fma_f32 v[108:109], v[24:25], v[246:247], v[110:111]
	v_pk_fma_f32 v[110:111], v[28:29], v[246:247], v[112:113]
	v_pk_fma_f32 v[112:113], v[44:45], v[246:247], v[114:115]
	v_pk_fma_f32 v[114:115], v[52:53], v[246:247], v[116:117]
	v_pk_fma_f32 v[116:117], v[48:49], v[246:247], v[118:119]
	v_pk_fma_f32 v[118:119], v[60:61], v[246:247], v[120:121]
	v_pk_fma_f32 v[120:121], v[58:59], v[246:247], v[122:123]
	v_pk_fma_f32 v[122:123], v[62:63], v[246:247], v[240:241]
	v_pk_fma_f32 v[240:241], v[50:51], v[246:247], v[242:243]
	v_pk_fma_f32 v[242:243], v[54:55], v[246:247], v[244:245]
	s_waitcnt lgkmcnt(0)
; DI float bflo(unsigned w) { return __uint_as_float(w << 16); }
; DI float bfhi(unsigned w) { return __uint_as_float(w & 0xffff0000u); }
; template <int R> DI void conv_row(f32x2 (&acc)[32], const f32x2 (&wt)[31], const unsigned* tile, int tid) {
;   const unsigned x = tile[R * 512 + tid];
;   const f32x2 xv = {bflo(x), bfhi(x)};
; #pragma unroll
;   for (int i = 0; i < 32; ++i) { if (R - i >= 0 && R - i < 31) acc[i] = acc[i] + xv * wt[(R - i >= 0 && R - i < 31) ? R - i : 0]; }
;   if ((R & 7) == 7) asm volatile("" ::: "memory");
	v_lshlrev_b32_e32 v244, 16, v56
	v_and_b32_e32 v245, 0xffff0000, v56
	v_pk_fma_f32 v[212:213], v[54:55], v[244:245], v[212:213]
	ds_read_b32 v54, v129
	v_pk_fma_f32 v[56:57], v[0:1], v[244:245], v[78:79]
	v_pk_fma_f32 v[78:79], v[70:71], v[244:245], v[80:81]
	v_pk_fma_f32 v[80:81], v[2:3], v[244:245], v[82:83]
	v_pk_fma_f32 v[82:83], v[4:5], v[244:245], v[84:85]
	v_pk_fma_f32 v[84:85], v[6:7], v[244:245], v[86:87]
	v_pk_fma_f32 v[86:87], v[8:9], v[244:245], v[88:89]
	v_pk_fma_f32 v[88:89], v[10:11], v[244:245], v[90:91]
	v_pk_fma_f32 v[90:91], v[18:19], v[244:245], v[92:93]
	v_pk_fma_f32 v[92:93], v[12:13], v[244:245], v[94:95]
	v_pk_fma_f32 v[94:95], v[14:15], v[244:245], v[96:97]
	v_pk_fma_f32 v[96:97], v[16:17], v[244:245], v[98:99]
	v_pk_fma_f32 v[98:99], v[22:23], v[244:245], v[100:101]
	v_pk_fma_f32 v[100:101], v[20:21], v[244:245], v[102:103]
	v_pk_fma_f32 v[102:103], v[30:31], v[244:245], v[104:105]
	v_pk_fma_f32 v[104:105], v[26:27], v[244:245], v[106:107]
	v_pk_fma_f32 v[106:107], v[46:47], v[244:245], v[108:109]
	v_pk_fma_f32 v[108:109], v[24:25], v[244:245], v[110:111]
	v_pk_fma_f32 v[110:111], v[28:29], v[244:245], v[112:113]
	v_pk_fma_f32 v[112:113], v[44:45], v[244:245], v[114:115]
	v_pk_fma_f32 v[114:115], v[52:53], v[244:245], v[116:117]
	v_pk_fma_f32 v[116:117], v[48:49], v[244:245], v[118:119]
	v_pk_fma_f32 v[118:119], v[60:61], v[244:245], v[120:121]
	v_pk_fma_f32 v[120:121], v[58:59], v[244:245], v[122:123]
	v_pk_fma_f32 v[122:123], v[62:63], v[244:245], v[240:241]
	v_pk_fma_f32 v[240:241], v[50:51], v[244:245], v[242:243]
	s_waitcnt lgkmcnt(0)
	v_lshlrev_b32_e32 v242, 16, v54
	v_and_b32_e32 v243, 0xffff0000, v54
	v_pk_fma_f32 v[212:213], v[50:51], v[242:243], v[212:213]
	ds_read_b32 v50, v130
	v_pk_fma_f32 v[54:55], v[0:1], v[242:243], v[78:79]
	v_pk_fma_f32 v[78:79], v[70:71], v[242:243], v[80:81]
	v_pk_fma_f32 v[80:81], v[2:3], v[242:243], v[82:83]
	v_pk_fma_f32 v[82:83], v[4:5], v[242:243], v[84:85]
	v_pk_fma_f32 v[84:85], v[6:7], v[242:243], v[86:87]
	v_pk_fma_f32 v[86:87], v[8:9], v[242:243], v[88:89]
	v_pk_fma_f32 v[88:89], v[10:11], v[242:243], v[90:91]
	v_pk_fma_f32 v[90:91], v[18:19], v[242:243], v[92:93]
	v_pk_fma_f32 v[92:93], v[12:13], v[242:243], v[94:95]
	v_pk_fma_f32 v[94:95], v[14:15], v[242:243], v[96:97]
	v_pk_fma_f32 v[96:97], v[16:17], v[242:243], v[98:99]
	v_pk_fma_f32 v[98:99], v[22:23], v[242:243], v[100:101]
	v_pk_fma_f32 v[100:101], v[20:21], v[242:243], v[102:103]
	v_pk_fma_f32 v[102:103], v[30:31], v[242:243], v[104:105]
	v_pk_fma_f32 v[104:105], v[26:27], v[242:243], v[106:107]
	v_pk_fma_f32 v[106:107], v[46:47], v[242:243], v[108:109]
	v_pk_fma_f32 v[108:109], v[24:25], v[242:243], v[110:111]
	v_pk_fma_f32 v[110:111], v[28:29], v[242:243], v[112:113]
	v_pk_fma_f32 v[112:113], v[44:45], v[242:243], v[114:115]
	v_pk_fma_f32 v[114:115], v[52:53], v[242:243], v[116:117]
	v_pk_fma_f32 v[116:117], v[48:49], v[242:243], v[118:119]
	v_pk_fma_f32 v[118:119], v[60:61], v[242:243], v[120:121]
	v_pk_fma_f32 v[120:121], v[58:59], v[242:243], v[122:123]
	v_pk_fma_f32 v[122:123], v[62:63], v[242:243], v[240:241]
	s_waitcnt lgkmcnt(0)
	v_lshlrev_b32_e32 v240, 16, v50
	v_and_b32_e32 v241, 0xffff0000, v50
	v_pk_fma_f32 v[50:51], v[0:1], v[240:241], v[78:79]
	v_pk_fma_f32 v[78:79], v[70:71], v[240:241], v[80:81]
	v_pk_fma_f32 v[80:81], v[2:3], v[240:241], v[82:83]
	v_pk_fma_f32 v[82:83], v[4:5], v[240:241], v[84:85]
	v_pk_fma_f32 v[84:85], v[6:7], v[240:241], v[86:87]
	v_pk_fma_f32 v[86:87], v[8:9], v[240:241], v[88:89]
	v_pk_fma_f32 v[88:89], v[10:11], v[240:241], v[90:91]
	v_pk_fma_f32 v[90:91], v[18:19], v[240:241], v[92:93]
	v_pk_fma_f32 v[92:93], v[12:13], v[240:241], v[94:95]
	v_pk_fma_f32 v[94:95], v[14:15], v[240:241], v[96:97]
	v_pk_fma_f32 v[96:97], v[16:17], v[240:241], v[98:99]
	v_pk_fma_f32 v[98:99], v[22:23], v[240:241], v[100:101]
	v_pk_fma_f32 v[100:101], v[20:21], v[240:241], v[102:103]
	v_pk_fma_f32 v[102:103], v[30:31], v[240:241], v[104:105]
	v_pk_fma_f32 v[104:105], v[26:27], v[240:241], v[106:107]
	v_pk_fma_f32 v[106:107], v[46:47], v[240:241], v[108:109]
	v_pk_fma_f32 v[108:109], v[24:25], v[240:241], v[110:111]
	v_pk_fma_f32 v[110:111], v[28:29], v[240:241], v[112:113]
	v_pk_fma_f32 v[112:113], v[44:45], v[240:241], v[114:115]
	v_pk_fma_f32 v[114:115], v[52:53], v[240:241], v[116:117]
	v_pk_fma_f32 v[116:117], v[48:49], v[240:241], v[118:119]
	v_pk_fma_f32 v[118:119], v[60:61], v[240:241], v[120:121]
	v_pk_fma_f32 v[120:121], v[58:59], v[240:241], v[122:123]
	v_pk_fma_f32 v[122:123], v[62:63], v[240:241], v[212:213]
	ds_read_b32 v62, v131
	s_waitcnt lgkmcnt(0)
	v_lshlrev_b32_e32 v212, 16, v62
	v_and_b32_e32 v213, 0xffff0000, v62
	v_pk_fma_f32 v[62:63], v[0:1], v[212:213], v[78:79]
	v_pk_fma_f32 v[78:79], v[70:71], v[212:213], v[80:81]
	v_pk_fma_f32 v[80:81], v[2:3], v[212:213], v[82:83]
	v_pk_fma_f32 v[82:83], v[4:5], v[212:213], v[84:85]
	v_pk_fma_f32 v[84:85], v[6:7], v[212:213], v[86:87]
	v_pk_fma_f32 v[86:87], v[8:9], v[212:213], v[88:89]
	v_pk_fma_f32 v[88:89], v[10:11], v[212:213], v[90:91]
	v_pk_fma_f32 v[90:91], v[18:19], v[212:213], v[92:93]
	v_pk_fma_f32 v[92:93], v[12:13], v[212:213], v[94:95]
	v_pk_fma_f32 v[94:95], v[14:15], v[212:213], v[96:97]
	v_pk_fma_f32 v[96:97], v[16:17], v[212:213], v[98:99]
	v_pk_fma_f32 v[98:99], v[22:23], v[212:213], v[100:101]
	v_pk_fma_f32 v[100:101], v[20:21], v[212:213], v[102:103]
	v_pk_fma_f32 v[102:103], v[30:31], v[212:213], v[104:105]
	v_pk_fma_f32 v[104:105], v[26:27], v[212:213], v[106:107]
	v_pk_fma_f32 v[106:107], v[46:47], v[212:213], v[108:109]
	v_pk_fma_f32 v[108:109], v[24:25], v[212:213], v[110:111]
	v_pk_fma_f32 v[110:111], v[28:29], v[212:213], v[112:113]
	v_pk_fma_f32 v[112:113], v[44:45], v[212:213], v[114:115]
	v_pk_fma_f32 v[114:115], v[52:53], v[212:213], v[116:117]
	v_pk_fma_f32 v[116:117], v[48:49], v[212:213], v[118:119]
	v_pk_fma_f32 v[118:119], v[60:61], v[212:213], v[120:121]
	v_pk_fma_f32 v[120:121], v[58:59], v[212:213], v[122:123]
	ds_read_b32 v58, v132
	s_waitcnt lgkmcnt(0)
; DI float bflo(unsigned w) { return __uint_as_float(w << 16); }
; DI float bfhi(unsigned w) { return __uint_as_float(w & 0xffff0000u); }
; template <int R> DI void conv_row(f32x2 (&acc)[32], const f32x2 (&wt)[31], const unsigned* tile, int tid) {
;   const unsigned x = tile[R * 512 + tid];
;   const f32x2 xv = {bflo(x), bfhi(x)};
; #pragma unroll
;   for (int i = 0; i < 32; ++i) { if (R - i >= 0 && R - i < 31) acc[i] = acc[i] + xv * wt[(R - i >= 0 && R - i < 31) ? R - i : 0]; }
;   if ((R & 7) == 7) asm volatile("" ::: "memory");
	v_lshlrev_b32_e32 v122, 16, v58
	v_and_b32_e32 v123, 0xffff0000, v58
	v_pk_fma_f32 v[58:59], v[0:1], v[122:123], v[78:79]
	v_pk_fma_f32 v[78:79], v[70:71], v[122:123], v[80:81]
	v_pk_fma_f32 v[80:81], v[2:3], v[122:123], v[82:83]
	v_pk_fma_f32 v[82:83], v[4:5], v[122:123], v[84:85]
	v_pk_fma_f32 v[84:85], v[6:7], v[122:123], v[86:87]
	v_pk_fma_f32 v[86:87], v[8:9], v[122:123], v[88:89]
	v_pk_fma_f32 v[88:89], v[10:11], v[122:123], v[90:91]
	v_pk_fma_f32 v[90:91], v[18:19], v[122:123], v[92:93]
	v_pk_fma_f32 v[92:93], v[12:13], v[122:123], v[94:95]
	v_pk_fma_f32 v[94:95], v[14:15], v[122:123], v[96:97]
	v_pk_fma_f32 v[96:97], v[16:17], v[122:123], v[98:99]
	v_pk_fma_f32 v[98:99], v[22:23], v[122:123], v[100:101]
	v_pk_fma_f32 v[100:101], v[20:21], v[122:123], v[102:103]
	v_pk_fma_f32 v[102:103], v[30:31], v[122:123], v[104:105]
	v_pk_fma_f32 v[104:105], v[26:27], v[122:123], v[106:107]
	v_pk_fma_f32 v[106:107], v[46:47], v[122:123], v[108:109]
	v_pk_fma_f32 v[108:109], v[24:25], v[122:123], v[110:111]
	v_pk_fma_f32 v[110:111], v[28:29], v[122:123], v[112:113]
	v_pk_fma_f32 v[112:113], v[44:45], v[122:123], v[114:115]
	v_pk_fma_f32 v[114:115], v[52:53], v[122:123], v[116:117]
	v_pk_fma_f32 v[116:117], v[48:49], v[122:123], v[118:119]
	v_pk_fma_f32 v[118:119], v[60:61], v[122:123], v[120:121]
	ds_read_b32 v60, v133
	s_waitcnt lgkmcnt(0)
	v_lshlrev_b32_e32 v120, 16, v60
	v_and_b32_e32 v121, 0xffff0000, v60
	v_pk_fma_f32 v[60:61], v[0:1], v[120:121], v[78:79]
	v_pk_fma_f32 v[78:79], v[70:71], v[120:121], v[80:81]
	v_pk_fma_f32 v[80:81], v[2:3], v[120:121], v[82:83]
	v_pk_fma_f32 v[82:83], v[4:5], v[120:121], v[84:85]
	v_pk_fma_f32 v[84:85], v[6:7], v[120:121], v[86:87]
	v_pk_fma_f32 v[86:87], v[8:9], v[120:121], v[88:89]
	v_pk_fma_f32 v[88:89], v[10:11], v[120:121], v[90:91]
	v_pk_fma_f32 v[90:91], v[18:19], v[120:121], v[92:93]
	v_pk_fma_f32 v[92:93], v[12:13], v[120:121], v[94:95]
	v_pk_fma_f32 v[94:95], v[14:15], v[120:121], v[96:97]
	v_pk_fma_f32 v[96:97], v[16:17], v[120:121], v[98:99]
	v_pk_fma_f32 v[98:99], v[22:23], v[120:121], v[100:101]
	v_pk_fma_f32 v[100:101], v[20:21], v[120:121], v[102:103]
	v_pk_fma_f32 v[102:103], v[30:31], v[120:121], v[104:105]
	v_pk_fma_f32 v[104:105], v[26:27], v[120:121], v[106:107]
	v_pk_fma_f32 v[106:107], v[46:47], v[120:121], v[108:109]
	v_pk_fma_f32 v[108:109], v[24:25], v[120:121], v[110:111]
	v_pk_fma_f32 v[110:111], v[28:29], v[120:121], v[112:113]
	v_pk_fma_f32 v[112:113], v[44:45], v[120:121], v[114:115]
	v_pk_fma_f32 v[114:115], v[52:53], v[120:121], v[116:117]
	v_pk_fma_f32 v[116:117], v[48:49], v[120:121], v[118:119]
	ds_read_b32 v48, v134
	s_waitcnt lgkmcnt(0)
	v_lshlrev_b32_e32 v118, 16, v48
	v_and_b32_e32 v119, 0xffff0000, v48
	v_pk_fma_f32 v[48:49], v[0:1], v[118:119], v[78:79]
	v_pk_fma_f32 v[78:79], v[70:71], v[118:119], v[80:81]
	v_pk_fma_f32 v[80:81], v[2:3], v[118:119], v[82:83]
	v_pk_fma_f32 v[82:83], v[4:5], v[118:119], v[84:85]
	v_pk_fma_f32 v[84:85], v[6:7], v[118:119], v[86:87]
	v_pk_fma_f32 v[86:87], v[8:9], v[118:119], v[88:89]
	v_pk_fma_f32 v[88:89], v[10:11], v[118:119], v[90:91]
	v_pk_fma_f32 v[90:91], v[18:19], v[118:119], v[92:93]
	v_pk_fma_f32 v[92:93], v[12:13], v[118:119], v[94:95]
	v_pk_fma_f32 v[94:95], v[14:15], v[118:119], v[96:97]
	v_pk_fma_f32 v[96:97], v[16:17], v[118:119], v[98:99]
	v_pk_fma_f32 v[98:99], v[22:23], v[118:119], v[100:101]
	v_pk_fma_f32 v[100:101], v[20:21], v[118:119], v[102:103]
	v_pk_fma_f32 v[102:103], v[30:31], v[118:119], v[104:105]
	v_pk_fma_f32 v[104:105], v[26:27], v[118:119], v[106:107]
	v_pk_fma_f32 v[106:107], v[46:47], v[118:119], v[108:109]
	v_pk_fma_f32 v[108:109], v[24:25], v[118:119], v[110:111]
	v_pk_fma_f32 v[110:111], v[28:29], v[118:119], v[112:113]
	v_pk_fma_f32 v[112:113], v[44:45], v[118:119], v[114:115]
	v_pk_fma_f32 v[114:115], v[52:53], v[118:119], v[116:117]
	ds_read_b32 v52, v135
	s_waitcnt lgkmcnt(0)
	v_lshlrev_b32_e32 v116, 16, v52
	v_and_b32_e32 v117, 0xffff0000, v52
	v_pk_fma_f32 v[52:53], v[0:1], v[116:117], v[78:79]
	v_pk_fma_f32 v[78:79], v[70:71], v[116:117], v[80:81]
	v_pk_fma_f32 v[80:81], v[2:3], v[116:117], v[82:83]
	v_pk_fma_f32 v[82:83], v[4:5], v[116:117], v[84:85]
	v_pk_fma_f32 v[84:85], v[6:7], v[116:117], v[86:87]
	v_pk_fma_f32 v[86:87], v[8:9], v[116:117], v[88:89]
	v_pk_fma_f32 v[88:89], v[10:11], v[116:117], v[90:91]
	v_pk_fma_f32 v[90:91], v[18:19], v[116:117], v[92:93]
	v_pk_fma_f32 v[92:93], v[12:13], v[116:117], v[94:95]
	v_pk_fma_f32 v[94:95], v[14:15], v[116:117], v[96:97]
	v_pk_fma_f32 v[96:97], v[16:17], v[116:117], v[98:99]
	v_pk_fma_f32 v[98:99], v[22:23], v[116:117], v[100:101]
	v_pk_fma_f32 v[100:101], v[20:21], v[116:117], v[102:103]
	v_pk_fma_f32 v[102:103], v[30:31], v[116:117], v[104:105]
	v_pk_fma_f32 v[104:105], v[26:27], v[116:117], v[106:107]
	v_pk_fma_f32 v[106:107], v[46:47], v[116:117], v[108:109]
	v_pk_fma_f32 v[108:109], v[24:25], v[116:117], v[110:111]
	v_pk_fma_f32 v[110:111], v[28:29], v[116:117], v[112:113]
	v_pk_fma_f32 v[112:113], v[44:45], v[116:117], v[114:115]
	ds_read_b32 v44, v136
	s_waitcnt lgkmcnt(0)
	v_lshlrev_b32_e32 v114, 16, v44
	v_and_b32_e32 v115, 0xffff0000, v44
	v_pk_fma_f32 v[44:45], v[0:1], v[114:115], v[78:79]
	v_pk_fma_f32 v[78:79], v[70:71], v[114:115], v[80:81]
	v_pk_fma_f32 v[80:81], v[2:3], v[114:115], v[82:83]
	v_pk_fma_f32 v[82:83], v[4:5], v[114:115], v[84:85]
	v_pk_fma_f32 v[84:85], v[6:7], v[114:115], v[86:87]
	v_pk_fma_f32 v[86:87], v[8:9], v[114:115], v[88:89]
	v_pk_fma_f32 v[88:89], v[10:11], v[114:115], v[90:91]
	v_pk_fma_f32 v[90:91], v[18:19], v[114:115], v[92:93]
	v_pk_fma_f32 v[92:93], v[12:13], v[114:115], v[94:95]
	v_pk_fma_f32 v[94:95], v[14:15], v[114:115], v[96:97]
	v_pk_fma_f32 v[96:97], v[16:17], v[114:115], v[98:99]
	v_pk_fma_f32 v[98:99], v[22:23], v[114:115], v[100:101]
	v_pk_fma_f32 v[100:101], v[20:21], v[114:115], v[102:103]
	v_pk_fma_f32 v[102:103], v[30:31], v[114:115], v[104:105]
	v_pk_fma_f32 v[104:105], v[26:27], v[114:115], v[106:107]
	v_pk_fma_f32 v[106:107], v[46:47], v[114:115], v[108:109]
	v_pk_fma_f32 v[108:109], v[24:25], v[114:115], v[110:111]
	v_pk_fma_f32 v[110:111], v[28:29], v[114:115], v[112:113]
	ds_read_b32 v28, v137
	s_waitcnt lgkmcnt(0)
; DI float bflo(unsigned w) { return __uint_as_float(w << 16); }
; DI float bfhi(unsigned w) { return __uint_as_float(w & 0xffff0000u); }
; template <int R> DI void conv_row(f32x2 (&acc)[32], const f32x2 (&wt)[31], const unsigned* tile, int tid) {
;   const unsigned x = tile[R * 512 + tid];
;   const f32x2 xv = {bflo(x), bfhi(x)};
; #pragma unroll
;   for (int i = 0; i < 32; ++i) { if (R - i >= 0 && R - i < 31) acc[i] = acc[i] + xv * wt[(R - i >= 0 && R - i < 31) ? R - i : 0]; }
;   if ((R & 7) == 7) asm volatile("" ::: "memory");
	v_lshlrev_b32_e32 v112, 16, v28
	v_and_b32_e32 v113, 0xffff0000, v28
	v_pk_fma_f32 v[28:29], v[0:1], v[112:113], v[78:79]
	v_pk_fma_f32 v[78:79], v[70:71], v[112:113], v[80:81]
	v_pk_fma_f32 v[80:81], v[2:3], v[112:113], v[82:83]
	v_pk_fma_f32 v[82:83], v[4:5], v[112:113], v[84:85]
	v_pk_fma_f32 v[84:85], v[6:7], v[112:113], v[86:87]
	v_pk_fma_f32 v[86:87], v[8:9], v[112:113], v[88:89]
	v_pk_fma_f32 v[88:89], v[10:11], v[112:113], v[90:91]
	v_pk_fma_f32 v[90:91], v[18:19], v[112:113], v[92:93]
	v_pk_fma_f32 v[92:93], v[12:13], v[112:113], v[94:95]
	v_pk_fma_f32 v[94:95], v[14:15], v[112:113], v[96:97]
	v_pk_fma_f32 v[96:97], v[16:17], v[112:113], v[98:99]
	v_pk_fma_f32 v[98:99], v[22:23], v[112:113], v[100:101]
	v_pk_fma_f32 v[100:101], v[20:21], v[112:113], v[102:103]
	v_pk_fma_f32 v[102:103], v[30:31], v[112:113], v[104:105]
	v_pk_fma_f32 v[104:105], v[26:27], v[112:113], v[106:107]
	v_pk_fma_f32 v[106:107], v[46:47], v[112:113], v[108:109]
	v_pk_fma_f32 v[108:109], v[24:25], v[112:113], v[110:111]
	ds_read_b32 v24, v138
	s_waitcnt lgkmcnt(0)
	v_lshlrev_b32_e32 v110, 16, v24
	v_and_b32_e32 v111, 0xffff0000, v24
	v_pk_fma_f32 v[24:25], v[0:1], v[110:111], v[78:79]
	v_pk_fma_f32 v[78:79], v[70:71], v[110:111], v[80:81]
	v_pk_fma_f32 v[80:81], v[2:3], v[110:111], v[82:83]
	v_pk_fma_f32 v[82:83], v[4:5], v[110:111], v[84:85]
	v_pk_fma_f32 v[84:85], v[6:7], v[110:111], v[86:87]
	v_pk_fma_f32 v[86:87], v[8:9], v[110:111], v[88:89]
	v_pk_fma_f32 v[88:89], v[10:11], v[110:111], v[90:91]
	v_pk_fma_f32 v[90:91], v[18:19], v[110:111], v[92:93]
	v_pk_fma_f32 v[92:93], v[12:13], v[110:111], v[94:95]
	v_pk_fma_f32 v[94:95], v[14:15], v[110:111], v[96:97]
	v_pk_fma_f32 v[96:97], v[16:17], v[110:111], v[98:99]
	v_pk_fma_f32 v[98:99], v[22:23], v[110:111], v[100:101]
	v_pk_fma_f32 v[100:101], v[20:21], v[110:111], v[102:103]
	v_pk_fma_f32 v[102:103], v[30:31], v[110:111], v[104:105]
	v_pk_fma_f32 v[104:105], v[26:27], v[110:111], v[106:107]
	v_pk_fma_f32 v[106:107], v[46:47], v[110:111], v[108:109]
	ds_read_b32 v46, v139
	s_waitcnt lgkmcnt(0)
	v_lshlrev_b32_e32 v108, 16, v46
	v_and_b32_e32 v109, 0xffff0000, v46
	v_pk_fma_f32 v[46:47], v[0:1], v[108:109], v[78:79]
	v_pk_fma_f32 v[78:79], v[70:71], v[108:109], v[80:81]
	v_pk_fma_f32 v[80:81], v[2:3], v[108:109], v[82:83]
	v_pk_fma_f32 v[82:83], v[4:5], v[108:109], v[84:85]
	v_pk_fma_f32 v[84:85], v[6:7], v[108:109], v[86:87]
	v_pk_fma_f32 v[86:87], v[8:9], v[108:109], v[88:89]
	v_pk_fma_f32 v[88:89], v[10:11], v[108:109], v[90:91]
	v_pk_fma_f32 v[90:91], v[18:19], v[108:109], v[92:93]
	v_pk_fma_f32 v[92:93], v[12:13], v[108:109], v[94:95]
	v_pk_fma_f32 v[94:95], v[14:15], v[108:109], v[96:97]
	v_pk_fma_f32 v[96:97], v[16:17], v[108:109], v[98:99]
	v_pk_fma_f32 v[98:99], v[22:23], v[108:109], v[100:101]
	v_pk_fma_f32 v[100:101], v[20:21], v[108:109], v[102:103]
	v_pk_fma_f32 v[102:103], v[30:31], v[108:109], v[104:105]
	v_pk_fma_f32 v[104:105], v[26:27], v[108:109], v[106:107]
	ds_read_b32 v26, v140
	s_waitcnt lgkmcnt(0)
	v_lshlrev_b32_e32 v106, 16, v26
	v_and_b32_e32 v107, 0xffff0000, v26
	v_pk_fma_f32 v[26:27], v[0:1], v[106:107], v[78:79]
	v_pk_fma_f32 v[78:79], v[70:71], v[106:107], v[80:81]
	v_pk_fma_f32 v[80:81], v[2:3], v[106:107], v[82:83]
	v_pk_fma_f32 v[82:83], v[4:5], v[106:107], v[84:85]
	v_pk_fma_f32 v[84:85], v[6:7], v[106:107], v[86:87]
	v_pk_fma_f32 v[86:87], v[8:9], v[106:107], v[88:89]
	v_pk_fma_f32 v[88:89], v[10:11], v[106:107], v[90:91]
	v_pk_fma_f32 v[90:91], v[18:19], v[106:107], v[92:93]
	v_pk_fma_f32 v[92:93], v[12:13], v[106:107], v[94:95]
	v_pk_fma_f32 v[94:95], v[14:15], v[106:107], v[96:97]
	v_pk_fma_f32 v[96:97], v[16:17], v[106:107], v[98:99]
	v_pk_fma_f32 v[98:99], v[22:23], v[106:107], v[100:101]
	v_pk_fma_f32 v[100:101], v[20:21], v[106:107], v[102:103]
	v_pk_fma_f32 v[102:103], v[30:31], v[106:107], v[104:105]
	ds_read_b32 v30, v141
	s_waitcnt lgkmcnt(0)
	v_lshlrev_b32_e32 v104, 16, v30
	v_and_b32_e32 v105, 0xffff0000, v30
	v_pk_fma_f32 v[30:31], v[0:1], v[104:105], v[78:79]
	v_pk_fma_f32 v[78:79], v[70:71], v[104:105], v[80:81]
	v_pk_fma_f32 v[80:81], v[2:3], v[104:105], v[82:83]
	v_pk_fma_f32 v[82:83], v[4:5], v[104:105], v[84:85]
	v_pk_fma_f32 v[84:85], v[6:7], v[104:105], v[86:87]
	v_pk_fma_f32 v[86:87], v[8:9], v[104:105], v[88:89]
	v_pk_fma_f32 v[88:89], v[10:11], v[104:105], v[90:91]
	v_pk_fma_f32 v[90:91], v[18:19], v[104:105], v[92:93]
	v_pk_fma_f32 v[92:93], v[12:13], v[104:105], v[94:95]
	v_pk_fma_f32 v[94:95], v[14:15], v[104:105], v[96:97]
	v_pk_fma_f32 v[96:97], v[16:17], v[104:105], v[98:99]
	v_pk_fma_f32 v[98:99], v[22:23], v[104:105], v[100:101]
	v_pk_fma_f32 v[100:101], v[20:21], v[104:105], v[102:103]
	ds_read_b32 v20, v142
	s_waitcnt lgkmcnt(0)
	v_lshlrev_b32_e32 v102, 16, v20
	v_and_b32_e32 v103, 0xffff0000, v20
	v_pk_fma_f32 v[20:21], v[0:1], v[102:103], v[78:79]
	v_pk_fma_f32 v[78:79], v[70:71], v[102:103], v[80:81]
	v_pk_fma_f32 v[80:81], v[2:3], v[102:103], v[82:83]
	v_pk_fma_f32 v[82:83], v[4:5], v[102:103], v[84:85]
	v_pk_fma_f32 v[84:85], v[6:7], v[102:103], v[86:87]
	v_pk_fma_f32 v[86:87], v[8:9], v[102:103], v[88:89]
	v_pk_fma_f32 v[88:89], v[10:11], v[102:103], v[90:91]
	v_pk_fma_f32 v[90:91], v[18:19], v[102:103], v[92:93]
	v_pk_fma_f32 v[92:93], v[12:13], v[102:103], v[94:95]
	v_pk_fma_f32 v[94:95], v[14:15], v[102:103], v[96:97]
	v_pk_fma_f32 v[96:97], v[16:17], v[102:103], v[98:99]
	v_pk_fma_f32 v[98:99], v[22:23], v[102:103], v[100:101]
	ds_read_b32 v22, v143
	s_waitcnt lgkmcnt(0)
; DI float bflo(unsigned w) { return __uint_as_float(w << 16); }
; DI float bfhi(unsigned w) { return __uint_as_float(w & 0xffff0000u); }
; template <int R> DI void conv_row(f32x2 (&acc)[32], const f32x2 (&wt)[31], const unsigned* tile, int tid) {
;   const unsigned x = tile[R * 512 + tid];
;   const f32x2 xv = {bflo(x), bfhi(x)};
; #pragma unroll
;   for (int i = 0; i < 32; ++i) { if (R - i >= 0 && R - i < 31) acc[i] = acc[i] + xv * wt[(R - i >= 0 && R - i < 31) ? R - i : 0]; }
;   if ((R & 7) == 7) asm volatile("" ::: "memory");
; DI void conv_phase(const bf16_t* hc, bf16_t* hn, char* lds) {
;     ...
;     __syncthreads();
	v_lshlrev_b32_e32 v100, 16, v22
	v_and_b32_e32 v101, 0xffff0000, v22
	v_pk_fma_f32 v[22:23], v[0:1], v[100:101], v[78:79]
	v_pk_fma_f32 v[78:79], v[70:71], v[100:101], v[80:81]
	v_pk_fma_f32 v[80:81], v[2:3], v[100:101], v[82:83]
	v_pk_fma_f32 v[82:83], v[4:5], v[100:101], v[84:85]
	v_pk_fma_f32 v[84:85], v[6:7], v[100:101], v[86:87]
	v_pk_fma_f32 v[86:87], v[8:9], v[100:101], v[88:89]
	v_pk_fma_f32 v[88:89], v[10:11], v[100:101], v[90:91]
	v_pk_fma_f32 v[90:91], v[18:19], v[100:101], v[92:93]
	v_pk_fma_f32 v[92:93], v[12:13], v[100:101], v[94:95]
	v_pk_fma_f32 v[94:95], v[14:15], v[100:101], v[96:97]
	v_pk_fma_f32 v[96:97], v[16:17], v[100:101], v[98:99]
	ds_read_b32 v16, v148
	s_waitcnt lgkmcnt(0)
	v_lshlrev_b32_e32 v98, 16, v16
	v_and_b32_e32 v99, 0xffff0000, v16
	v_pk_fma_f32 v[16:17], v[0:1], v[98:99], v[78:79]
	v_pk_fma_f32 v[78:79], v[70:71], v[98:99], v[80:81]
	v_pk_fma_f32 v[80:81], v[2:3], v[98:99], v[82:83]
	v_pk_fma_f32 v[82:83], v[4:5], v[98:99], v[84:85]
	v_pk_fma_f32 v[84:85], v[6:7], v[98:99], v[86:87]
	v_pk_fma_f32 v[86:87], v[8:9], v[98:99], v[88:89]
	v_pk_fma_f32 v[88:89], v[10:11], v[98:99], v[90:91]
	v_pk_fma_f32 v[90:91], v[18:19], v[98:99], v[92:93]
	v_pk_fma_f32 v[92:93], v[12:13], v[98:99], v[94:95]
	v_pk_fma_f32 v[94:95], v[14:15], v[98:99], v[96:97]
	ds_read_b32 v14, v150
	s_waitcnt lgkmcnt(0)
	v_lshlrev_b32_e32 v96, 16, v14
	v_and_b32_e32 v97, 0xffff0000, v14
	v_pk_fma_f32 v[14:15], v[0:1], v[96:97], v[78:79]
	v_pk_fma_f32 v[78:79], v[70:71], v[96:97], v[80:81]
	v_pk_fma_f32 v[80:81], v[2:3], v[96:97], v[82:83]
	v_pk_fma_f32 v[82:83], v[4:5], v[96:97], v[84:85]
	v_pk_fma_f32 v[84:85], v[6:7], v[96:97], v[86:87]
	v_pk_fma_f32 v[86:87], v[8:9], v[96:97], v[88:89]
	v_pk_fma_f32 v[88:89], v[10:11], v[96:97], v[90:91]
	v_pk_fma_f32 v[90:91], v[18:19], v[96:97], v[92:93]
	v_pk_fma_f32 v[92:93], v[12:13], v[96:97], v[94:95]
	ds_read_b32 v12, v151
	s_waitcnt lgkmcnt(0)
	v_lshlrev_b32_e32 v94, 16, v12
	v_and_b32_e32 v95, 0xffff0000, v12
	v_pk_fma_f32 v[12:13], v[0:1], v[94:95], v[78:79]
	v_pk_fma_f32 v[78:79], v[70:71], v[94:95], v[80:81]
	v_pk_fma_f32 v[80:81], v[2:3], v[94:95], v[82:83]
	v_pk_fma_f32 v[82:83], v[4:5], v[94:95], v[84:85]
	v_pk_fma_f32 v[84:85], v[6:7], v[94:95], v[86:87]
	v_pk_fma_f32 v[86:87], v[8:9], v[94:95], v[88:89]
	v_pk_fma_f32 v[88:89], v[10:11], v[94:95], v[90:91]
	v_pk_fma_f32 v[90:91], v[18:19], v[94:95], v[92:93]
	ds_read_b32 v18, v152
	s_waitcnt lgkmcnt(0)
	v_lshlrev_b32_e32 v92, 16, v18
	v_and_b32_e32 v93, 0xffff0000, v18
	v_pk_fma_f32 v[18:19], v[0:1], v[92:93], v[78:79]
	v_pk_fma_f32 v[78:79], v[70:71], v[92:93], v[80:81]
	v_pk_fma_f32 v[80:81], v[2:3], v[92:93], v[82:83]
	v_pk_fma_f32 v[82:83], v[4:5], v[92:93], v[84:85]
	v_pk_fma_f32 v[84:85], v[6:7], v[92:93], v[86:87]
	v_pk_fma_f32 v[86:87], v[8:9], v[92:93], v[88:89]
	v_pk_fma_f32 v[88:89], v[10:11], v[92:93], v[90:91]
	ds_read_b32 v10, v153
	s_waitcnt lgkmcnt(0)
	v_lshlrev_b32_e32 v90, 16, v10
	v_and_b32_e32 v91, 0xffff0000, v10
	v_pk_fma_f32 v[10:11], v[0:1], v[90:91], v[78:79]
	v_pk_fma_f32 v[78:79], v[70:71], v[90:91], v[80:81]
	v_pk_fma_f32 v[80:81], v[2:3], v[90:91], v[82:83]
	v_pk_fma_f32 v[82:83], v[4:5], v[90:91], v[84:85]
	v_pk_fma_f32 v[84:85], v[6:7], v[90:91], v[86:87]
	v_pk_fma_f32 v[86:87], v[8:9], v[90:91], v[88:89]
	ds_read_b32 v8, v154
	s_waitcnt lgkmcnt(0)
	v_lshlrev_b32_e32 v88, 16, v8
	v_and_b32_e32 v89, 0xffff0000, v8
	v_pk_fma_f32 v[8:9], v[0:1], v[88:89], v[78:79]
	v_pk_fma_f32 v[78:79], v[70:71], v[88:89], v[80:81]
	v_pk_fma_f32 v[80:81], v[2:3], v[88:89], v[82:83]
	v_pk_fma_f32 v[82:83], v[4:5], v[88:89], v[84:85]
	v_pk_fma_f32 v[84:85], v[6:7], v[88:89], v[86:87]
	ds_read_b32 v6, v155
	s_waitcnt lgkmcnt(0)
	v_lshlrev_b32_e32 v86, 16, v6
	v_and_b32_e32 v87, 0xffff0000, v6
	v_pk_fma_f32 v[6:7], v[0:1], v[86:87], v[78:79]
	v_pk_fma_f32 v[78:79], v[70:71], v[86:87], v[80:81]
	v_pk_fma_f32 v[80:81], v[2:3], v[86:87], v[82:83]
	v_pk_fma_f32 v[82:83], v[4:5], v[86:87], v[84:85]
	ds_read_b32 v4, v156
	s_waitcnt lgkmcnt(0)
	v_lshlrev_b32_e32 v84, 16, v4
	v_and_b32_e32 v85, 0xffff0000, v4
	v_pk_fma_f32 v[4:5], v[0:1], v[84:85], v[78:79]
	v_pk_fma_f32 v[78:79], v[70:71], v[84:85], v[80:81]
	v_pk_fma_f32 v[80:81], v[2:3], v[84:85], v[82:83]
	ds_read_b32 v2, v157
	s_waitcnt lgkmcnt(0)
	v_lshlrev_b32_e32 v82, 16, v2
	v_and_b32_e32 v83, 0xffff0000, v2
	v_pk_fma_f32 v[2:3], v[0:1], v[82:83], v[78:79]
	ds_read_b32 v79, v158
	v_pk_fma_f32 v[70:71], v[70:71], v[82:83], v[80:81]
	s_waitcnt lgkmcnt(0)
	s_barrier
; DI void conv_phase(const bf16_t* hc, bf16_t* hn, char* lds) {
;     ...
;     for (int i = 0; i < 32; ++i) { red[i * 512 + tid] = acc[i].x + acc[i].y; red[(32 + i) * 512 + tid] = acc[i].x * acc[i].x + acc[i].y * acc[i].y; }
;     __syncthreads();
	v_lshlrev_b32_e32 v78, 16, v79
	v_and_b32_e32 v79, 0xffff0000, v79
	v_pk_fma_f32 v[0:1], v[0:1], v[78:79], v[70:71]
	v_pk_mul_f32 v[70:71], v[76:77], v[76:77]
	v_add_f32_e32 v78, v76, v77
	v_add_f32_e32 v70, v70, v71
	ds_write_b32 v177, v70
	v_add_f32_e32 v70, v74, v75
	ds_write2st64_b32 v124, v78, v70 offset1:8
	v_pk_mul_f32 v[70:71], v[74:75], v[74:75]
	v_add_f32_e32 v78, v68, v69
	v_add_f32_e32 v70, v70, v71
	ds_write_b32 v178, v70
	v_pk_mul_f32 v[70:71], v[68:69], v[68:69]
	s_nop 0
	v_add_f32_e32 v70, v70, v71
	ds_write_b32 v179, v70
	v_add_f32_e32 v70, v72, v73
	ds_write2st64_b32 v124, v78, v70 offset0:16 offset1:24
	v_pk_mul_f32 v[70:71], v[72:73], v[72:73]
	v_add_f32_e32 v78, v64, v65
	v_add_f32_e32 v70, v70, v71
	ds_write_b32 v180, v70
	v_pk_mul_f32 v[70:71], v[64:65], v[64:65]
	s_nop 0
	v_add_f32_e32 v70, v70, v71
	ds_write_b32 v181, v70
	v_add_f32_e32 v70, v66, v67
	ds_write2st64_b32 v124, v78, v70 offset0:32 offset1:40
	v_pk_mul_f32 v[70:71], v[66:67], v[66:67]
	v_add_f32_e32 v78, v56, v57
	v_add_f32_e32 v70, v70, v71
	ds_write_b32 v182, v70
	v_pk_mul_f32 v[70:71], v[56:57], v[56:57]
	s_nop 0
	v_add_f32_e32 v70, v70, v71
	ds_write_b32 v183, v70
	v_add_f32_e32 v70, v54, v55
	ds_write2st64_b32 v124, v78, v70 offset0:48 offset1:56
	v_pk_mul_f32 v[70:71], v[54:55], v[54:55]
	v_add_f32_e32 v78, v50, v51
	v_add_f32_e32 v70, v70, v71
	ds_write_b32 v184, v70
	v_pk_mul_f32 v[70:71], v[50:51], v[50:51]
	s_nop 0
	v_add_f32_e32 v70, v70, v71
	ds_write_b32 v185, v70
	v_add_f32_e32 v70, v62, v63
	ds_write2st64_b32 v124, v78, v70 offset0:64 offset1:72
	v_pk_mul_f32 v[70:71], v[62:63], v[62:63]
	v_add_f32_e32 v78, v58, v59
	v_add_f32_e32 v70, v70, v71
	ds_write_b32 v186, v70
	v_pk_mul_f32 v[70:71], v[58:59], v[58:59]
	s_nop 0
	v_add_f32_e32 v70, v70, v71
	ds_write_b32 v187, v70
	v_add_f32_e32 v70, v60, v61
	ds_write2st64_b32 v124, v78, v70 offset0:80 offset1:88
	v_pk_mul_f32 v[70:71], v[60:61], v[60:61]
	v_add_f32_e32 v78, v48, v49
	v_add_f32_e32 v70, v70, v71
	ds_write_b32 v188, v70
	v_pk_mul_f32 v[70:71], v[48:49], v[48:49]
	s_nop 0
	v_add_f32_e32 v70, v70, v71
	ds_write_b32 v189, v70
	v_add_f32_e32 v70, v52, v53
	ds_write2st64_b32 v124, v78, v70 offset0:96 offset1:104
	v_pk_mul_f32 v[70:71], v[52:53], v[52:53]
	v_add_f32_e32 v78, v44, v45
	v_add_f32_e32 v70, v70, v71
	ds_write_b32 v190, v70
	v_pk_mul_f32 v[70:71], v[44:45], v[44:45]
	s_nop 0
	v_add_f32_e32 v70, v70, v71
	ds_write_b32 v191, v70
	v_add_f32_e32 v70, v28, v29
	ds_write2st64_b32 v124, v78, v70 offset0:112 offset1:120
	v_pk_mul_f32 v[70:71], v[28:29], v[28:29]
	v_add_f32_e32 v78, v24, v25
	v_add_f32_e32 v70, v70, v71
	ds_write_b32 v192, v70
	v_pk_mul_f32 v[70:71], v[24:25], v[24:25]
	s_nop 0
	v_add_f32_e32 v70, v70, v71
	ds_write_b32 v193, v70
	v_add_f32_e32 v70, v46, v47
	ds_write2st64_b32 v124, v78, v70 offset0:128 offset1:136
	v_pk_mul_f32 v[70:71], v[46:47], v[46:47]
	v_add_f32_e32 v78, v26, v27
	v_add_f32_e32 v70, v70, v71
	ds_write_b32 v194, v70
	v_pk_mul_f32 v[70:71], v[26:27], v[26:27]
	s_nop 0
	v_add_f32_e32 v70, v70, v71
	ds_write_b32 v195, v70
	v_add_f32_e32 v70, v30, v31
	ds_write2st64_b32 v124, v78, v70 offset0:144 offset1:152
	v_pk_mul_f32 v[70:71], v[30:31], v[30:31]
	v_add_f32_e32 v78, v20, v21
	v_add_f32_e32 v70, v70, v71
	ds_write_b32 v196, v70
	v_pk_mul_f32 v[70:71], v[20:21], v[20:21]
	s_nop 0
	v_add_f32_e32 v70, v70, v71
	ds_write_b32 v197, v70
	v_add_f32_e32 v70, v22, v23
	ds_write2st64_b32 v124, v78, v70 offset0:160 offset1:168
	v_pk_mul_f32 v[70:71], v[22:23], v[22:23]
	v_add_f32_e32 v78, v16, v17
	v_add_f32_e32 v70, v70, v71
	ds_write_b32 v198, v70
	v_pk_mul_f32 v[70:71], v[16:17], v[16:17]
	s_nop 0
	v_add_f32_e32 v70, v70, v71
	ds_write_b32 v199, v70
	v_add_f32_e32 v70, v14, v15
	ds_write2st64_b32 v124, v78, v70 offset0:176 offset1:184
	v_pk_mul_f32 v[70:71], v[14:15], v[14:15]
	v_add_f32_e32 v78, v12, v13
	v_add_f32_e32 v70, v70, v71
	ds_write_b32 v200, v70
	v_pk_mul_f32 v[70:71], v[12:13], v[12:13]
	s_nop 0
	v_add_f32_e32 v70, v70, v71
	ds_write_b32 v201, v70
	v_add_f32_e32 v70, v18, v19
	ds_write2st64_b32 v124, v78, v70 offset0:192 offset1:200
	v_pk_mul_f32 v[70:71], v[18:19], v[18:19]
	v_add_f32_e32 v78, v10, v11
	v_add_f32_e32 v70, v70, v71
	ds_write_b32 v202, v70
	v_pk_mul_f32 v[70:71], v[10:11], v[10:11]
	s_nop 0
	v_add_f32_e32 v70, v70, v71
	ds_write_b32 v203, v70
	v_add_f32_e32 v70, v8, v9
	ds_write2st64_b32 v124, v78, v70 offset0:208 offset1:216
	v_pk_mul_f32 v[70:71], v[8:9], v[8:9]
	v_add_f32_e32 v78, v6, v7
	v_add_f32_e32 v70, v70, v71
	ds_write_b32 v218, v70
	v_pk_mul_f32 v[70:71], v[6:7], v[6:7]
	s_nop 0
	v_add_f32_e32 v70, v70, v71
	ds_write_b32 v219, v70
	v_add_f32_e32 v70, v4, v5
	ds_write2st64_b32 v124, v78, v70 offset0:224 offset1:232
	v_pk_mul_f32 v[70:71], v[4:5], v[4:5]
	v_add_f32_e32 v78, v2, v3
	v_add_f32_e32 v70, v70, v71
	ds_write_b32 v220, v70
	v_pk_mul_f32 v[70:71], v[2:3], v[2:3]
	s_nop 0
	v_add_f32_e32 v70, v70, v71
	ds_write_b32 v221, v70
	v_add_f32_e32 v70, v0, v1
	ds_write2st64_b32 v124, v78, v70 offset0:240 offset1:248
	v_pk_mul_f32 v[70:71], v[0:1], v[0:1]
	s_nop 0
	v_add_f32_e32 v70, v70, v71
	ds_write_b32 v222, v70
	s_waitcnt lgkmcnt(0)
	s_barrier
; DI void conv_phase(const bf16_t* hc, bf16_t* hn, char* lds) {
;     ...
;     {
;       const int q = tid >> 3, part = tid & 7;
;       float sm = 0.f;
; #pragma unroll
;       for (int i = 0; i < 16; ++i) { f32x4 v = *(const f32x4*)(red + q * 512 + part * 64 + i * 4); sm += (v[0] + v[1]) + (v[2] + v[3]); }
;       sm += __shfl_xor(sm, 1); sm += __shfl_xor(sm, 2); sm += __shfl_xor(sm, 4);
;       if (part == 0) tot[q] = sm;
	ds_read_b128 v[78:81], v239
	ds_read_b128 v[82:85], v239 offset:16
	ds_read_b128 v[86:89], v239 offset:32
	ds_read_b128 v[90:93], v239 offset:48
	s_waitcnt lgkmcnt(3)
	v_add_f32_e32 v70, v78, v79
	v_add_f32_e32 v71, v80, v81
	v_add_f32_e32 v70, v70, v71
	s_waitcnt lgkmcnt(2)
	v_add_f32_e32 v71, v82, v83
	v_add_f32_e32 v78, v84, v85
	v_add_f32_e32 v70, 0, v70
	v_add_f32_e32 v71, v71, v78
	v_add_f32_e32 v70, v70, v71
	s_waitcnt lgkmcnt(1)
	v_add_f32_e32 v71, v86, v87
	v_add_f32_e32 v78, v88, v89
	v_add_f32_e32 v71, v71, v78
	v_add_f32_e32 v70, v70, v71
	s_waitcnt lgkmcnt(0)
	v_add_f32_e32 v71, v90, v91
	v_add_f32_e32 v78, v92, v93
	v_add_f32_e32 v71, v71, v78
	ds_read_b128 v[78:81], v239 offset:64
	v_add_f32_e32 v70, v70, v71
	s_waitcnt lgkmcnt(0)
	v_add_f32_e32 v71, v78, v79
	v_add_f32_e32 v78, v80, v81
	v_add_f32_e32 v71, v71, v78
	ds_read_b128 v[78:81], v239 offset:80
	v_add_f32_e32 v70, v70, v71
	s_waitcnt lgkmcnt(0)
	v_add_f32_e32 v71, v78, v79
	v_add_f32_e32 v78, v80, v81
	v_add_f32_e32 v71, v71, v78
	ds_read_b128 v[78:81], v239 offset:96
	v_add_f32_e32 v70, v70, v71
	s_waitcnt lgkmcnt(0)
	v_add_f32_e32 v71, v78, v79
	v_add_f32_e32 v78, v80, v81
	v_add_f32_e32 v71, v71, v78
	ds_read_b128 v[78:81], v239 offset:112
	v_add_f32_e32 v70, v70, v71
	s_waitcnt lgkmcnt(0)
	v_add_f32_e32 v71, v78, v79
	v_add_f32_e32 v78, v80, v81
	v_add_f32_e32 v71, v71, v78
	ds_read_b128 v[78:81], v239 offset:128
	v_add_f32_e32 v70, v70, v71
	s_waitcnt lgkmcnt(0)
	v_add_f32_e32 v71, v78, v79
	v_add_f32_e32 v78, v80, v81
	v_add_f32_e32 v71, v71, v78
	ds_read_b128 v[78:81], v239 offset:144
	v_add_f32_e32 v70, v70, v71
	s_waitcnt lgkmcnt(0)
	v_add_f32_e32 v71, v78, v79
	v_add_f32_e32 v78, v80, v81
	v_add_f32_e32 v71, v71, v78
	ds_read_b128 v[78:81], v239 offset:160
	v_add_f32_e32 v70, v70, v71
	s_waitcnt lgkmcnt(0)
	v_add_f32_e32 v71, v78, v79
	v_add_f32_e32 v78, v80, v81
	v_add_f32_e32 v71, v71, v78
	ds_read_b128 v[78:81], v239 offset:176
	v_add_f32_e32 v70, v70, v71
	s_waitcnt lgkmcnt(0)
	v_add_f32_e32 v71, v78, v79
	v_add_f32_e32 v78, v80, v81
	v_add_f32_e32 v71, v71, v78
	ds_read_b128 v[78:81], v239 offset:192
	v_add_f32_e32 v70, v70, v71
	s_waitcnt lgkmcnt(0)
	v_add_f32_e32 v71, v78, v79
	v_add_f32_e32 v78, v80, v81
	v_add_f32_e32 v71, v71, v78
	ds_read_b128 v[78:81], v239 offset:208
	v_add_f32_e32 v70, v70, v71
	s_waitcnt lgkmcnt(0)
	v_add_f32_e32 v71, v78, v79
	v_add_f32_e32 v78, v80, v81
	v_add_f32_e32 v71, v71, v78
	ds_read_b128 v[78:81], v239 offset:224
	v_add_f32_e32 v70, v70, v71
	s_waitcnt lgkmcnt(0)
	v_add_f32_e32 v71, v78, v79
	v_add_f32_e32 v78, v80, v81
	v_add_f32_e32 v71, v71, v78
	ds_read_b128 v[78:81], v239 offset:240
	v_add_f32_e32 v70, v70, v71
	s_waitcnt lgkmcnt(0)
	v_add_f32_e32 v71, v78, v79
	v_add_f32_e32 v78, v80, v81
	v_add_f32_e32 v71, v71, v78
	v_add_f32_e32 v70, v70, v71
	v_cndmask_b32_e32 v71, v206, v209, vcc
	v_lshlrev_b32_e32 v71, 2, v71
	s_nop 1
	v_mov_b32_dpp v71, v70 quad_perm:[1,0,3,2] row_mask:0xf bank_mask:0xf
	v_cmp_lt_i32_e32 vcc, v210, v208
	s_waitcnt lgkmcnt(0)
	v_add_f32_e32 v70, v70, v71
	v_cndmask_b32_e32 v71, v206, v210, vcc
	v_lshlrev_b32_e32 v71, 2, v71
	s_nop 1
	v_mov_b32_dpp v71, v70 quad_perm:[2,3,0,1] row_mask:0xf bank_mask:0xf
	v_cmp_lt_i32_e32 vcc, v211, v208
	s_waitcnt lgkmcnt(0)
	v_add_f32_e32 v70, v70, v71
	v_cndmask_b32_e32 v71, v206, v211, vcc
	v_lshlrev_b32_e32 v71, 2, v71
	s_nop 1
	v_mov_b32_dpp v71, v70 row_half_mirror row_mask:0xf bank_mask:0xf
	s_and_saveexec_b64 s[26:27], s[92:93]
	s_cbranch_execz .LBB0_651
	s_waitcnt lgkmcnt(0)
	v_add_f32_e32 v70, v70, v71
	ds_write_b32 v160, v70
	s_branch .LBB0_651

; DI float bflo(unsigned w) { return __uint_as_float(w << 16); }
; DI void rw_phase(const float* x, bf16_t* hb, const bf16_t* y, const float* gpost, float* rh, float* fout, bool y_unscaled) {
;     ...
;       for (int c = 0; c < 2; ++c) {
;         const u32x4 w = gld<u32x4>(hb + (size_t)row * 1024 + 512 * c + 8 * lane);
;         hv[8 * c + 0] = bflo(w.x); hv[8 * c + 1] = bfhi(w.x); hv[8 * c + 2] = bflo(w.y); hv[8 * c + 3] = bfhi(w.y);
;         hv[8 * c + 4] = bflo(w.z); hv[8 * c + 5] = bfhi(w.z); hv[8 * c + 6] = bflo(w.w); hv[8 * c + 7] = bfhi(w.w);
;       }
;     }
;     if (y) {
;       float yv[16]; float ss = 0.f;
; #pragma unroll
;       for (int c = 0; c < 2; ++c) {
;         const u32x4 w = gld<u32x4>(y + (size_t)row * 1024 + 512 * c + 8 * lane);
;         yv[8 * c + 0] = bflo(w.x); yv[8 * c + 1] = bfhi(w.x); yv[8 * c + 2] = bflo(w.y); yv[8 * c + 3] = bfhi(w.y);
;         yv[8 * c + 4] = bflo(w.z); yv[8 * c + 5] = bfhi(w.z); yv[8 * c + 6] = bflo(w.w); yv[8 * c + 7] = bfhi(w.w);
;       }
; #pragma unroll
;       for (int i = 0; i < 16; ++i) ss += yv[i] * yv[i];
;       ss = wave_sum(ss);
;       float epsn = EPS;
;       if (y_unscaled) { const float r = gld<float>(rh + row), r2 = r * r; epsn = EPS / (r2 * r2); }
;       const float ry = rsqrtf(ss * (1.0f / 1024.0f) + epsn);
; #pragma unroll
;       for (int c = 0; c < 2; ++c) {
;         const f32x4 g0 = gld<f32x4>(gpost + 512 * c + 8 * lane), g1 = gld<f32x4>(gpost + 512 * c + 8 * lane + 4);
; #pragma unroll
;         for (int i = 0; i < 4; ++i) { hv[8 * c + i] += yv[8 * c + i] * ry * g0[i]; hv[8 * c + 4 + i] += yv[8 * c + 4 + i] * ry * g1[i]; }
;       }
;     }
;     if (fout) {
;       float* op = fout + (size_t)row * 1024;
; #pragma unroll
;       for (int c = 0; c < 2; ++c) {
;         gst<f32x4>(op + 512 * c + 8 * lane, (f32x4){hv[8 * c], hv[8 * c + 1], hv[8 * c + 2], hv[8 * c + 3]});
;         gst<f32x4>(op + 512 * c + 8 * lane + 4, (f32x4){hv[8 * c + 4], hv[8 * c + 5], hv[8 * c + 6], hv[8 * c + 7]});
;       }
;     } else {
;       float s2 = 0.f;
; #pragma unroll
;       for (int c = 0; c < 2; ++c) {
;         u32x4 w;
;         w.x = pk(hv[8 * c + 0], hv[8 * c + 1]); w.y = pk(hv[8 * c + 2], hv[8 * c + 3]); w.z = pk(hv[8 * c + 4], hv[8 * c + 5]); w.w = pk(hv[8 * c + 6], hv[8 * c + 7]);
;         gst<u32x4>(hb + (size_t)row * 1024 + 512 * c + 8 * lane, w);
.LBB0_733:
	v_ashrrev_i32_e32 v1, 31, v0
	v_lshlrev_b64 v[8:9], 11, v[0:1]
	v_lshl_add_u64 v[20:21], v[4:5], 0, v[8:9]
	s_waitcnt lgkmcnt(0)
	global_load_dwordx4 v[16:19], v[20:21], off offset:1024
	s_nop 0
	global_load_dwordx4 v[20:23], v[20:21], off
	v_lshl_add_u64 v[8:9], v[2:3], 0, v[8:9]
	global_load_dwordx4 v[24:27], v[8:9], off offset:1024
	global_load_dwordx4 v[28:31], v[8:9], off
	global_load_dwordx4 v[32:35], v[6:7], off offset:16
	global_load_dwordx4 v[36:39], v[6:7], off
	global_load_dwordx4 v[40:43], v[6:7], off offset:2064
	global_load_dwordx4 v[44:47], v[6:7], off offset:2048
	s_waitcnt vmcnt(0)
	v_lshlrev_b32_e32 v48, 16, v19
	v_lshlrev_b32_e32 v56, 16, v20
	v_and_b32_e32 v57, 0xffff0000, v20
	v_and_b32_e32 v49, 0xffff0000, v19
	v_lshlrev_b32_e32 v50, 16, v18
	v_and_b32_e32 v51, 0xffff0000, v18
	v_lshlrev_b32_e32 v18, 16, v17
	v_and_b32_e32 v19, 0xffff0000, v17
	v_lshlrev_b32_e32 v52, 16, v16
	v_and_b32_e32 v53, 0xffff0000, v16
	v_lshlrev_b32_e32 v16, 16, v23
	v_and_b32_e32 v17, 0xffff0000, v23
	v_lshlrev_b32_e32 v54, 16, v22
	v_and_b32_e32 v55, 0xffff0000, v22
	v_lshlrev_b32_e32 v22, 16, v21
	v_and_b32_e32 v23, 0xffff0000, v21
	v_pk_mul_f32 v[70:71], v[56:57], v[56:57]
	v_pk_mul_f32 v[68:69], v[22:23], v[22:23]
	v_add_f32_e32 v70, v70, v71
	v_add_f32_e32 v68, v68, v70
	v_pk_mul_f32 v[66:67], v[54:55], v[54:55]
	v_add_f32_e32 v68, v69, v68
	v_add_f32_e32 v66, v66, v68
	v_pk_mul_f32 v[64:65], v[16:17], v[16:17]
	v_add_f32_e32 v66, v67, v66
	v_add_f32_e32 v64, v64, v66
	v_pk_mul_f32 v[62:63], v[52:53], v[52:53]
	v_add_f32_e32 v64, v65, v64
	v_add_f32_e32 v62, v62, v64
	v_pk_mul_f32 v[60:61], v[18:19], v[18:19]
	v_add_f32_e32 v62, v63, v62
	v_add_f32_e32 v60, v60, v62
	v_pk_mul_f32 v[58:59], v[50:51], v[50:51]
	v_add_f32_e32 v60, v61, v60
	v_add_f32_e32 v58, v58, v60
	v_pk_mul_f32 v[20:21], v[48:49], v[48:49]
	v_add_f32_e32 v58, v59, v58
	v_add_f32_e32 v20, v20, v58
	v_add_f32_e32 v20, v21, v20
	s_nop 1
	v_mov_b32_dpp v21, v20 quad_perm:[1,0,3,2] row_mask:0xf bank_mask:0xf
	v_and_b32_e32 v59, 0xffff0000, v26
	s_waitcnt lgkmcnt(0)
	v_add_f32_e32 v20, v20, v21
	s_nop 1
	v_mov_b32_dpp v21, v20 quad_perm:[2,3,0,1] row_mask:0xf bank_mask:0xf
	s_waitcnt lgkmcnt(0)
	v_add_f32_e32 v21, v20, v21
	s_nop 1
	v_mov_b32_dpp v58, v21 row_half_mirror row_mask:0xf bank_mask:0xf
	v_lshlrev_b32_e32 v20, 16, v27
	s_waitcnt lgkmcnt(0)
	v_add_f32_e32 v60, v21, v58
	s_nop 1
	v_mov_b32_dpp v61, v60 row_mirror row_mask:0xf bank_mask:0xf
	v_and_b32_e32 v21, 0xffff0000, v27
	v_lshlrev_b32_e32 v58, 16, v26
	v_lshlrev_b32_e32 v26, 16, v25
	v_and_b32_e32 v27, 0xffff0000, v25
	s_waitcnt lgkmcnt(0)
	v_add_f32_e32 v62, v60, v61
	v_mov_b32_e32 v63, v62
	v_mov_b32_e32 v120, v62
	s_nop 1
	v_permlane16_swap_b32_e32 v63, v120
	v_lshlrev_b32_e32 v60, 16, v24
	v_and_b32_e32 v61, 0xffff0000, v24
	v_lshlrev_b32_e32 v24, 16, v31
	v_and_b32_e32 v25, 0xffff0000, v31
	s_waitcnt lgkmcnt(0)
	v_add_f32_e32 v64, v63, v120
	v_mov_b32_e32 v65, v64
	v_mov_b32_e32 v120, v64
	s_nop 1
	v_permlane32_swap_b32_e32 v65, v120
	v_lshlrev_b32_e32 v62, 16, v30
	v_and_b32_e32 v63, 0xffff0000, v30
	v_lshlrev_b32_e32 v30, 16, v29
	s_waitcnt lgkmcnt(0)
	v_add_f32_e32 v31, v65, v120
	v_fmamk_f32 v31, v31, 0x3a800000, v204
	v_mul_f32_e32 v64, 0x4b800000, v31
	v_cmp_gt_f32_e64 s[42:43], s33, v31
	v_and_b32_e32 v65, 0xffff0000, v28
	s_nop 0
	v_cndmask_b32_e64 v31, v31, v64, s[42:43]
	v_rsq_f32_e32 v66, v31
	v_lshlrev_b32_e32 v64, 16, v28
	v_and_b32_e32 v31, 0xffff0000, v29
	v_mul_f32_e32 v28, 0x45800000, v66
	v_cndmask_b32_e64 v28, v66, v28, s[42:43]
	v_pk_mul_f32 v[56:57], v[28:29], v[56:57] op_sel_hi:[0,1]
	v_pk_mul_f32 v[22:23], v[28:29], v[22:23] op_sel_hi:[0,1]
	v_pk_mul_f32 v[16:17], v[28:29], v[16:17] op_sel_hi:[0,1]
	v_pk_mul_f32 v[52:53], v[28:29], v[52:53] op_sel_hi:[0,1]
	v_pk_mul_f32 v[54:55], v[28:29], v[54:55] op_sel_hi:[0,1]
	v_pk_mul_f32 v[18:19], v[28:29], v[18:19] op_sel_hi:[0,1]
	v_pk_fma_f32 v[36:37], v[36:37], v[56:57], v[64:65]
	v_pk_fma_f32 v[22:23], v[38:39], v[22:23], v[30:31]
	v_pk_fma_f32 v[16:17], v[34:35], v[16:17], v[24:25]
	v_pk_fma_f32 v[24:25], v[44:45], v[52:53], v[60:61]
	v_pk_mul_f32 v[50:51], v[28:29], v[50:51] op_sel_hi:[0,1]
	v_pk_mul_f32 v[28:29], v[28:29], v[48:49] op_sel_hi:[0,1]
	v_pk_fma_f32 v[32:33], v[32:33], v[54:55], v[62:63]
	v_pk_fma_f32 v[26:27], v[46:47], v[18:19], v[26:27]
	v_cvt_pk_bf16_f32 v18, v36, v37
	v_cvt_pk_bf16_f32 v19, v22, v23
	v_cvt_pk_bf16_f32 v22, v24, v25
	v_pk_fma_f32 v[28:29], v[42:43], v[28:29], v[20:21]
	v_cvt_pk_bf16_f32 v20, v32, v33
	v_cvt_pk_bf16_f32 v21, v16, v17
	v_and_b32_e32 v17, 0xffff0000, v18
	v_and_b32_e32 v33, 0xffff0000, v22
	v_cvt_pk_bf16_f32 v23, v26, v27
	v_lshlrev_b32_e32 v16, 16, v18
	v_lshlrev_b32_e32 v32, 16, v22
	v_mul_f32_e32 v17, v17, v17
	v_mul_f32_e32 v33, v33, v33
	v_pk_fma_f32 v[30:31], v[40:41], v[50:51], v[58:59]
	v_lshlrev_b32_e32 v26, 16, v19
	v_lshlrev_b32_e32 v34, 16, v23
	v_fmac_f32_e32 v17, v16, v16
	v_fmac_f32_e32 v33, v32, v32
	v_cvt_pk_bf16_f32 v24, v30, v31
	v_and_b32_e32 v27, 0xffff0000, v19
	v_and_b32_e32 v35, 0xffff0000, v23
	v_fmac_f32_e32 v17, v26, v26
	v_fmac_f32_e32 v33, v34, v34
	v_cvt_pk_bf16_f32 v25, v28, v29
	v_lshlrev_b32_e32 v28, 16, v20
	v_lshlrev_b32_e32 v36, 16, v24
	v_fmac_f32_e32 v17, v27, v27
	v_fmac_f32_e32 v33, v35, v35
	v_and_b32_e32 v29, 0xffff0000, v20
	v_and_b32_e32 v37, 0xffff0000, v24
	v_fmac_f32_e32 v17, v28, v28
	v_fmac_f32_e32 v33, v36, v36
	v_lshlrev_b32_e32 v30, 16, v21
	v_lshlrev_b32_e32 v38, 16, v25
	v_fmac_f32_e32 v17, v29, v29
	v_fmac_f32_e32 v33, v37, v37
	v_and_b32_e32 v31, 0xffff0000, v21
	v_and_b32_e32 v39, 0xffff0000, v25
	v_fmac_f32_e32 v17, v30, v30
	v_fmac_f32_e32 v33, v38, v38
	v_fmac_f32_e32 v17, v31, v31
	v_fmac_f32_e32 v33, v39, v39
	v_add_f32_e32 v16, v17, v33
	s_nop 1
	v_mov_b32_dpp v17, v16 quad_perm:[1,0,3,2] row_mask:0xf bank_mask:0xf
	global_store_dwordx4 v[8:9], v[18:21], off
	global_store_dwordx4 v[8:9], v[22:25], off offset:1024
	s_waitcnt lgkmcnt(0)
	v_add_f32_e32 v16, v16, v17
	s_nop 1
	v_mov_b32_dpp v17, v16 quad_perm:[2,3,0,1] row_mask:0xf bank_mask:0xf
	s_waitcnt lgkmcnt(0)
	v_add_f32_e32 v16, v16, v17
	s_nop 1
	v_mov_b32_dpp v17, v16 row_half_mirror row_mask:0xf bank_mask:0xf
	s_waitcnt lgkmcnt(0)
	v_add_f32_e32 v16, v16, v17
	s_nop 1
	v_mov_b32_dpp v17, v16 row_mirror row_mask:0xf bank_mask:0xf
	s_waitcnt lgkmcnt(0)
	v_add_f32_e32 v16, v16, v17
	v_mov_b32_e32 v17, v16
	v_mov_b32_e32 v120, v16
	s_nop 1
	v_permlane16_swap_b32_e32 v17, v120
	s_waitcnt lgkmcnt(0)
	v_add_f32_e32 v16, v17, v120
	v_mov_b32_e32 v17, v16
	v_mov_b32_e32 v120, v16
	s_nop 1
	v_permlane32_swap_b32_e32 v17, v120
	s_and_saveexec_b64 s[44:45], vcc
	s_cbranch_execz .LBB0_732
; DI void rw_phase(const float* x, bf16_t* hb, const bf16_t* y, const float* gpost, float* rh, float* fout, bool y_unscaled) {
;     ...
;       if (lane == 0) gst<float>(rh + row, rsqrtf(s2 * (1.0f / 1024.0f) + EPS));
	s_waitcnt lgkmcnt(0)
	v_add_f32_e32 v8, v17, v120
	v_fmamk_f32 v8, v8, 0x3a800000, v204
	v_mul_f32_e32 v9, 0x4b800000, v8
	v_cmp_gt_f32_e64 s[42:43], s33, v8
	s_nop 1
	v_cndmask_b32_e64 v8, v8, v9, s[42:43]
	v_rsq_f32_e32 v16, v8
	v_lshl_add_u64 v[8:9], v[0:1], 2, s[74:75]
	v_mul_f32_e32 v1, 0x45800000, v16
	v_cndmask_b32_e64 v1, v16, v1, s[42:43]
	global_store_dword v[8:9], v1, off
	s_branch .LBB0_732

.LBB0_750:
	s_mov_b64 vcc, s[44:45]
	s_waitcnt vmcnt(1)
	v_and_b32_e32 v17, 0xffff0000, v64
	v_cndmask_b32_sdwa v16, v149, v64, vcc dst_sel:DWORD dst_unused:UNUSED_PAD src0_sel:DWORD src1_sel:WORD_0
	v_cndmask_b32_e64 v17, 0, v17, s[46:47]
	s_mov_b64 vcc, s[48:49]
	v_and_b32_e32 v18, 0xffff0000, v65
	v_or_b32_e32 v16, v17, v16
	v_cndmask_b32_sdwa v17, v149, v65, vcc dst_sel:DWORD dst_unused:UNUSED_PAD src0_sel:DWORD src1_sel:WORD_0
	v_cndmask_b32_e64 v18, 0, v18, s[50:51]
	s_mov_b64 vcc, s[52:53]
	v_and_b32_e32 v19, 0xffff0000, v66
	v_or_b32_e32 v17, v18, v17
	v_cndmask_b32_sdwa v18, v149, v66, vcc dst_sel:DWORD dst_unused:UNUSED_PAD src0_sel:DWORD src1_sel:WORD_0
	v_cndmask_b32_e64 v19, 0, v19, s[54:55]
	s_mov_b64 vcc, s[56:57]
	v_and_b32_e32 v20, 0xffff0000, v67
	v_or_b32_e32 v18, v19, v18
	v_cndmask_b32_sdwa v19, v149, v67, vcc dst_sel:DWORD dst_unused:UNUSED_PAD src0_sel:DWORD src1_sel:WORD_0
	v_cndmask_b32_e64 v20, 0, v20, s[58:59]
	v_add_u32_e32 v155, v104, v105
	v_add_u32_e32 v156, v106, v107
	v_add_u32_e32 v157, v108, v109
	v_or_b32_e32 v19, v20, v19
	ds_write_b128 v155, v[48:51]
	ds_write_b128 v141, v[52:55] offset:17408
	ds_write_b128 v156, v[56:59]
	ds_write_b128 v142, v[60:63] offset:17408
	ds_write_b128 v157, v[68:71] offset:37888
	ds_write_b128 v143, v[16:19] offset:50176
	v_add_u32_e32 v16, 0, v124
	v_add_u32_e32 v154, 0x1e800, v16
	s_and_saveexec_b64 s[72:73], s[42:43]
	ds_write_b32 v154, v133
	s_or_b64 exec, exec, s[72:73]
	s_add_i32 s93, s96, 2
	s_add_i32 s24, s96, 4
	s_add_i32 s83, s97, -2
	s_and_b64 s[72:73], s[76:77], exec
	s_cselect_b32 s24, s24, s83
	s_lshl_b64 s[72:73], s[24:25], 17
	s_add_u32 vcc_lo, s5, s72
	s_addc_u32 vcc_hi, s80, s73
	s_add_u32 s94, s81, s72
	s_waitcnt lgkmcnt(0)
	s_barrier
	s_addc_u32 s95, s82, s73
	v_lshl_add_u64 v[16:17], vcc, 0, v[148:149]
	global_load_dwordx4 v[48:51], v[16:17], off
	v_lshl_add_u64 v[16:17], s[94:95], 0, v[148:149]
	global_load_dwordx4 v[52:55], v[16:17], off
	v_lshl_add_u64 v[16:17], vcc, 0, v[102:103]
	global_load_dwordx4 v[56:59], v[16:17], off
	v_lshl_add_u64 v[16:17], s[94:95], 0, v[102:103]
	global_load_dwordx4 v[60:63], v[16:17], off
	v_lshl_add_u64 v[16:17], v[112:113], 0, s[72:73]
	s_lshl_b64 s[72:73], s[24:25], 15
	s_add_i32 s62, s96, 3
	s_add_i32 s63, s97, -1
	global_load_dwordx4 v[68:71], v[16:17], off
	v_lshl_add_u64 v[16:17], v[114:115], 0, s[72:73]
	s_and_b64 s[72:73], s[76:77], exec
	s_cselect_b32 s94, s62, s63
	s_lshl_b32 s72, s94, 11
	s_mov_b32 s73, s25
	global_load_dwordx4 v[64:67], v[16:17], off
	v_lshl_add_u64 v[16:17], v[116:117], 0, s[72:73]
	global_load_dword v133, v[16:17], off
	ds_read_b64_tr_b16 v[160:161], v99 offset:0
	ds_read_b64_tr_b16 v[162:163], v99 offset:0x300
	ds_read_b64_tr_b16 v[164:165], v99 offset:0xc00
	ds_read_b64_tr_b16 v[166:167], v99 offset:0xf00
	ds_read_b64_tr_b16 v[168:169], v99 offset:0x1800
	ds_read_b64_tr_b16 v[170:171], v99 offset:0x1b00
	ds_read_b64_tr_b16 v[172:173], v99 offset:0x2400
	ds_read_b64_tr_b16 v[174:175], v99 offset:0x2700
	ds_read_b128 v[16:19], v150 offset:50176
	ds_read_b128 v[20:23], v150 offset:54784
	ds_read_b64_tr_b16 v[24:25], v120
	ds_read_b64_tr_b16 v[26:27], v120 offset:0x300
	v_add_u32_e32 v153, 0x2000, v151
	ds_read2_b64 v[176:179], v151 offset1:2
	ds_read2_b64 v[180:183], v153 offset0:64 offset1:66
	s_waitcnt lgkmcnt(0)
	ds_read2_b64 v[184:187], v151 offset0:4 offset1:6
	ds_read2_b64 v[188:191], v153 offset0:68 offset1:70
	s_waitcnt lgkmcnt(5)
	v_mfma_f32_32x32x16_bf16 v[32:47], v[16:19], v[24:27], 0
	s_waitcnt lgkmcnt(4)
	v_mfma_f32_32x32x16_bf16 v[16:31], v[20:23], v[24:27], 0
	v_cvt_pk_bf16_f32 v192, v0, v1
	v_cvt_pk_bf16_f32 v193, v2, v3
	v_cvt_pk_bf16_f32 v194, v4, v5
	v_cvt_pk_bf16_f32 v195, v6, v7
	s_waitcnt lgkmcnt(2)
	s_nop 0
	v_mfma_f32_32x32x16_bf16 v[16:31], v[180:183], v[192:195], v[16:31]
	v_mfma_f32_32x32x16_bf16 v[32:47], v[176:179], v[192:195], v[32:47]
	v_cvt_pk_bf16_f32 v176, v8, v9
	v_cvt_pk_bf16_f32 v177, v10, v11
	v_cvt_pk_bf16_f32 v178, v12, v13
	v_cvt_pk_bf16_f32 v179, v14, v15
	s_waitcnt lgkmcnt(0)
	s_nop 0
	v_mfma_f32_32x32x16_bf16 v[16:31], v[188:191], v[176:179], v[16:31]
	v_mfma_f32_32x32x16_bf16 v[32:47], v[184:187], v[176:179], v[32:47]
	s_nop 11
	ds_write2st64_b32 v111, v32, v33 offset0:232 offset1:233
	ds_write2st64_b32 v111, v34, v35 offset0:234 offset1:235
	ds_write2st64_b32 v111, v36, v37 offset0:240 offset1:241
	ds_write2st64_b32 v111, v38, v39 offset0:242 offset1:243
	ds_write2st64_b32 v111, v40, v41 offset0:248 offset1:249
	ds_write2st64_b32 v111, v42, v43 offset0:250 offset1:251
	ds_write2st64_b32 v121, v44, v45 offset0:24 offset1:25
	ds_write2st64_b32 v121, v46, v47 offset0:26 offset1:27
	ds_write2st64_b32 v121, v16, v17 offset0:32 offset1:33
	ds_write2st64_b32 v121, v18, v19 offset0:34 offset1:35
	ds_write2st64_b32 v121, v20, v21 offset0:40 offset1:41
	ds_write2st64_b32 v121, v22, v23 offset0:42 offset1:43
	ds_write2st64_b32 v121, v24, v25 offset0:48 offset1:49
	ds_write2st64_b32 v121, v26, v27 offset0:50 offset1:51
	ds_write2st64_b32 v121, v28, v29 offset0:56 offset1:57
	ds_write2st64_b32 v121, v30, v31 offset0:58 offset1:59
	ds_read_b64_tr_b16 v[20:21], v139 offset:0
	ds_read_b64_tr_b16 v[22:23], v139 offset:0x500
	ds_read_b64_tr_b16 v[16:17], v139 offset:0x1400
	ds_read_b64_tr_b16 v[18:19], v139 offset:0x1900
	ds_read_b64_tr_b16 v[36:37], v139 offset:0x2800
	ds_read_b64_tr_b16 v[38:39], v139 offset:0x2d00
	ds_read_b64_tr_b16 v[32:33], v139 offset:0x3c00
	ds_read_b64_tr_b16 v[34:35], v139 offset:0x4100
	s_and_b64 s[72:73], s[76:77], exec
	s_waitcnt lgkmcnt(0)
	s_cselect_b32 s62, s93, s97
	v_mfma_f32_32x32x16_bf16 v[0:15], v[20:23], v[160:163], v[0:15]
	s_lshl_b32 s72, s62, 17
	s_mov_b32 s73, s25
	s_mov_b64 vcc, s[44:45]
	v_mfma_f32_32x32x16_bf16 v[0:15], v[16:19], v[164:167], v[0:15]
	ds_read_b128 v[28:31], v152
	ds_read_b128 v[24:27], v152 offset:32
	ds_read_b128 v[20:23], v152 offset:64
	ds_read_b128 v[16:19], v152 offset:96
	s_waitcnt lgkmcnt(0)
	s_barrier
; DI unsigned pk(float lo, float hi) { f32x2 v = {lo, hi}; bf2_t b = __builtin_convertvector(v, bf2_t); return __builtin_bit_cast(unsigned, b); }
; DI float bflo(unsigned w) { return __uint_as_float(w << 16); }
; DI float bfhi(unsigned w) { return __uint_as_float(w & 0xffff0000u); }
; template <int DK>
; DI void scan_phase(const ScanArgs& a, char* lds, const XcdBarrier& xb) {
;     ...
;       *(u32x4*)(lds + row * QS + ch * 16) = R.q[i];
;       *(u32x4*)(lds + OFF_K + row * KS + ch * 16) = R.k[i];
;     }
;     *(u32x4*)(lds + OFF_V + vrow * VS + vch * 16) = ret ? scale8(R.v, ksc[vrow]) : R.v;
;     {
;       u32x4 w = R.p; unsigned ww[4] = {w.x, w.y, w.z, w.w};
; #pragma unroll
;       for (int e = 0; e < 4; ++e) {
;         const int s0 = vch * 8 + 2 * e, s1 = s0 + 1;
;         const bool k0 = dir ? (s0 > vrow) : (s0 <= vrow), k1 = dir ? (s1 > vrow) : (s1 <= vrow);
;         ww[e] = (k0 ? (ww[e] & 0xffffu) : 0u) | (k1 ? (ww[e] & 0xffff0000u) : 0u);
;       }
;       *(u32x4*)(lds + OFF_PP + vrow * PS + vch * 16) = (u32x4){ww[0], ww[1], ww[2], ww[3]};
;     }
;     if (!ret) { if (tid < DK) *(float*)(lds + OFF_EE + tid * 4) = enext; }
;     ...
;     {
;       float sum[8];
; #pragma unroll
;       for (int e = 0; e < 8; ++e) sum[e] = 0.f;
; #pragma unroll
;       for (int w4 = 0; w4 < 4; ++w4) {
;         const float* op = (const float*)(lds + OFF_O + ((w4 * 64 + vrow) * 64 + vch * 8) * 4);
;         const f32x4 x0 = *(const f32x4*)op, x1 = *(const f32x4*)(op + 4);
;         sum[0] += x0[0]; sum[1] += x0[1]; sum[2] += x0[2]; sum[3] += x0[3]; sum[4] += x1[0]; sum[5] += x1[1]; sum[6] += x1[2]; sum[7] += x1[3];
;       }
;       if (ret) {
;         const float myqs = qsc[vrow];
; #pragma unroll
;         for (int e = 0; e < 8; ++e) sum[e] *= myqs;
;       }
;       if (second) {
;         sum[0] += bflo(ocur.x); sum[1] += bfhi(ocur.x); sum[2] += bflo(ocur.y); sum[3] += bfhi(ocur.y);
;         sum[4] += bflo(ocur.z); sum[5] += bfhi(ocur.z); sum[6] += bflo(ocur.w); sum[7] += bfhi(ocur.w);
;       }
;       u32x4 w; w.x = pk(sum[0], sum[1]); w.y = pk(sum[2], sum[3]); w.z = pk(sum[4], sum[5]); w.w = pk(sum[6], sum[7]);
;       gst<u32x4>((char*)og + (size_t)n * (64 * LDO * 2) + ooff, w);
	v_mfma_f32_32x32x16_bf16 v[0:15], v[36:39], v[168:171], v[0:15]
	ds_read_b128 v[36:39], v125 offset:59392
	ds_read_b128 v[40:43], v125 offset:59408
	ds_read_b128 v[44:47], v140 offset:16384
	ds_read_b128 v[160:163], v140 offset:16400
	s_waitcnt lgkmcnt(3)
	v_pk_add_f32 v[36:37], v[36:37], 0 op_sel_hi:[1,0]
	s_waitcnt lgkmcnt(1)
	v_pk_add_f32 v[36:37], v[36:37], v[44:45]
	v_mfma_f32_32x32x16_bf16 v[0:15], v[32:35], v[172:175], v[0:15]
	ds_read_b128 v[32:35], v140 offset:32768
	ds_read_b128 v[164:167], v140 offset:32784
	ds_read_b128 v[168:171], v140 offset:49152
	ds_read_b128 v[172:175], v140 offset:49168
	s_waitcnt lgkmcnt(3)
	v_pk_add_f32 v[32:33], v[36:37], v[32:33]
	v_pk_add_f32 v[36:37], v[38:39], 0 op_sel_hi:[1,0]
	v_pk_add_f32 v[38:39], v[42:43], 0 op_sel_hi:[1,0]
	v_pk_add_f32 v[36:37], v[36:37], v[46:47]
	v_pk_add_f32 v[38:39], v[38:39], v[162:163]
	v_pk_add_f32 v[34:35], v[36:37], v[34:35]
	v_pk_add_f32 v[36:37], v[40:41], 0 op_sel_hi:[1,0]
	s_waitcnt lgkmcnt(2)
	v_pk_add_f32 v[38:39], v[38:39], v[166:167]
	v_pk_add_f32 v[36:37], v[36:37], v[160:161]
	s_waitcnt lgkmcnt(1)
	v_pk_add_f32 v[32:33], v[32:33], v[168:169]
	v_pk_add_f32 v[36:37], v[36:37], v[164:165]
	v_pk_add_f32 v[34:35], v[34:35], v[170:171]
	s_waitcnt lgkmcnt(0)
	v_pk_add_f32 v[36:37], v[36:37], v[172:173]
	v_pk_add_f32 v[38:39], v[38:39], v[174:175]
	v_cvt_pk_bf16_f32 v32, v32, v33
	v_cvt_pk_bf16_f32 v33, v34, v35
	v_cvt_pk_bf16_f32 v34, v36, v37
	v_cvt_pk_bf16_f32 v35, v38, v39
	v_lshl_add_u64 v[36:37], v[118:119], 0, s[72:73]
	global_store_dwordx4 v[36:37], v[32:35], off
	v_and_b32_e32 v36, 0xffff0000, v83
	v_cndmask_b32_e64 v36, 0, v36, s[58:59]
	v_and_b32_e32 v33, 0xffff0000, v80
	v_cndmask_b32_sdwa v32, v149, v80, vcc dst_sel:DWORD dst_unused:UNUSED_PAD src0_sel:DWORD src1_sel:WORD_0
	v_cndmask_b32_e64 v33, 0, v33, s[46:47]
	s_mov_b64 vcc, s[48:49]
	v_and_b32_e32 v34, 0xffff0000, v81
	v_or_b32_e32 v32, v33, v32
	v_cndmask_b32_sdwa v33, v149, v81, vcc dst_sel:DWORD dst_unused:UNUSED_PAD src0_sel:DWORD src1_sel:WORD_0
	v_cndmask_b32_e64 v34, 0, v34, s[50:51]
	s_mov_b64 vcc, s[52:53]
	v_and_b32_e32 v35, 0xffff0000, v82
	v_or_b32_e32 v33, v34, v33
	v_cndmask_b32_sdwa v34, v149, v82, vcc dst_sel:DWORD dst_unused:UNUSED_PAD src0_sel:DWORD src1_sel:WORD_0
	v_cndmask_b32_e64 v35, 0, v35, s[54:55]
	s_mov_b64 vcc, s[56:57]
	v_or_b32_e32 v34, v35, v34
	v_cndmask_b32_sdwa v35, v149, v83, vcc dst_sel:DWORD dst_unused:UNUSED_PAD src0_sel:DWORD src1_sel:WORD_0
	v_or_b32_e32 v35, v36, v35
	ds_write_b128 v155, v[72:75]
	ds_write_b128 v141, v[76:79] offset:17408
	ds_write_b128 v156, v[84:87]
	ds_write_b128 v142, v[88:91] offset:17408
	ds_write_b128 v157, v[92:95] offset:37888
	ds_write_b128 v143, v[32:35] offset:50176
	s_and_saveexec_b64 s[72:73], s[42:43]
	s_cbranch_execz .LBB0_754
	s_waitcnt vmcnt(1)
	ds_write_b32 v154, v133

; template <int DK>
; DI void scan_phase(const ScanArgs& a, char* lds, const XcdBarrier& xb) {
;     ...
;     u32x4 ocur = {0u, 0u, 0u, 0u};
;     if (second) ocur = gld<u32x4>((const char*)og + (size_t)n * (64 * LDO * 2) + ooff);
; #pragma unroll
;     for (int i = 0; i < NQ; ++i) {
;       const int c = tid + 512 * i, row = c / (DK / 8), ch = c % (DK / 8);
;       *(u32x4*)(lds + row * QS + ch * 16) = R.q[i];
;       *(u32x4*)(lds + OFF_K + row * KS + ch * 16) = R.k[i];
;     }
;     *(u32x4*)(lds + OFF_V + vrow * VS + vch * 16) = ret ? scale8(R.v, ksc[vrow]) : R.v;
;     {
;       u32x4 w = R.p; unsigned ww[4] = {w.x, w.y, w.z, w.w};
; #pragma unroll
;       for (int e = 0; e < 4; ++e) {
;         const int s0 = vch * 8 + 2 * e, s1 = s0 + 1;
;         const bool k0 = dir ? (s0 > vrow) : (s0 <= vrow), k1 = dir ? (s1 > vrow) : (s1 <= vrow);
;         ww[e] = (k0 ? (ww[e] & 0xffffu) : 0u) | (k1 ? (ww[e] & 0xffff0000u) : 0u);
;       }
;       *(u32x4*)(lds + OFF_PP + vrow * PS + vch * 16) = (u32x4){ww[0], ww[1], ww[2], ww[3]};
;     }
;     if (!ret) { if (tid < DK) *(float*)(lds + OFF_EE + tid * 4) = enext; }
;     lds_barrier();
;     issue(R, chunk_of(step + DEPTH));
;     issue1(chunk_of(step + 1));
;     bf16x8 vf[4];
;     bf16x8 qa[2][2];
;     auto ldq = [&](int jk, bf16x8 (&dst)[2]) {
;       const int j = jk >> 1, ks = jk & 1;
; #pragma unroll
;       for (int tt = 0; tt < 2; ++tt) {
;         const char* qp = lds + (32 * tt + r) * QS + (wr * RW + 32 * j + 16 * ks + 4 * hh) * 2;
;         dst[tt] = cat8(*(const s16x4*)qp, *(const s16x4*)(qp + 16));
;       }
;     };
;     f32x16 oacc[2];
;     const f32x16 zero16 = {0.f, 0.f, 0.f, 0.f, 0.f, 0.f, 0.f, 0.f, 0.f, 0.f, 0.f, 0.f, 0.f, 0.f, 0.f, 0.f};
;     {
;       s16x4 t8[8];
;       tr_issue8<4 * VS, 16 * VS>(ldsb + OFF_V + (8 * hh + qd) * VS + (32 * wc + 16 * g1 + 4 * pp) * 2, t8);
;       const bf16x8 pa0 = *(const bf16x8*)(lds + OFF_PP + r * PS + (16 * wr + 8 * hh) * 2);
;       const bf16x8 pa1 = *(const bf16x8*)(lds + OFF_PP + (32 + r) * PS + (16 * wr + 8 * hh) * 2);
;       s16x4 tv[2];
;       tr_issue2<4 * VS>(ldsb + OFF_V + (16 * wr + 8 * hh + qd) * VS + (32 * wc + 16 * g1 + 4 * pp) * 2, tv);
;       ldq(0, qa[0]);
;       tr_wait10(t8, tv);
; #pragma unroll
;       for (int s4 = 0; s4 < 4; ++s4) vf[s4] = cat8(t8[2 * s4], t8[2 * s4 + 1]);
;       const bf16x8 vpv = cat8(tv[0], tv[1]);
.LBB0_804:
	s_add_i32 s94, s93, -1
	s_add_i32 s24, s83, 1
	s_and_b64 s[62:63], s[76:77], exec
	s_cselect_b32 s24, s94, s24
	s_lshl_b64 s[62:63], s[24:25], 17
	v_lshl_add_u64 v[122:123], v[112:113], 0, s[62:63]
	global_load_dwordx4 v[96:99], v[122:123], off
	s_waitcnt vmcnt(2)
	v_and_b32_e32 v16, 0xffff, v64
	v_and_b32_e32 v17, 0xffff0000, v64
	v_cndmask_b32_e64 v16, 0, v16, s[42:43]
	v_cndmask_b32_e64 v17, 0, v17, s[44:45]
	v_or_b32_e32 v16, v17, v16
	v_and_b32_e32 v17, 0xffff, v65
	v_and_b32_e32 v18, 0xffff0000, v65
	v_cndmask_b32_e64 v17, 0, v17, s[46:47]
	v_cndmask_b32_e64 v18, 0, v18, s[48:49]
	v_or_b32_e32 v17, v18, v17
	v_and_b32_e32 v18, 0xffff, v66
	v_and_b32_e32 v19, 0xffff0000, v66
	v_cndmask_b32_e64 v18, 0, v18, s[50:51]
	v_cndmask_b32_e64 v19, 0, v19, s[52:53]
	v_or_b32_e32 v18, v19, v18
	v_and_b32_e32 v19, 0xffff, v67
	v_and_b32_e32 v20, 0xffff0000, v67
	v_cndmask_b32_e64 v19, 0, v19, s[54:55]
	v_cndmask_b32_e64 v20, 0, v20, s[56:57]
	v_add_u32_e32 v142, v104, v105
	v_add_u32_e32 v143, v106, v107
	v_add_u32_e32 v150, v108, v109
	v_or_b32_e32 v19, v20, v19
	ds_write_b128 v142, v[48:51]
	ds_write_b128 v127, v[52:55] offset:17408
	ds_write_b128 v143, v[56:59]
	ds_write_b128 v131, v[60:63] offset:17408
	ds_write_b128 v150, v[68:71] offset:37888
	ds_write_b128 v134, v[16:19] offset:50176
	v_add_u32_e32 v16, 0, v124
	v_mov_b64_e32 v[120:121], 0
	v_add_u32_e32 v141, 0x1e800, v16
	s_and_saveexec_b64 s[70:71], s[58:59]
	v_mov_b64_e32 v[120:121], v[100:101]
	ds_write_b32 v141, v133
	s_or_b64 exec, exec, s[70:71]
	s_min_u32 s62, s94, 0x7d
	s_add_i32 s70, s62, 2
	s_sub_i32 s71, 0x7d, s62
	s_and_b64 s[62:63], s[76:77], exec
	s_cselect_b32 s95, s70, s71
	s_lshl_b32 s62, s95, 17
	s_add_u32 s70, s5, s62
	s_addc_u32 s71, s80, 0
	s_add_u32 s72, s81, s62
	s_waitcnt lgkmcnt(0)
	s_barrier
	s_addc_u32 s73, s82, 0
	v_lshl_add_u64 v[16:17], s[70:71], 0, v[148:149]
	global_load_dwordx4 v[48:51], v[16:17], off
	v_lshl_add_u64 v[16:17], s[72:73], 0, v[148:149]
	global_load_dwordx4 v[52:55], v[16:17], off
	v_lshl_add_u64 v[16:17], s[70:71], 0, v[102:103]
	s_mov_b32 s63, s25
	global_load_dwordx4 v[56:59], v[16:17], off
	v_lshl_add_u64 v[16:17], s[72:73], 0, v[102:103]
	global_load_dwordx4 v[60:63], v[16:17], off
	v_lshl_add_u64 v[16:17], v[110:111], 0, s[62:63]
	s_lshl_b32 s62, s95, 15
	global_load_dwordx4 v[68:71], v[16:17], off
	v_lshl_add_u64 v[16:17], v[114:115], 0, s[62:63]
	s_and_b64 s[62:63], s[76:77], exec
	s_cselect_b32 s70, s93, s83
	s_lshl_b32 s62, s70, 11
	s_add_u32 s62, s86, s62
	s_addc_u32 s63, s87, 0
	global_load_dwordx4 v[64:67], v[16:17], off
	v_lshl_add_u64 v[16:17], v[120:121], 2, s[62:63]
	global_load_dword v133, v[16:17], off
	ds_read_b64_tr_b16 v[168:169], v132 offset:0
	ds_read_b64_tr_b16 v[170:171], v132 offset:0x300
	ds_read_b64_tr_b16 v[164:165], v132 offset:0xc00
	ds_read_b64_tr_b16 v[166:167], v132 offset:0xf00
	ds_read_b64_tr_b16 v[160:161], v132 offset:0x1800
	ds_read_b64_tr_b16 v[162:163], v132 offset:0x1b00
	ds_read_b64_tr_b16 v[152:153], v132 offset:0x2400
	ds_read_b64_tr_b16 v[154:155], v132 offset:0x2700
	ds_read_b128 v[16:19], v126 offset:50176
	ds_read_b128 v[20:23], v126 offset:54784
	ds_read_b64_tr_b16 v[24:25], v116
	ds_read_b64_tr_b16 v[26:27], v116 offset:0x300
	v_add_u32_e32 v137, 0x2000, v135
	ds_read2_b64 v[172:175], v135 offset1:2
	ds_read2_b64 v[176:179], v137 offset0:64 offset1:66
	s_waitcnt lgkmcnt(0)
	ds_read2_b64 v[180:183], v135 offset0:4 offset1:6
	ds_read2_b64 v[184:187], v137 offset0:68 offset1:70
	s_waitcnt lgkmcnt(5)
	v_mfma_f32_32x32x16_bf16 v[32:47], v[16:19], v[24:27], 0
	s_waitcnt lgkmcnt(4)
	v_mfma_f32_32x32x16_bf16 v[16:31], v[20:23], v[24:27], 0
	v_cvt_pk_bf16_f32 v188, v0, v1
	v_cvt_pk_bf16_f32 v189, v2, v3
	v_cvt_pk_bf16_f32 v190, v4, v5
	v_cvt_pk_bf16_f32 v191, v6, v7
	s_waitcnt lgkmcnt(3)
	s_nop 0
	v_mfma_f32_32x32x16_bf16 v[32:47], v[172:175], v[188:191], v[32:47]
	s_waitcnt lgkmcnt(2)
	v_mfma_f32_32x32x16_bf16 v[16:31], v[176:179], v[188:191], v[16:31]
	v_cvt_pk_bf16_f32 v172, v8, v9
	v_cvt_pk_bf16_f32 v173, v10, v11
	v_cvt_pk_bf16_f32 v174, v12, v13
	v_cvt_pk_bf16_f32 v175, v14, v15
	s_waitcnt lgkmcnt(1)
	s_nop 0
	v_mfma_f32_32x32x16_bf16 v[32:47], v[180:183], v[172:175], v[32:47]
	s_waitcnt lgkmcnt(0)
	v_mfma_f32_32x32x16_bf16 v[16:31], v[184:187], v[172:175], v[16:31]
	s_nop 9
	ds_write2st64_b32 v117, v32, v33 offset0:232 offset1:233
	ds_write2st64_b32 v117, v34, v35 offset0:234 offset1:235
	ds_write2st64_b32 v117, v36, v37 offset0:240 offset1:241
	ds_write2st64_b32 v117, v38, v39 offset0:242 offset1:243
	ds_write2st64_b32 v117, v40, v41 offset0:248 offset1:249
	ds_write2st64_b32 v117, v42, v43 offset0:250 offset1:251
	ds_write2st64_b32 v129, v44, v45 offset0:24 offset1:25
	ds_write2st64_b32 v129, v46, v47 offset0:26 offset1:27
	ds_write2st64_b32 v129, v16, v17 offset0:32 offset1:33
	ds_write2st64_b32 v129, v18, v19 offset0:34 offset1:35
	ds_write2st64_b32 v129, v20, v21 offset0:40 offset1:41
	ds_write2st64_b32 v129, v22, v23 offset0:42 offset1:43
	ds_write2st64_b32 v129, v24, v25 offset0:48 offset1:49
	ds_write2st64_b32 v129, v26, v27 offset0:50 offset1:51
	ds_write2st64_b32 v129, v28, v29 offset0:56 offset1:57
	ds_write2st64_b32 v129, v30, v31 offset0:58 offset1:59
	ds_read_b64_tr_b16 v[28:29], v130 offset:0
	ds_read_b64_tr_b16 v[30:31], v130 offset:0x500
	ds_read_b64_tr_b16 v[24:25], v130 offset:0x1400
	ds_read_b64_tr_b16 v[26:27], v130 offset:0x1900
	ds_read_b64_tr_b16 v[20:21], v130 offset:0x2800
	ds_read_b64_tr_b16 v[22:23], v130 offset:0x2d00
	ds_read_b64_tr_b16 v[16:17], v130 offset:0x3c00
	ds_read_b64_tr_b16 v[18:19], v130 offset:0x4100
	v_cmp_lt_i32_e32 vcc, v209, v208
	s_waitcnt lgkmcnt(0)
	s_nop 0
	v_mfma_f32_32x32x16_bf16 v[0:15], v[28:31], v[168:171], v[0:15]
	v_mfma_f32_32x32x16_bf16 v[0:15], v[24:27], v[164:167], v[0:15]
	v_mfma_f32_32x32x16_bf16 v[0:15], v[20:23], v[160:163], v[0:15]
	v_mfma_f32_32x32x16_bf16 v[0:15], v[16:19], v[152:155], v[0:15]
	ds_read_b128 v[28:31], v136
	ds_read_b128 v[24:27], v136 offset:32
	ds_read_b128 v[20:23], v136 offset:64
	ds_read_b128 v[16:19], v136 offset:96
	s_waitcnt lgkmcnt(0)
	s_barrier
; DI unsigned pk(float lo, float hi) { f32x2 v = {lo, hi}; bf2_t b = __builtin_convertvector(v, bf2_t); return __builtin_bit_cast(unsigned, b); }
; DI float bflo(unsigned w) { return __uint_as_float(w << 16); }
; DI float bfhi(unsigned w) { return __uint_as_float(w & 0xffff0000u); }
; template <int DK>
; DI void scan_phase(const ScanArgs& a, char* lds, const XcdBarrier& xb) {
;     ...
;     {
;       float sum[8];
; #pragma unroll
;       for (int e = 0; e < 8; ++e) sum[e] = 0.f;
; #pragma unroll
;       for (int w4 = 0; w4 < 4; ++w4) {
;         const float* op = (const float*)(lds + OFF_O + ((w4 * 64 + vrow) * 64 + vch * 8) * 4);
;         const f32x4 x0 = *(const f32x4*)op, x1 = *(const f32x4*)(op + 4);
;         sum[0] += x0[0]; sum[1] += x0[1]; sum[2] += x0[2]; sum[3] += x0[3]; sum[4] += x1[0]; sum[5] += x1[1]; sum[6] += x1[2]; sum[7] += x1[3];
;       }
;       if (ret) {
;         const float myqs = qsc[vrow];
; #pragma unroll
;         for (int e = 0; e < 8; ++e) sum[e] *= myqs;
;       }
;       if (second) {
;         sum[0] += bflo(ocur.x); sum[1] += bfhi(ocur.x); sum[2] += bflo(ocur.y); sum[3] += bfhi(ocur.y);
;         sum[4] += bflo(ocur.z); sum[5] += bfhi(ocur.z); sum[6] += bflo(ocur.w); sum[7] += bfhi(ocur.w);
;       }
;       u32x4 w; w.x = pk(sum[0], sum[1]); w.y = pk(sum[2], sum[3]); w.z = pk(sum[4], sum[5]); w.w = pk(sum[6], sum[7]);
;       gst<u32x4>((char*)og + (size_t)n * (64 * LDO * 2) + ooff, w);
;       if (second) {
;         float q2 = bflo(w.x) * bflo(w.x) + bfhi(w.x) * bfhi(w.x) + bflo(w.y) * bflo(w.y) + bfhi(w.y) * bfhi(w.y) +
;                    bflo(w.z) * bflo(w.z) + bfhi(w.z) * bfhi(w.z) + bflo(w.w) * bflo(w.w) + bfhi(w.w) * bfhi(w.w);
;         q2 += __shfl_xor(q2, 1); q2 += __shfl_xor(q2, 2); q2 += __shfl_xor(q2, 4);
;         if (vch == 0) gst<float>(a.ssp + ((size_t)b * L_ + (size_t)n * 64 + vrow) * 32 + h * 8 + slice, q2);
	ds_read_b128 v[32:35], v125 offset:59392
	ds_read_b128 v[36:39], v125 offset:59408
	ds_read_b128 v[40:43], v128 offset:16384
	ds_read_b128 v[44:47], v128 offset:16400
	ds_read_b128 v[152:155], v128 offset:32768
	ds_read_b128 v[160:163], v128 offset:32784
	ds_read_b128 v[164:167], v128 offset:49152
	ds_read_b128 v[168:171], v128 offset:49168
	s_waitcnt lgkmcnt(7)
	v_pk_add_f32 v[32:33], v[32:33], 0 op_sel_hi:[1,0]
	v_pk_add_f32 v[34:35], v[34:35], 0 op_sel_hi:[1,0]
	s_waitcnt lgkmcnt(5)
	v_pk_add_f32 v[32:33], v[32:33], v[40:41]
	v_pk_add_f32 v[34:35], v[34:35], v[42:43]
	s_waitcnt lgkmcnt(3)
	v_pk_add_f32 v[32:33], v[32:33], v[152:153]
	v_pk_add_f32 v[36:37], v[36:37], 0 op_sel_hi:[1,0]
	s_waitcnt lgkmcnt(1)
	v_pk_add_f32 v[32:33], v[32:33], v[164:165]
	s_waitcnt vmcnt(7)
	v_lshlrev_b32_e32 v40, 16, v96
	v_and_b32_e32 v41, 0xffff0000, v96
	v_pk_add_f32 v[34:35], v[34:35], v[154:155]
	v_pk_add_f32 v[36:37], v[36:37], v[44:45]
	v_pk_add_f32 v[38:39], v[38:39], 0 op_sel_hi:[1,0]
	v_pk_add_f32 v[32:33], v[32:33], v[40:41]
	v_pk_add_f32 v[34:35], v[34:35], v[166:167]
	v_lshlrev_b32_e32 v40, 16, v97
	v_and_b32_e32 v41, 0xffff0000, v97
	v_pk_add_f32 v[36:37], v[36:37], v[160:161]
	v_pk_add_f32 v[38:39], v[38:39], v[46:47]
	v_pk_add_f32 v[34:35], v[34:35], v[40:41]
	s_waitcnt lgkmcnt(0)
	v_pk_add_f32 v[36:37], v[36:37], v[168:169]
	v_lshlrev_b32_e32 v40, 16, v98
	v_and_b32_e32 v41, 0xffff0000, v98
	v_pk_add_f32 v[38:39], v[38:39], v[162:163]
	v_pk_add_f32 v[36:37], v[36:37], v[40:41]
	v_pk_add_f32 v[38:39], v[38:39], v[170:171]
	v_lshlrev_b32_e32 v40, 16, v99
	v_and_b32_e32 v41, 0xffff0000, v99
	v_pk_add_f32 v[38:39], v[38:39], v[40:41]
	v_cvt_pk_bf16_f32 v32, v32, v33
	v_cvt_pk_bf16_f32 v33, v34, v35
	v_cvt_pk_bf16_f32 v34, v36, v37
	v_cvt_pk_bf16_f32 v35, v38, v39
	global_store_dwordx4 v[122:123], v[32:35], off
	v_lshlrev_b32_e32 v36, 16, v32
	s_nop 0
	v_and_b32_e32 v32, 0xffff0000, v32
	v_mul_f32_e32 v32, v32, v32
	v_fmac_f32_e32 v32, v36, v36
	v_lshlrev_b32_e32 v36, 16, v33
	v_fmac_f32_e32 v32, v36, v36
	v_and_b32_e32 v33, 0xffff0000, v33
	v_fmac_f32_e32 v32, v33, v33
	v_lshlrev_b32_e32 v33, 16, v34
	v_fmac_f32_e32 v32, v33, v33
	v_and_b32_e32 v33, 0xffff0000, v34
	v_fmac_f32_e32 v32, v33, v33
	v_lshlrev_b32_e32 v33, 16, v35
	v_fmac_f32_e32 v32, v33, v33
	v_and_b32_e32 v33, 0xffff0000, v35
	v_fmac_f32_e32 v32, v33, v33
	v_cndmask_b32_e32 v33, v206, v209, vcc
	v_lshlrev_b32_e32 v138, 2, v33
	s_nop 1
	v_mov_b32_dpp v33, v32 quad_perm:[1,0,3,2] row_mask:0xf bank_mask:0xf
	v_cmp_lt_i32_e32 vcc, v210, v208
	s_waitcnt lgkmcnt(0)
	v_add_f32_e32 v32, v32, v33
	v_cndmask_b32_e32 v33, v206, v210, vcc
	v_lshlrev_b32_e32 v139, 2, v33
	s_nop 1
	v_mov_b32_dpp v33, v32 quad_perm:[2,3,0,1] row_mask:0xf bank_mask:0xf
	v_cmp_lt_i32_e32 vcc, v211, v208
	s_waitcnt lgkmcnt(0)
	v_add_f32_e32 v32, v32, v33
	v_cndmask_b32_e32 v33, v206, v211, vcc
	v_lshlrev_b32_e32 v140, 2, v33
	s_nop 1
	v_mov_b32_dpp v33, v32 row_half_mirror row_mask:0xf bank_mask:0xf
	s_and_saveexec_b64 s[72:73], s[60:61]
	s_cbranch_execz .LBB0_808
	s_lshl_b64 s[62:63], s[24:25], 13
	s_waitcnt lgkmcnt(0)
	v_add_f32_e32 v34, v32, v33
	v_lshl_add_u64 v[32:33], v[118:119], 0, s[62:63]
	global_store_dword v[32:33], v34, off

; template <int DK>
; DI void scan_phase(const ScanArgs& a, char* lds, const XcdBarrier& xb) {
;     ...
;     bf16x8 vf[4];
;     bf16x8 qa[2][2];
;     auto ldq = [&](int jk, bf16x8 (&dst)[2]) {
;       const int j = jk >> 1, ks = jk & 1;
; #pragma unroll
;       for (int tt = 0; tt < 2; ++tt) {
;         const char* qp = lds + (32 * tt + r) * QS + (wr * RW + 32 * j + 16 * ks + 4 * hh) * 2;
;         dst[tt] = cat8(*(const s16x4*)qp, *(const s16x4*)(qp + 16));
;       }
;     };
;     f32x16 oacc[2];
;     const f32x16 zero16 = {0.f, 0.f, 0.f, 0.f, 0.f, 0.f, 0.f, 0.f, 0.f, 0.f, 0.f, 0.f, 0.f, 0.f, 0.f, 0.f};
;     {
;       s16x4 t8[8];
;       tr_issue8<4 * VS, 16 * VS>(ldsb + OFF_V + (8 * hh + qd) * VS + (32 * wc + 16 * g1 + 4 * pp) * 2, t8);
;       const bf16x8 pa0 = *(const bf16x8*)(lds + OFF_PP + r * PS + (16 * wr + 8 * hh) * 2);
;       const bf16x8 pa1 = *(const bf16x8*)(lds + OFF_PP + (32 + r) * PS + (16 * wr + 8 * hh) * 2);
;       s16x4 tv[2];
;       tr_issue2<4 * VS>(ldsb + OFF_V + (16 * wr + 8 * hh + qd) * VS + (32 * wc + 16 * g1 + 4 * pp) * 2, tv);
;       ldq(0, qa[0]);
;       tr_wait10(t8, tv);
; #pragma unroll
;       for (int s4 = 0; s4 < 4; ++s4) vf[s4] = cat8(t8[2 * s4], t8[2 * s4 + 1]);
;       const bf16x8 vpv = cat8(tv[0], tv[1]);
;       oacc[0] = __builtin_amdgcn_mfma_f32_32x32x16_bf16(pa0, vpv, zero16, 0, 0, 0);
;       oacc[1] = __builtin_amdgcn_mfma_f32_32x32x16_bf16(pa1, vpv, zero16, 0, 0, 0);
;     }
; #pragma unroll
;     for (int jk = 0; jk < 2 * NT; ++jk) {
;       if (jk + 1 < 2 * NT) ldq(jk + 1, qa[(jk + 1) & 1]);
;       __builtin_amdgcn_sched_barrier(0);
;       const int j = jk >> 1, ks = jk & 1;
;       u32x4 sb;
;       sb.x = pk(S[j][8 * ks + 0], S[j][8 * ks + 1]); sb.y = pk(S[j][8 * ks + 2], S[j][8 * ks + 3]);
;       sb.z = pk(S[j][8 * ks + 4], S[j][8 * ks + 5]); sb.w = pk(S[j][8 * ks + 6], S[j][8 * ks + 7]);
;       const bf16x8 bfr = __builtin_bit_cast(bf16x8, sb);
;       oacc[0] = __builtin_amdgcn_mfma_f32_32x32x16_bf16(qa[jk & 1][0], bfr, oacc[0], 0, 0, 0);
;       oacc[1] = __builtin_amdgcn_mfma_f32_32x32x16_bf16(qa[jk & 1][1], bfr, oacc[1], 0, 0, 0);
;       __builtin_amdgcn_sched_barrier(0);
;     }
; #pragma unroll
;     for (int tt = 0; tt < 2; ++tt)
; #pragma unroll
;       for (int e = 0; e < 16; ++e) {
;         const int t = 32 * tt + (e & 3) + 8 * (e >> 2) + 4 * hh;
.LBB0_810:
	s_or_b64 exec, exec, s[72:73]
	s_min_u32 s24, s93, 0x7d
	s_add_i32 s72, s24, 2
	s_sub_i32 s24, 0x7d, s24
	s_and_b64 s[62:63], s[76:77], exec
	s_cselect_b32 s95, s72, s24
	s_lshl_b32 s24, s95, 17
	s_add_u32 s62, s5, s24
	s_addc_u32 s63, s80, 0
	s_add_u32 s72, s81, s24
	v_pk_mul_f32 v[12:13], v[12:13], v[16:17]
	s_waitcnt lgkmcnt(0)
	s_barrier
	s_addc_u32 s73, s82, 0
	v_lshl_add_u64 v[16:17], s[62:63], 0, v[148:149]
	global_load_dwordx4 v[72:75], v[16:17], off
	v_lshl_add_u64 v[16:17], s[72:73], 0, v[148:149]
	global_load_dwordx4 v[76:79], v[16:17], off
	v_lshl_add_u64 v[16:17], s[62:63], 0, v[102:103]
	global_load_dwordx4 v[84:87], v[16:17], off
	v_lshl_add_u64 v[16:17], s[72:73], 0, v[102:103]
	global_load_dwordx4 v[88:91], v[16:17], off
	v_lshl_add_u64 v[16:17], v[110:111], 0, s[24:25]
	s_lshl_b32 s24, s95, 15
	global_load_dwordx4 v[92:95], v[16:17], off
	v_lshl_add_u64 v[16:17], v[114:115], 0, s[24:25]
	s_min_u32 s24, s93, 0x7e
	s_add_i32 s72, s24, 1
	s_sub_i32 s24, 0x7e, s24
	s_and_b64 s[62:63], s[76:77], exec
	s_cselect_b32 s24, s72, s24
	s_lshl_b32 s24, s24, 11
	s_add_u32 s62, s86, s24
	s_addc_u32 s63, s87, 0
	global_load_dwordx4 v[80:83], v[16:17], off
	v_lshl_add_u64 v[16:17], v[120:121], 2, s[62:63]
	global_load_dword v133, v[16:17], off
	ds_read_b64_tr_b16 v[164:165], v132 offset:0
	ds_read_b64_tr_b16 v[166:167], v132 offset:0x300
	ds_read_b64_tr_b16 v[160:161], v132 offset:0xc00
	ds_read_b64_tr_b16 v[162:163], v132 offset:0xf00
	ds_read_b64_tr_b16 v[154:155], v132 offset:0x1800
	ds_read_b64_tr_b16 v[156:157], v132 offset:0x1b00
	ds_read_b64_tr_b16 v[150:151], v132 offset:0x2400
	ds_read_b64_tr_b16 v[152:153], v132 offset:0x2700
	v_pk_mul_f32 v[8:9], v[8:9], v[20:21]
	v_pk_mul_f32 v[10:11], v[10:11], v[22:23]
	v_pk_mul_f32 v[14:15], v[14:15], v[18:19]
	ds_read_b128 v[16:19], v126 offset:50176
	ds_read_b128 v[20:23], v126 offset:54784
	v_pk_mul_f32 v[4:5], v[4:5], v[24:25]
	v_pk_mul_f32 v[6:7], v[6:7], v[26:27]
	ds_read_b64_tr_b16 v[24:25], v116
	ds_read_b64_tr_b16 v[26:27], v116 offset:0x300
	ds_read2_b64 v[168:171], v135 offset1:2
	ds_read2_b64 v[172:175], v137 offset0:64 offset1:66
	s_waitcnt lgkmcnt(0)
	v_pk_mul_f32 v[0:1], v[0:1], v[28:29]
	v_pk_mul_f32 v[2:3], v[2:3], v[30:31]
	s_waitcnt lgkmcnt(3)
	v_mfma_f32_32x32x16_bf16 v[32:47], v[16:19], v[24:27], 0
	ds_read2_b64 v[176:179], v135 offset0:4 offset1:6
	ds_read2_b64 v[180:183], v137 offset0:68 offset1:70
	s_waitcnt lgkmcnt(4)
	v_mfma_f32_32x32x16_bf16 v[16:31], v[20:23], v[24:27], 0
	v_cvt_pk_bf16_f32 v184, v0, v1
	v_cvt_pk_bf16_f32 v185, v2, v3
	v_cvt_pk_bf16_f32 v186, v4, v5
	v_cvt_pk_bf16_f32 v187, v6, v7
	s_waitcnt lgkmcnt(3)
	s_nop 0
	v_mfma_f32_32x32x16_bf16 v[32:47], v[168:171], v[184:187], v[32:47]
	s_waitcnt lgkmcnt(2)
	v_mfma_f32_32x32x16_bf16 v[16:31], v[172:175], v[184:187], v[16:31]
	v_cvt_pk_bf16_f32 v168, v8, v9
	v_cvt_pk_bf16_f32 v169, v10, v11
	v_cvt_pk_bf16_f32 v170, v12, v13
	v_cvt_pk_bf16_f32 v171, v14, v15
	s_waitcnt lgkmcnt(1)
	s_nop 0
	v_mfma_f32_32x32x16_bf16 v[32:47], v[176:179], v[168:171], v[32:47]
	s_waitcnt lgkmcnt(0)
	v_mfma_f32_32x32x16_bf16 v[16:31], v[180:183], v[168:171], v[16:31]
	s_nop 9
	ds_write2st64_b32 v117, v32, v33 offset0:232 offset1:233
	ds_write2st64_b32 v117, v34, v35 offset0:234 offset1:235
	ds_write2st64_b32 v117, v36, v37 offset0:240 offset1:241
	ds_write2st64_b32 v117, v38, v39 offset0:242 offset1:243
	ds_write2st64_b32 v117, v40, v41 offset0:248 offset1:249
	ds_write2st64_b32 v117, v42, v43 offset0:250 offset1:251
	ds_write2st64_b32 v129, v44, v45 offset0:24 offset1:25
	ds_write2st64_b32 v129, v46, v47 offset0:26 offset1:27
	ds_write2st64_b32 v129, v16, v17 offset0:32 offset1:33
	ds_write2st64_b32 v129, v18, v19 offset0:34 offset1:35
	ds_write2st64_b32 v129, v20, v21 offset0:40 offset1:41
	ds_write2st64_b32 v129, v22, v23 offset0:42 offset1:43
	ds_write2st64_b32 v129, v24, v25 offset0:48 offset1:49
	ds_write2st64_b32 v129, v26, v27 offset0:50 offset1:51
	ds_write2st64_b32 v129, v28, v29 offset0:56 offset1:57
	ds_write2st64_b32 v129, v30, v31 offset0:58 offset1:59
	ds_read_b64_tr_b16 v[28:29], v130 offset:0
	ds_read_b64_tr_b16 v[30:31], v130 offset:0x500
	ds_read_b64_tr_b16 v[24:25], v130 offset:0x1400
	ds_read_b64_tr_b16 v[26:27], v130 offset:0x1900
	ds_read_b64_tr_b16 v[20:21], v130 offset:0x2800
	ds_read_b64_tr_b16 v[22:23], v130 offset:0x2d00
	ds_read_b64_tr_b16 v[16:17], v130 offset:0x3c00
	ds_read_b64_tr_b16 v[18:19], v130 offset:0x4100
	s_nop 0
	s_waitcnt lgkmcnt(0)
	s_nop 0
	v_mfma_f32_32x32x16_bf16 v[0:15], v[28:31], v[164:167], v[0:15]
	v_mfma_f32_32x32x16_bf16 v[0:15], v[24:27], v[160:163], v[0:15]
	v_mfma_f32_32x32x16_bf16 v[0:15], v[20:23], v[154:157], v[0:15]
	v_mfma_f32_32x32x16_bf16 v[0:15], v[16:19], v[150:153], v[0:15]
	ds_read_b128 v[24:27], v136
	ds_read_b128 v[16:19], v136 offset:32
	ds_read_b128 v[20:23], v136 offset:64
	ds_read_b128 v[28:31], v136 offset:96
	s_waitcnt lgkmcnt(0)
	s_barrier
; DI unsigned pk(float lo, float hi) { f32x2 v = {lo, hi}; bf2_t b = __builtin_convertvector(v, bf2_t); return __builtin_bit_cast(unsigned, b); }
; DI float bflo(unsigned w) { return __uint_as_float(w << 16); }
; DI float bfhi(unsigned w) { return __uint_as_float(w & 0xffff0000u); }
; template <int DK>
; DI void scan_phase(const ScanArgs& a, char* lds, const XcdBarrier& xb) {
;     ...
;     {
;       float sum[8];
; #pragma unroll
;       for (int e = 0; e < 8; ++e) sum[e] = 0.f;
; #pragma unroll
;       for (int w4 = 0; w4 < 4; ++w4) {
;         const float* op = (const float*)(lds + OFF_O + ((w4 * 64 + vrow) * 64 + vch * 8) * 4);
;         const f32x4 x0 = *(const f32x4*)op, x1 = *(const f32x4*)(op + 4);
;         sum[0] += x0[0]; sum[1] += x0[1]; sum[2] += x0[2]; sum[3] += x0[3]; sum[4] += x1[0]; sum[5] += x1[1]; sum[6] += x1[2]; sum[7] += x1[3];
;       }
;       if (ret) {
;         const float myqs = qsc[vrow];
; #pragma unroll
;         for (int e = 0; e < 8; ++e) sum[e] *= myqs;
;       }
;       if (second) {
;         sum[0] += bflo(ocur.x); sum[1] += bfhi(ocur.x); sum[2] += bflo(ocur.y); sum[3] += bfhi(ocur.y);
;         sum[4] += bflo(ocur.z); sum[5] += bfhi(ocur.z); sum[6] += bflo(ocur.w); sum[7] += bfhi(ocur.w);
;       }
;       u32x4 w; w.x = pk(sum[0], sum[1]); w.y = pk(sum[2], sum[3]); w.z = pk(sum[4], sum[5]); w.w = pk(sum[6], sum[7]);
;       gst<u32x4>((char*)og + (size_t)n * (64 * LDO * 2) + ooff, w);
;       if (second) {
;         float q2 = bflo(w.x) * bflo(w.x) + bfhi(w.x) * bfhi(w.x) + bflo(w.y) * bflo(w.y) + bfhi(w.y) * bfhi(w.y) +
;                    bflo(w.z) * bflo(w.z) + bfhi(w.z) * bfhi(w.z) + bflo(w.w) * bflo(w.w) + bfhi(w.w) * bfhi(w.w);
;         q2 += __shfl_xor(q2, 1); q2 += __shfl_xor(q2, 2); q2 += __shfl_xor(q2, 4);
;         if (vch == 0) gst<float>(a.ssp + ((size_t)b * L_ + (size_t)n * 64 + vrow) * 32 + h * 8 + slice, q2);
	ds_read_b128 v[32:35], v125 offset:59392
	ds_read_b128 v[36:39], v125 offset:59408
	ds_read_b128 v[40:43], v128 offset:16384
	ds_read_b128 v[44:47], v128 offset:16400
	ds_read_b128 v[150:153], v128 offset:32768
	ds_read_b128 v[154:157], v128 offset:32784
	ds_read_b128 v[160:163], v128 offset:49152
	ds_read_b128 v[164:167], v128 offset:49168
	s_waitcnt lgkmcnt(7)
	v_pk_add_f32 v[32:33], v[32:33], 0 op_sel_hi:[1,0]
	v_pk_add_f32 v[34:35], v[34:35], 0 op_sel_hi:[1,0]
	s_waitcnt lgkmcnt(5)
	v_pk_add_f32 v[32:33], v[32:33], v[40:41]
	v_pk_add_f32 v[34:35], v[34:35], v[42:43]
	s_waitcnt lgkmcnt(3)
	v_pk_add_f32 v[32:33], v[32:33], v[150:151]
	v_pk_add_f32 v[36:37], v[36:37], 0 op_sel_hi:[1,0]
	s_waitcnt lgkmcnt(1)
	v_pk_add_f32 v[32:33], v[32:33], v[160:161]
	s_waitcnt vmcnt(7)
	v_lshlrev_b32_e32 v40, 16, v96
	v_and_b32_e32 v41, 0xffff0000, v96
	v_pk_add_f32 v[34:35], v[34:35], v[152:153]
	v_pk_add_f32 v[36:37], v[36:37], v[44:45]
	v_pk_add_f32 v[38:39], v[38:39], 0 op_sel_hi:[1,0]
	v_pk_add_f32 v[32:33], v[32:33], v[40:41]
	v_pk_add_f32 v[34:35], v[34:35], v[162:163]
	v_lshlrev_b32_e32 v40, 16, v97
	v_and_b32_e32 v41, 0xffff0000, v97
	v_pk_add_f32 v[36:37], v[36:37], v[154:155]
	v_pk_add_f32 v[38:39], v[38:39], v[46:47]
	v_pk_add_f32 v[34:35], v[34:35], v[40:41]
	s_waitcnt lgkmcnt(0)
	v_pk_add_f32 v[36:37], v[36:37], v[164:165]
	v_lshlrev_b32_e32 v40, 16, v98
	v_and_b32_e32 v41, 0xffff0000, v98
	v_pk_add_f32 v[38:39], v[38:39], v[156:157]
	v_pk_add_f32 v[36:37], v[36:37], v[40:41]
	v_pk_add_f32 v[38:39], v[38:39], v[166:167]
	v_lshlrev_b32_e32 v40, 16, v99
	v_and_b32_e32 v41, 0xffff0000, v99
	v_pk_add_f32 v[38:39], v[38:39], v[40:41]
	v_cvt_pk_bf16_f32 v32, v32, v33
	v_cvt_pk_bf16_f32 v33, v34, v35
	v_cvt_pk_bf16_f32 v34, v36, v37
	v_cvt_pk_bf16_f32 v35, v38, v39
	global_store_dwordx4 v[122:123], v[32:35], off
	v_lshlrev_b32_e32 v36, 16, v32
	s_nop 0
	v_and_b32_e32 v32, 0xffff0000, v32
	v_mul_f32_e32 v32, v32, v32
	v_fmac_f32_e32 v32, v36, v36
	v_lshlrev_b32_e32 v36, 16, v33
	v_fmac_f32_e32 v32, v36, v36
	v_and_b32_e32 v33, 0xffff0000, v33
	v_fmac_f32_e32 v32, v33, v33
	v_lshlrev_b32_e32 v33, 16, v34
	v_fmac_f32_e32 v32, v33, v33
	v_and_b32_e32 v33, 0xffff0000, v34
	v_fmac_f32_e32 v32, v33, v33
	v_lshlrev_b32_e32 v33, 16, v35
	v_fmac_f32_e32 v32, v33, v33
	v_and_b32_e32 v33, 0xffff0000, v35
	v_fmac_f32_e32 v32, v33, v33
	s_nop 1
	v_mov_b32_dpp v33, v32 quad_perm:[1,0,3,2] row_mask:0xf bank_mask:0xf
	s_waitcnt lgkmcnt(0)
	v_add_f32_e32 v32, v32, v33
	s_nop 1
	v_mov_b32_dpp v33, v32 quad_perm:[2,3,0,1] row_mask:0xf bank_mask:0xf
	s_waitcnt lgkmcnt(0)
	v_add_f32_e32 v32, v32, v33
	s_nop 1
	v_mov_b32_dpp v33, v32 row_half_mirror row_mask:0xf bank_mask:0xf
	s_and_saveexec_b64 s[72:73], s[60:61]
	s_cbranch_execz .LBB0_803
	s_lshl_b64 s[62:63], s[70:71], 13
	s_waitcnt lgkmcnt(0)
	v_add_f32_e32 v34, v32, v33
	v_lshl_add_u64 v[32:33], v[118:119], 0, s[62:63]
	global_store_dword v[32:33], v34, off
	s_branch .LBB0_803
